# v27: v25 + removed the 44 back-to-back s_setprio 0 / s_setprio 1 yield pairs between the MFMA groups of the GEMM K-loops (continuous MFMA priority)
# speedup vs baseline: 1.0028x; 1.0028x over previous
; #define PG8_STAGE(bufoff, gbase, voff) do { _Pragma("unroll") for (int _i = 0; _i < 2; ++_i) \
;         __builtin_amdgcn_global_load_lds((const unsigned*)((const char*)(gbase) + (voff)[_i]), (PG8_LAS unsigned*)(lds + (bufoff) + ldsw + _i * 8192), 16, 0, 0); } while (0)
; #define PG8_LDA(dst, b, h) do { _Pragma("unroll") for (int m = 0; m < 4; ++m) _Pragma("unroll") for (int k = 0; k < 2; ++k) dst[m][k] = *(const PG8_LAS bf16x8*)(lds + PG8_SA(b, h) + aoff + m * 2048 + k * 1024); } while (0)
; #define PG8_LDB(dst, b, h) do { _Pragma("unroll") for (int n = 0; n < 2; ++n) _Pragma("unroll") for (int k = 0; k < 2; ++k) dst[n][k] = *(const PG8_LAS bf16x8*)(lds + PG8_SB(b, h) + boff + n * 2048 + k * 1024); } while (0)
; #define PG8_MMA(ai, bj, At, Bt) do { __builtin_amdgcn_s_setprio(1); _Pragma("unroll") for (int m = 0; m < 4; ++m) _Pragma("unroll") for (int n = 0; n < 2; ++n) _Pragma("unroll") for (int k = 0; k < 2; ++k) \
;         acc[ai][bj][m][n] = __builtin_amdgcn_mfma_f32_16x16x32_bf16(Bt[n][k], At[m][k], acc[ai][bj][m][n], 0, 0, 0); __builtin_amdgcn_s_setprio(0); } while (0)
; #define PG8_WAIT_V(n) asm volatile("s_waitcnt vmcnt(" #n ")" ::: "memory")
; #define PG8_WAIT_L(n) asm volatile("s_waitcnt lgkmcnt(" #n ")" ::: "memory")
; #define PG8_BAR __builtin_amdgcn_s_barrier()
; #define PG8_SCHED __builtin_amdgcn_sched_barrier(0)
; template <class Epi, class Sched, bool ALIGN_EPI = false, bool SP2 = false>
; __device__ __forceinline__ void gemm_phase(PG8_LAS unsigned char* lds, const Gemm g, const Sched& S, const Epi& E) {
;     ...
;             const bool last = (t == nt - 2);
;             const char* a1 = cA + (size_t)(t + 1) * kstep;
;             const char* a2 = last ? nA : cA + (size_t)(t + 2) * kstep; const char* b2 = last ? nB : cB + (size_t)(t + 2) * kstep;
;             const char* a3 = a2 + kstep; const char* b3 = b2 + kstep;
;             if (last && has_next) S.a_ready(nxt);
;             if constexpr (SP2) {
;             PG8_LDB(B0, 0, 0); PG8_LDB(B1, 0, 1); PG8_SCHED; PG8_LDA(At, 0, 0); PG8_STAGE(PG8_SA(1, 1), a1 + hstep, voffA);
;             PG8_WAIT_V(8); PG8_WAIT_L(0); PG8_BAR; PG8_MMA(0, 0, At, B0); PG8_MMA(0, 1, At, B1); PG8_BAR; PG8_SCHED;
;             PG8_LDA(At, 0, 1); PG8_STAGE(PG8_SB(0, 0), b2, voffB); PG8_STAGE(PG8_SB(0, 1), b2 + hstep, voffB); PG8_STAGE(PG8_SA(0, 0), a2, voffA);
.LBB0_168:
	s_add_i32 s18, s6, 2
	s_add_u32 s19, s0, 0x80
	s_addc_u32 s7, s1, 0
	s_add_i32 s28, 0, 0x10000
	s_cmp_eq_u32 s79, s6
	s_cselect_b32 s7, s67, s7
	s_cselect_b32 s6, s66, s19
	s_cselect_b32 s25, s27, s9
	s_cselect_b32 s24, s26, s8
	s_add_i32 s19, 0, 0x14000
	v_add_u32_e32 v154, s28, v197
	v_add_u32_e32 v170, s19, v197
	ds_read_b128 v[142:145], v154
	ds_read_b128 v[146:149], v154 offset:1024
	ds_read_b128 v[150:153], v154 offset:2048
	ds_read_b128 v[154:157], v154 offset:3072
	ds_read_b128 v[158:161], v170
	ds_read_b128 v[162:165], v170 offset:1024
	ds_read_b128 v[166:169], v170 offset:2048
	ds_read_b128 v[170:173], v170 offset:3072
	v_lshl_add_u64 v[174:175], s[0:1], 0, v[136:137]
	s_add_i32 m0, s42, 0xc000
	ds_read_b128 v[186:189], v198
	ds_read_b128 v[190:193], v198 offset:1024
	ds_read_b128 v[200:203], v198 offset:2048
	ds_read_b128 v[204:207], v198 offset:3072
	ds_read_b128 v[208:211], v198 offset:4096
	ds_read_b128 v[212:215], v198 offset:5120
	ds_read_b128 v[216:219], v198 offset:6144
	ds_read_b128 v[220:223], v198 offset:7168
	global_load_lds_dwordx4 v[174:175], off
	v_lshl_add_u64 v[174:175], s[0:1], 0, v[138:139]
	s_add_i32 m0, s42, 0xe000
	s_nop 0
	global_load_lds_dwordx4 v[174:175], off
	s_waitcnt vmcnt(8)
	s_waitcnt lgkmcnt(0)
	s_barrier
	s_setprio 1
	s_waitcnt lgkmcnt(0)
	v_mfma_f32_16x16x32_bf16 v[120:123], v[142:145], v[186:189], v[120:123]
	v_mfma_f32_16x16x32_bf16 v[124:127], v[150:153], v[186:189], v[124:127]
	v_mfma_f32_16x16x32_bf16 v[112:115], v[142:145], v[200:203], v[112:115]
	v_mfma_f32_16x16x32_bf16 v[116:119], v[150:153], v[200:203], v[116:119]
	v_mfma_f32_16x16x32_bf16 v[104:107], v[142:145], v[208:211], v[104:107]
	v_mfma_f32_16x16x32_bf16 v[108:111], v[150:153], v[208:211], v[108:111]
	v_mfma_f32_16x16x32_bf16 v[96:99], v[142:145], v[216:219], v[96:99]
	v_mfma_f32_16x16x32_bf16 v[100:103], v[150:153], v[216:219], v[100:103]
	v_mfma_f32_16x16x32_bf16 v[120:123], v[146:149], v[190:193], v[120:123]
	v_mfma_f32_16x16x32_bf16 v[124:127], v[154:157], v[190:193], v[124:127]
	v_mfma_f32_16x16x32_bf16 v[112:115], v[146:149], v[204:207], v[112:115]
	v_mfma_f32_16x16x32_bf16 v[116:119], v[154:157], v[204:207], v[116:119]
	v_mfma_f32_16x16x32_bf16 v[104:107], v[146:149], v[212:215], v[104:107]
	v_mfma_f32_16x16x32_bf16 v[108:111], v[154:157], v[212:215], v[108:111]
	v_mfma_f32_16x16x32_bf16 v[96:99], v[146:149], v[220:223], v[96:99]
	v_mfma_f32_16x16x32_bf16 v[100:103], v[154:157], v[220:223], v[100:103]
	v_mfma_f32_16x16x32_bf16 v[60:63], v[158:161], v[186:189], v[60:63]
	v_mfma_f32_16x16x32_bf16 v[56:59], v[166:169], v[186:189], v[56:59]
	v_mfma_f32_16x16x32_bf16 v[52:55], v[158:161], v[200:203], v[52:55]
	v_mfma_f32_16x16x32_bf16 v[48:51], v[166:169], v[200:203], v[48:51]
	v_mfma_f32_16x16x32_bf16 v[44:47], v[158:161], v[208:211], v[44:47]
	v_mfma_f32_16x16x32_bf16 v[40:43], v[166:169], v[208:211], v[40:43]
	v_mfma_f32_16x16x32_bf16 v[36:39], v[158:161], v[216:219], v[36:39]
	v_mfma_f32_16x16x32_bf16 v[32:35], v[166:169], v[216:219], v[32:35]
	v_mfma_f32_16x16x32_bf16 v[60:63], v[162:165], v[190:193], v[60:63]
	v_mfma_f32_16x16x32_bf16 v[56:59], v[170:173], v[190:193], v[56:59]
	v_mfma_f32_16x16x32_bf16 v[52:55], v[162:165], v[204:207], v[52:55]
	v_mfma_f32_16x16x32_bf16 v[48:51], v[170:173], v[204:207], v[48:51]
	v_mfma_f32_16x16x32_bf16 v[44:47], v[162:165], v[212:215], v[44:47]
	v_mfma_f32_16x16x32_bf16 v[40:43], v[170:173], v[212:215], v[40:43]
	v_mfma_f32_16x16x32_bf16 v[36:39], v[162:165], v[220:223], v[36:39]
	v_mfma_f32_16x16x32_bf16 v[32:35], v[170:173], v[220:223], v[32:35]
	s_setprio 0
	s_barrier
	s_add_i32 s28, s28, s31
	v_lshl_add_u64 v[174:175], s[24:25], 0, v[130:131]
	s_mov_b32 m0, s28
	ds_read_b128 v[186:189], v198 offset:16384
	ds_read_b128 v[190:193], v198 offset:17408
	ds_read_b128 v[200:203], v198 offset:18432
	ds_read_b128 v[204:207], v198 offset:19456
	ds_read_b128 v[208:211], v198 offset:20480
	ds_read_b128 v[212:215], v198 offset:21504
	ds_read_b128 v[216:219], v198 offset:22528
	ds_read_b128 v[220:223], v198 offset:23552
	global_load_lds_dwordx4 v[174:175], off
	s_add_i32 m0, s28, 0x2000
	v_lshl_add_u64 v[182:183], s[24:25], 0, v[134:135]
	s_add_u32 s24, s24, s14
	s_addc_u32 s25, s25, s15
	s_add_i32 s19, s19, s31
	global_load_lds_dwordx4 v[182:183], off
	v_lshl_add_u64 v[184:185], s[24:25], 0, v[130:131]
	s_mov_b32 m0, s19
	v_lshl_add_u64 v[194:195], s[24:25], 0, v[134:135]
	global_load_lds_dwordx4 v[184:185], off
	s_add_i32 m0, s19, 0x2000
	v_lshl_add_u64 v[224:225], s[6:7], 0, v[128:129]
	global_load_lds_dwordx4 v[194:195], off
	s_mov_b32 m0, s42
	v_lshl_add_u64 v[226:227], s[6:7], 0, v[132:133]
	global_load_lds_dwordx4 v[224:225], off
	s_mov_b32 m0, s43
	s_nop 0
	global_load_lds_dwordx4 v[226:227], off
	s_waitcnt vmcnt(8)
	s_waitcnt lgkmcnt(0)
	s_barrier
; #define PG8_STAGE(bufoff, gbase, voff) do { _Pragma("unroll") for (int _i = 0; _i < 2; ++_i) \
;         __builtin_amdgcn_global_load_lds((const unsigned*)((const char*)(gbase) + (voff)[_i]), (PG8_LAS unsigned*)(lds + (bufoff) + ldsw + _i * 8192), 16, 0, 0); } while (0)
; #define PG8_LDA(dst, b, h) do { _Pragma("unroll") for (int m = 0; m < 4; ++m) _Pragma("unroll") for (int k = 0; k < 2; ++k) dst[m][k] = *(const PG8_LAS bf16x8*)(lds + PG8_SA(b, h) + aoff + m * 2048 + k * 1024); } while (0)
; #define PG8_LDB(dst, b, h) do { _Pragma("unroll") for (int n = 0; n < 2; ++n) _Pragma("unroll") for (int k = 0; k < 2; ++k) dst[n][k] = *(const PG8_LAS bf16x8*)(lds + PG8_SB(b, h) + boff + n * 2048 + k * 1024); } while (0)
; #define PG8_MMA(ai, bj, At, Bt) do { __builtin_amdgcn_s_setprio(1); _Pragma("unroll") for (int m = 0; m < 4; ++m) _Pragma("unroll") for (int n = 0; n < 2; ++n) _Pragma("unroll") for (int k = 0; k < 2; ++k) \
;         acc[ai][bj][m][n] = __builtin_amdgcn_mfma_f32_16x16x32_bf16(Bt[n][k], At[m][k], acc[ai][bj][m][n], 0, 0, 0); __builtin_amdgcn_s_setprio(0); } while (0)
; #define PG8_WAIT_V(n) asm volatile("s_waitcnt vmcnt(" #n ")" ::: "memory")
; #define PG8_WAIT_L(n) asm volatile("s_waitcnt lgkmcnt(" #n ")" ::: "memory")
; #define PG8_BAR __builtin_amdgcn_s_barrier()
; #define PG8_SCHED __builtin_amdgcn_sched_barrier(0)
; template <class Epi, class Sched, bool ALIGN_EPI = false, bool SP2 = false>
; __device__ __forceinline__ void gemm_phase(PG8_LAS unsigned char* lds, const Gemm g, const Sched& S, const Epi& E) {
;     ...
;             PG8_WAIT_V(8); PG8_WAIT_L(0); PG8_BAR; PG8_MMA(1, 0, At, B0); PG8_MMA(1, 1, At, B1); PG8_BAR; PG8_SCHED;
;             PG8_LDB(B0, 1, 0); PG8_LDB(B1, 1, 1); PG8_SCHED; PG8_LDA(At, 1, 0); PG8_STAGE(PG8_SA(0, 1), a2 + hstep, voffA);
;             PG8_WAIT_V(8); PG8_WAIT_L(0); PG8_BAR; PG8_MMA(0, 0, At, B0); PG8_MMA(0, 1, At, B1); PG8_BAR; PG8_SCHED;
	s_setprio 1
	s_waitcnt lgkmcnt(0)
	v_mfma_f32_16x16x32_bf16 v[88:91], v[142:145], v[186:189], v[88:91]
	v_mfma_f32_16x16x32_bf16 v[92:95], v[150:153], v[186:189], v[92:95]
	v_mfma_f32_16x16x32_bf16 v[80:83], v[142:145], v[200:203], v[80:83]
	v_mfma_f32_16x16x32_bf16 v[84:87], v[150:153], v[200:203], v[84:87]
	v_mfma_f32_16x16x32_bf16 v[72:75], v[142:145], v[208:211], v[72:75]
	v_mfma_f32_16x16x32_bf16 v[76:79], v[150:153], v[208:211], v[76:79]
	v_mfma_f32_16x16x32_bf16 v[64:67], v[142:145], v[216:219], v[64:67]
	v_mfma_f32_16x16x32_bf16 v[68:71], v[150:153], v[216:219], v[68:71]
	v_mfma_f32_16x16x32_bf16 v[88:91], v[146:149], v[190:193], v[88:91]
	v_mfma_f32_16x16x32_bf16 v[92:95], v[154:157], v[190:193], v[92:95]
	v_mfma_f32_16x16x32_bf16 v[80:83], v[146:149], v[204:207], v[80:83]
	v_mfma_f32_16x16x32_bf16 v[84:87], v[154:157], v[204:207], v[84:87]
	v_mfma_f32_16x16x32_bf16 v[72:75], v[146:149], v[212:215], v[72:75]
	v_mfma_f32_16x16x32_bf16 v[76:79], v[154:157], v[212:215], v[76:79]
	v_mfma_f32_16x16x32_bf16 v[64:67], v[146:149], v[220:223], v[64:67]
	v_mfma_f32_16x16x32_bf16 v[68:71], v[154:157], v[220:223], v[68:71]
	v_mfma_f32_16x16x32_bf16 v[28:31], v[158:161], v[186:189], v[28:31]
	v_mfma_f32_16x16x32_bf16 v[24:27], v[166:169], v[186:189], v[24:27]
	v_mfma_f32_16x16x32_bf16 v[20:23], v[158:161], v[200:203], v[20:23]
	v_mfma_f32_16x16x32_bf16 v[16:19], v[166:169], v[200:203], v[16:19]
	v_mfma_f32_16x16x32_bf16 v[12:15], v[158:161], v[208:211], v[12:15]
	v_mfma_f32_16x16x32_bf16 v[8:11], v[166:169], v[208:211], v[8:11]
	v_mfma_f32_16x16x32_bf16 v[4:7], v[158:161], v[216:219], v[4:7]
	v_mfma_f32_16x16x32_bf16 v[0:3], v[166:169], v[216:219], v[0:3]
	v_mfma_f32_16x16x32_bf16 v[28:31], v[162:165], v[190:193], v[28:31]
	v_mfma_f32_16x16x32_bf16 v[24:27], v[170:173], v[190:193], v[24:27]
	v_mfma_f32_16x16x32_bf16 v[20:23], v[162:165], v[204:207], v[20:23]
	v_mfma_f32_16x16x32_bf16 v[16:19], v[170:173], v[204:207], v[16:19]
	v_mfma_f32_16x16x32_bf16 v[12:15], v[162:165], v[212:215], v[12:15]
	v_mfma_f32_16x16x32_bf16 v[8:11], v[170:173], v[212:215], v[8:11]
	v_mfma_f32_16x16x32_bf16 v[4:7], v[162:165], v[220:223], v[4:7]
	v_mfma_f32_16x16x32_bf16 v[0:3], v[170:173], v[220:223], v[0:3]
	s_setprio 0
	s_barrier
	s_add_i32 s19, 0, 0x18000
	s_add_i32 s24, 0, 0x1c000
	v_add_u32_e32 v154, s19, v197
	v_add_u32_e32 v170, s24, v197
	ds_read_b128 v[142:145], v154
	ds_read_b128 v[146:149], v154 offset:1024
	ds_read_b128 v[150:153], v154 offset:2048
	ds_read_b128 v[154:157], v154 offset:3072
	ds_read_b128 v[158:161], v170
	ds_read_b128 v[162:165], v170 offset:1024
	ds_read_b128 v[166:169], v170 offset:2048
	ds_read_b128 v[170:173], v170 offset:3072
	s_add_u32 s6, s6, s14
	s_addc_u32 s7, s7, s15
	s_mov_b32 m0, s72
	v_lshl_add_u64 v[236:237], s[6:7], 0, v[128:129]
	ds_read_b128 v[186:189], v198 offset:32768
	ds_read_b128 v[190:193], v198 offset:33792
	ds_read_b128 v[200:203], v198 offset:34816
	ds_read_b128 v[204:207], v198 offset:35840
	ds_read_b128 v[208:211], v198 offset:36864
	ds_read_b128 v[212:215], v198 offset:37888
	ds_read_b128 v[216:219], v198 offset:38912
	ds_read_b128 v[220:223], v198 offset:39936
	global_load_lds_dwordx4 v[236:237], off
	v_lshl_add_u64 v[236:237], s[6:7], 0, v[132:133]
	s_mov_b32 m0, s73
	s_nop 0
	global_load_lds_dwordx4 v[236:237], off
	s_waitcnt vmcnt(8)
	s_waitcnt lgkmcnt(0)
	s_barrier
	s_setprio 1
	s_waitcnt lgkmcnt(0)
	v_mfma_f32_16x16x32_bf16 v[120:123], v[142:145], v[186:189], v[120:123]
	v_mfma_f32_16x16x32_bf16 v[124:127], v[150:153], v[186:189], v[124:127]
	v_mfma_f32_16x16x32_bf16 v[112:115], v[142:145], v[200:203], v[112:115]
	v_mfma_f32_16x16x32_bf16 v[116:119], v[150:153], v[200:203], v[116:119]
	v_mfma_f32_16x16x32_bf16 v[104:107], v[142:145], v[208:211], v[104:107]
	v_mfma_f32_16x16x32_bf16 v[108:111], v[150:153], v[208:211], v[108:111]
	v_mfma_f32_16x16x32_bf16 v[96:99], v[142:145], v[216:219], v[96:99]
	v_mfma_f32_16x16x32_bf16 v[100:103], v[150:153], v[216:219], v[100:103]
	v_mfma_f32_16x16x32_bf16 v[120:123], v[146:149], v[190:193], v[120:123]
	v_mfma_f32_16x16x32_bf16 v[124:127], v[154:157], v[190:193], v[124:127]
	v_mfma_f32_16x16x32_bf16 v[112:115], v[146:149], v[204:207], v[112:115]
	v_mfma_f32_16x16x32_bf16 v[116:119], v[154:157], v[204:207], v[116:119]
	v_mfma_f32_16x16x32_bf16 v[104:107], v[146:149], v[212:215], v[104:107]
	v_mfma_f32_16x16x32_bf16 v[108:111], v[154:157], v[212:215], v[108:111]
	v_mfma_f32_16x16x32_bf16 v[96:99], v[146:149], v[220:223], v[96:99]
	v_mfma_f32_16x16x32_bf16 v[100:103], v[154:157], v[220:223], v[100:103]
	v_mfma_f32_16x16x32_bf16 v[60:63], v[158:161], v[186:189], v[60:63]
	v_mfma_f32_16x16x32_bf16 v[56:59], v[166:169], v[186:189], v[56:59]
	v_mfma_f32_16x16x32_bf16 v[52:55], v[158:161], v[200:203], v[52:55]
	v_mfma_f32_16x16x32_bf16 v[48:51], v[166:169], v[200:203], v[48:51]
	v_mfma_f32_16x16x32_bf16 v[44:47], v[158:161], v[208:211], v[44:47]
	v_mfma_f32_16x16x32_bf16 v[40:43], v[166:169], v[208:211], v[40:43]
	v_mfma_f32_16x16x32_bf16 v[36:39], v[158:161], v[216:219], v[36:39]
	v_mfma_f32_16x16x32_bf16 v[32:35], v[166:169], v[216:219], v[32:35]
	v_mfma_f32_16x16x32_bf16 v[60:63], v[162:165], v[190:193], v[60:63]
	v_mfma_f32_16x16x32_bf16 v[56:59], v[170:173], v[190:193], v[56:59]
	v_mfma_f32_16x16x32_bf16 v[52:55], v[162:165], v[204:207], v[52:55]
	v_mfma_f32_16x16x32_bf16 v[48:51], v[170:173], v[204:207], v[48:51]
	v_mfma_f32_16x16x32_bf16 v[44:47], v[162:165], v[212:215], v[44:47]
	v_mfma_f32_16x16x32_bf16 v[40:43], v[170:173], v[212:215], v[40:43]
	v_mfma_f32_16x16x32_bf16 v[36:39], v[162:165], v[220:223], v[36:39]
	v_mfma_f32_16x16x32_bf16 v[32:35], v[170:173], v[220:223], v[32:35]
	s_setprio 0
	s_barrier
; #define PG8_STAGE(bufoff, gbase, voff) do { _Pragma("unroll") for (int _i = 0; _i < 2; ++_i) \
;         __builtin_amdgcn_global_load_lds((const unsigned*)((const char*)(gbase) + (voff)[_i]), (PG8_LAS unsigned*)(lds + (bufoff) + ldsw + _i * 8192), 16, 0, 0); } while (0)
; #define PG8_LDA(dst, b, h) do { _Pragma("unroll") for (int m = 0; m < 4; ++m) _Pragma("unroll") for (int k = 0; k < 2; ++k) dst[m][k] = *(const PG8_LAS bf16x8*)(lds + PG8_SA(b, h) + aoff + m * 2048 + k * 1024); } while (0)
; #define PG8_MMA(ai, bj, At, Bt) do { __builtin_amdgcn_s_setprio(1); _Pragma("unroll") for (int m = 0; m < 4; ++m) _Pragma("unroll") for (int n = 0; n < 2; ++n) _Pragma("unroll") for (int k = 0; k < 2; ++k) \
;         acc[ai][bj][m][n] = __builtin_amdgcn_mfma_f32_16x16x32_bf16(Bt[n][k], At[m][k], acc[ai][bj][m][n], 0, 0, 0); __builtin_amdgcn_s_setprio(0); } while (0)
; #define PG8_WAIT_V(n) asm volatile("s_waitcnt vmcnt(" #n ")" ::: "memory")
; #define PG8_WAIT_L(n) asm volatile("s_waitcnt lgkmcnt(" #n ")" ::: "memory")
; #define PG8_BAR __builtin_amdgcn_s_barrier()
; #define PG8_SCHED __builtin_amdgcn_sched_barrier(0)
; template <class Epi, class Sched, bool ALIGN_EPI = false, bool SP2 = false>
; __device__ __forceinline__ void gemm_phase(PG8_LAS unsigned char* lds, const Gemm g, const Sched& S, const Epi& E) {
;     ...
;             PG8_LDA(At, 1, 1); PG8_STAGE(PG8_SB(1, 0), b3, voffB); PG8_STAGE(PG8_SB(1, 1), b3 + hstep, voffB); PG8_STAGE(PG8_SA(1, 0), a3, voffA);
;             PG8_WAIT_V(8); PG8_WAIT_L(0); PG8_BAR; PG8_MMA(1, 0, At, B0); PG8_MMA(1, 1, At, B1); PG8_BAR; PG8_SCHED;
	s_add_i32 s6, s19, s31
	v_lshl_add_u64 v[174:175], v[174:175], 0, s[44:45]
	s_mov_b32 m0, s6
	ds_read_b128 v[186:189], v198 offset:49152
	ds_read_b128 v[190:193], v198 offset:50176
	ds_read_b128 v[200:203], v198 offset:51200
	ds_read_b128 v[204:207], v198 offset:52224
	ds_read_b128 v[208:211], v198 offset:53248
	ds_read_b128 v[212:215], v198 offset:54272
	ds_read_b128 v[216:219], v198 offset:55296
	ds_read_b128 v[220:223], v198 offset:56320
	global_load_lds_dwordx4 v[174:175], off
	v_lshl_add_u64 v[174:175], v[182:183], 0, s[44:45]
	s_add_i32 m0, s6, 0x2000
	s_add_i32 s6, s24, s31
	global_load_lds_dwordx4 v[174:175], off
	v_lshl_add_u64 v[174:175], v[184:185], 0, s[44:45]
	s_mov_b32 m0, s6
	s_nop 0
	global_load_lds_dwordx4 v[174:175], off
	v_lshl_add_u64 v[174:175], v[194:195], 0, s[44:45]
	s_add_i32 m0, s6, 0x2000
	s_nop 0
	global_load_lds_dwordx4 v[174:175], off
	v_lshl_add_u64 v[174:175], v[224:225], 0, s[44:45]
	s_mov_b32 m0, s74
	s_nop 0
	global_load_lds_dwordx4 v[174:175], off
	v_lshl_add_u64 v[174:175], v[226:227], 0, s[44:45]
	s_mov_b32 m0, s75
	s_nop 0
	global_load_lds_dwordx4 v[174:175], off
	s_waitcnt vmcnt(8)
	s_waitcnt lgkmcnt(0)
	s_barrier
	s_setprio 1
	s_waitcnt lgkmcnt(0)
	v_mfma_f32_16x16x32_bf16 v[88:91], v[142:145], v[186:189], v[88:91]
	v_mfma_f32_16x16x32_bf16 v[92:95], v[150:153], v[186:189], v[92:95]
	v_mfma_f32_16x16x32_bf16 v[80:83], v[142:145], v[200:203], v[80:83]
	v_mfma_f32_16x16x32_bf16 v[84:87], v[150:153], v[200:203], v[84:87]
	v_mfma_f32_16x16x32_bf16 v[72:75], v[142:145], v[208:211], v[72:75]
	v_mfma_f32_16x16x32_bf16 v[76:79], v[150:153], v[208:211], v[76:79]
	v_mfma_f32_16x16x32_bf16 v[64:67], v[142:145], v[216:219], v[64:67]
	v_mfma_f32_16x16x32_bf16 v[68:71], v[150:153], v[216:219], v[68:71]
	v_mfma_f32_16x16x32_bf16 v[88:91], v[146:149], v[190:193], v[88:91]
	v_mfma_f32_16x16x32_bf16 v[92:95], v[154:157], v[190:193], v[92:95]
	v_mfma_f32_16x16x32_bf16 v[80:83], v[146:149], v[204:207], v[80:83]
	v_mfma_f32_16x16x32_bf16 v[84:87], v[154:157], v[204:207], v[84:87]
	v_mfma_f32_16x16x32_bf16 v[72:75], v[146:149], v[212:215], v[72:75]
	v_mfma_f32_16x16x32_bf16 v[76:79], v[154:157], v[212:215], v[76:79]
	v_mfma_f32_16x16x32_bf16 v[64:67], v[146:149], v[220:223], v[64:67]
	v_mfma_f32_16x16x32_bf16 v[68:71], v[154:157], v[220:223], v[68:71]
	v_mfma_f32_16x16x32_bf16 v[28:31], v[158:161], v[186:189], v[28:31]
	v_mfma_f32_16x16x32_bf16 v[24:27], v[166:169], v[186:189], v[24:27]
	v_mfma_f32_16x16x32_bf16 v[20:23], v[158:161], v[200:203], v[20:23]
	v_mfma_f32_16x16x32_bf16 v[16:19], v[166:169], v[200:203], v[16:19]
	v_mfma_f32_16x16x32_bf16 v[12:15], v[158:161], v[208:211], v[12:15]
	v_mfma_f32_16x16x32_bf16 v[8:11], v[166:169], v[208:211], v[8:11]
	v_mfma_f32_16x16x32_bf16 v[4:7], v[158:161], v[216:219], v[4:7]
	v_mfma_f32_16x16x32_bf16 v[0:3], v[166:169], v[216:219], v[0:3]
	v_mfma_f32_16x16x32_bf16 v[28:31], v[162:165], v[190:193], v[28:31]
	v_mfma_f32_16x16x32_bf16 v[24:27], v[170:173], v[190:193], v[24:27]
	s_add_u32 s0, s0, 0x100
	v_mfma_f32_16x16x32_bf16 v[20:23], v[162:165], v[204:207], v[20:23]
	s_addc_u32 s1, s1, 0
	v_mfma_f32_16x16x32_bf16 v[16:19], v[170:173], v[204:207], v[16:19]
	s_add_u32 s8, s8, 0x100
	v_mfma_f32_16x16x32_bf16 v[12:15], v[162:165], v[212:215], v[12:15]
	s_addc_u32 s9, s9, 0
	v_mfma_f32_16x16x32_bf16 v[8:11], v[170:173], v[212:215], v[8:11]
	s_cmp_ge_i32 s18, s76
	v_mfma_f32_16x16x32_bf16 v[4:7], v[162:165], v[220:223], v[4:7]
	s_mov_b32 s6, s18
	v_mfma_f32_16x16x32_bf16 v[0:3], v[170:173], v[220:223], v[0:3]
	s_setprio 0
	s_barrier
	s_cbranch_scc0 .LBB0_168

; #define PG8_STAGE(bufoff, gbase, voff) do { _Pragma("unroll") for (int _i = 0; _i < 2; ++_i) \
;         __builtin_amdgcn_global_load_lds((const unsigned*)((const char*)(gbase) + (voff)[_i]), (PG8_LAS unsigned*)(lds + (bufoff) + ldsw + _i * 8192), 16, 0, 0); } while (0)
; #define PG8_LDA(dst, b, h) do { _Pragma("unroll") for (int m = 0; m < 4; ++m) _Pragma("unroll") for (int k = 0; k < 2; ++k) dst[m][k] = *(const PG8_LAS bf16x8*)(lds + PG8_SA(b, h) + aoff + m * 2048 + k * 1024); } while (0)
; #define PG8_LDB(dst, b, h) do { _Pragma("unroll") for (int n = 0; n < 2; ++n) _Pragma("unroll") for (int k = 0; k < 2; ++k) dst[n][k] = *(const PG8_LAS bf16x8*)(lds + PG8_SB(b, h) + boff + n * 2048 + k * 1024); } while (0)
; #define PG8_MMA(ai, bj, At, Bt) do { __builtin_amdgcn_s_setprio(1); _Pragma("unroll") for (int m = 0; m < 4; ++m) _Pragma("unroll") for (int n = 0; n < 2; ++n) _Pragma("unroll") for (int k = 0; k < 2; ++k) \
;         acc[ai][bj][m][n] = __builtin_amdgcn_mfma_f32_16x16x32_bf16(Bt[n][k], At[m][k], acc[ai][bj][m][n], 0, 0, 0); __builtin_amdgcn_s_setprio(0); } while (0)
; #define PG8_WAIT_V(n) asm volatile("s_waitcnt vmcnt(" #n ")" ::: "memory")
; #define PG8_WAIT_L(n) asm volatile("s_waitcnt lgkmcnt(" #n ")" ::: "memory")
; #define PG8_BAR __builtin_amdgcn_s_barrier()
; #define PG8_SCHED __builtin_amdgcn_sched_barrier(0)
; template <class Epi, class Sched, bool ALIGN_EPI = false, bool SP2 = false>
; __device__ __forceinline__ void gemm_phase(PG8_LAS unsigned char* lds, const Gemm g, const Sched& S, const Epi& E) {
;     ...
;             const bool last = (t == nt - 2);
;             const char* a1 = cA + (size_t)(t + 1) * kstep;
;             const char* a2 = last ? nA : cA + (size_t)(t + 2) * kstep; const char* b2 = last ? nB : cB + (size_t)(t + 2) * kstep;
;             const char* a3 = a2 + kstep; const char* b3 = b2 + kstep;
;             if (last && has_next) S.a_ready(nxt);
;             if constexpr (SP2) {
;             PG8_LDB(B0, 0, 0); PG8_LDB(B1, 0, 1); PG8_SCHED; PG8_LDA(At, 0, 0); PG8_STAGE(PG8_SA(1, 1), a1 + hstep, voffA);
;             PG8_WAIT_V(8); PG8_WAIT_L(0); PG8_BAR; PG8_MMA(0, 0, At, B0); PG8_MMA(0, 1, At, B1); PG8_BAR; PG8_SCHED;
;             PG8_LDA(At, 0, 1); PG8_STAGE(PG8_SB(0, 0), b2, voffB); PG8_STAGE(PG8_SB(0, 1), b2 + hstep, voffB); PG8_STAGE(PG8_SA(0, 0), a2, voffA);
.LBB0_375:
	s_add_i32 s80, s64, 2
	s_add_u32 s28, s40, 0x80
	s_addc_u32 s38, s41, 0
	s_add_i32 s48, 0, 0x10000
	s_cmp_eq_u32 s74, s64
	s_cselect_b32 s65, s5, s38
	s_cselect_b32 s64, s4, s28
	s_cselect_b32 s39, s37, s79
	s_cselect_b32 s38, s36, s78
	s_add_i32 s28, 0, 0x14000
	v_add_u32_e32 v154, s48, v140
	v_add_u32_e32 v170, s28, v140
	ds_read_b128 v[142:145], v154
	ds_read_b128 v[146:149], v154 offset:1024
	ds_read_b128 v[150:153], v154 offset:2048
	ds_read_b128 v[154:157], v154 offset:3072
	ds_read_b128 v[158:161], v170
	ds_read_b128 v[162:165], v170 offset:1024
	ds_read_b128 v[166:169], v170 offset:2048
	ds_read_b128 v[170:173], v170 offset:3072
	v_lshl_add_u64 v[174:175], s[40:41], 0, v[134:135]
	s_add_i32 m0, s43, 0xc000
	ds_read_b128 v[182:185], v141
	ds_read_b128 v[186:189], v141 offset:1024
	ds_read_b128 v[190:193], v141 offset:2048
	ds_read_b128 v[194:197], v141 offset:3072
	ds_read_b128 v[198:201], v141 offset:4096
	ds_read_b128 v[202:205], v141 offset:5120
	ds_read_b128 v[206:209], v141 offset:6144
	ds_read_b128 v[210:213], v141 offset:7168
	global_load_lds_dwordx4 v[174:175], off
	v_lshl_add_u64 v[174:175], s[40:41], 0, v[136:137]
	s_add_i32 m0, s43, 0xe000
	s_nop 0
	global_load_lds_dwordx4 v[174:175], off
	s_waitcnt vmcnt(8)
	s_waitcnt lgkmcnt(0)
	s_barrier
	s_setprio 1
	s_waitcnt lgkmcnt(0)
	v_mfma_f32_16x16x32_bf16 v[120:123], v[142:145], v[182:185], v[120:123]
	v_mfma_f32_16x16x32_bf16 v[124:127], v[150:153], v[182:185], v[124:127]
	v_mfma_f32_16x16x32_bf16 v[108:111], v[142:145], v[190:193], v[108:111]
	v_mfma_f32_16x16x32_bf16 v[104:107], v[150:153], v[190:193], v[104:107]
	v_mfma_f32_16x16x32_bf16 v[92:95], v[142:145], v[198:201], v[92:95]
	v_mfma_f32_16x16x32_bf16 v[88:91], v[150:153], v[198:201], v[88:91]
	v_mfma_f32_16x16x32_bf16 v[76:79], v[142:145], v[206:209], v[76:79]
	v_mfma_f32_16x16x32_bf16 v[72:75], v[150:153], v[206:209], v[72:75]
	v_mfma_f32_16x16x32_bf16 v[120:123], v[146:149], v[186:189], v[120:123]
	v_mfma_f32_16x16x32_bf16 v[124:127], v[154:157], v[186:189], v[124:127]
	v_mfma_f32_16x16x32_bf16 v[108:111], v[146:149], v[194:197], v[108:111]
	v_mfma_f32_16x16x32_bf16 v[104:107], v[154:157], v[194:197], v[104:107]
	v_mfma_f32_16x16x32_bf16 v[92:95], v[146:149], v[202:205], v[92:95]
	v_mfma_f32_16x16x32_bf16 v[88:91], v[154:157], v[202:205], v[88:91]
	v_mfma_f32_16x16x32_bf16 v[76:79], v[146:149], v[210:213], v[76:79]
	v_mfma_f32_16x16x32_bf16 v[72:75], v[154:157], v[210:213], v[72:75]
	v_mfma_f32_16x16x32_bf16 v[116:119], v[158:161], v[182:185], v[116:119]
	v_mfma_f32_16x16x32_bf16 v[112:115], v[166:169], v[182:185], v[112:115]
	v_mfma_f32_16x16x32_bf16 v[100:103], v[158:161], v[190:193], v[100:103]
	v_mfma_f32_16x16x32_bf16 v[96:99], v[166:169], v[190:193], v[96:99]
	v_mfma_f32_16x16x32_bf16 v[84:87], v[158:161], v[198:201], v[84:87]
	v_mfma_f32_16x16x32_bf16 v[80:83], v[166:169], v[198:201], v[80:83]
	v_mfma_f32_16x16x32_bf16 v[68:71], v[158:161], v[206:209], v[68:71]
	v_mfma_f32_16x16x32_bf16 v[64:67], v[166:169], v[206:209], v[64:67]
	v_mfma_f32_16x16x32_bf16 v[116:119], v[162:165], v[186:189], v[116:119]
	v_mfma_f32_16x16x32_bf16 v[112:115], v[170:173], v[186:189], v[112:115]
	v_mfma_f32_16x16x32_bf16 v[100:103], v[162:165], v[194:197], v[100:103]
	v_mfma_f32_16x16x32_bf16 v[96:99], v[170:173], v[194:197], v[96:99]
	v_mfma_f32_16x16x32_bf16 v[84:87], v[162:165], v[202:205], v[84:87]
	v_mfma_f32_16x16x32_bf16 v[80:83], v[170:173], v[202:205], v[80:83]
	v_mfma_f32_16x16x32_bf16 v[68:71], v[162:165], v[210:213], v[68:71]
	v_mfma_f32_16x16x32_bf16 v[64:67], v[170:173], v[210:213], v[64:67]
	s_setprio 0
	s_barrier
	s_add_i32 s48, s48, s24
	v_lshl_add_u64 v[174:175], s[38:39], 0, v[176:177]
	s_mov_b32 m0, s48
	ds_read_b128 v[182:185], v141 offset:16384
	ds_read_b128 v[186:189], v141 offset:17408
	ds_read_b128 v[190:193], v141 offset:18432
	ds_read_b128 v[194:197], v141 offset:19456
	ds_read_b128 v[198:201], v141 offset:20480
	ds_read_b128 v[202:205], v141 offset:21504
	ds_read_b128 v[206:209], v141 offset:22528
	ds_read_b128 v[210:213], v141 offset:23552
	global_load_lds_dwordx4 v[174:175], off
	s_add_i32 m0, s48, 0x2000
	v_lshl_add_u64 v[214:215], s[38:39], 0, v[132:133]
	s_add_u32 s38, s38, s10
	s_addc_u32 s39, s39, s11
	s_add_i32 s28, s28, s24
	global_load_lds_dwordx4 v[214:215], off
	v_lshl_add_u64 v[216:217], s[38:39], 0, v[176:177]
	s_mov_b32 m0, s28
	v_lshl_add_u64 v[218:219], s[38:39], 0, v[132:133]
	global_load_lds_dwordx4 v[216:217], off
	s_add_i32 m0, s28, 0x2000
	v_lshl_add_u64 v[220:221], s[64:65], 0, v[128:129]
	global_load_lds_dwordx4 v[218:219], off
	s_mov_b32 m0, s43
	v_lshl_add_u64 v[222:223], s[64:65], 0, v[130:131]
	global_load_lds_dwordx4 v[220:221], off
	s_mov_b32 m0, s46
	s_nop 0
	global_load_lds_dwordx4 v[222:223], off
	s_waitcnt vmcnt(8)
	s_waitcnt lgkmcnt(0)
	s_barrier
; #define PG8_STAGE(bufoff, gbase, voff) do { _Pragma("unroll") for (int _i = 0; _i < 2; ++_i) \
;         __builtin_amdgcn_global_load_lds((const unsigned*)((const char*)(gbase) + (voff)[_i]), (PG8_LAS unsigned*)(lds + (bufoff) + ldsw + _i * 8192), 16, 0, 0); } while (0)
; #define PG8_LDA(dst, b, h) do { _Pragma("unroll") for (int m = 0; m < 4; ++m) _Pragma("unroll") for (int k = 0; k < 2; ++k) dst[m][k] = *(const PG8_LAS bf16x8*)(lds + PG8_SA(b, h) + aoff + m * 2048 + k * 1024); } while (0)
; #define PG8_LDB(dst, b, h) do { _Pragma("unroll") for (int n = 0; n < 2; ++n) _Pragma("unroll") for (int k = 0; k < 2; ++k) dst[n][k] = *(const PG8_LAS bf16x8*)(lds + PG8_SB(b, h) + boff + n * 2048 + k * 1024); } while (0)
; #define PG8_MMA(ai, bj, At, Bt) do { __builtin_amdgcn_s_setprio(1); _Pragma("unroll") for (int m = 0; m < 4; ++m) _Pragma("unroll") for (int n = 0; n < 2; ++n) _Pragma("unroll") for (int k = 0; k < 2; ++k) \
;         acc[ai][bj][m][n] = __builtin_amdgcn_mfma_f32_16x16x32_bf16(Bt[n][k], At[m][k], acc[ai][bj][m][n], 0, 0, 0); __builtin_amdgcn_s_setprio(0); } while (0)
; #define PG8_WAIT_V(n) asm volatile("s_waitcnt vmcnt(" #n ")" ::: "memory")
; #define PG8_WAIT_L(n) asm volatile("s_waitcnt lgkmcnt(" #n ")" ::: "memory")
; #define PG8_BAR __builtin_amdgcn_s_barrier()
; #define PG8_SCHED __builtin_amdgcn_sched_barrier(0)
; template <class Epi, class Sched, bool ALIGN_EPI = false, bool SP2 = false>
; __device__ __forceinline__ void gemm_phase(PG8_LAS unsigned char* lds, const Gemm g, const Sched& S, const Epi& E) {
;     ...
;             PG8_WAIT_V(8); PG8_WAIT_L(0); PG8_BAR; PG8_MMA(1, 0, At, B0); PG8_MMA(1, 1, At, B1); PG8_BAR; PG8_SCHED;
;             PG8_LDB(B0, 1, 0); PG8_LDB(B1, 1, 1); PG8_SCHED; PG8_LDA(At, 1, 0); PG8_STAGE(PG8_SA(0, 1), a2 + hstep, voffA);
;             PG8_WAIT_V(8); PG8_WAIT_L(0); PG8_BAR; PG8_MMA(0, 0, At, B0); PG8_MMA(0, 1, At, B1); PG8_BAR; PG8_SCHED;
	s_setprio 1
	s_waitcnt lgkmcnt(0)
	v_mfma_f32_16x16x32_bf16 v[60:63], v[142:145], v[182:185], v[60:63]
	v_mfma_f32_16x16x32_bf16 v[56:59], v[150:153], v[182:185], v[56:59]
	v_mfma_f32_16x16x32_bf16 v[44:47], v[142:145], v[190:193], v[44:47]
	v_mfma_f32_16x16x32_bf16 v[40:43], v[150:153], v[190:193], v[40:43]
	v_mfma_f32_16x16x32_bf16 v[28:31], v[142:145], v[198:201], v[28:31]
	v_mfma_f32_16x16x32_bf16 v[24:27], v[150:153], v[198:201], v[24:27]
	v_mfma_f32_16x16x32_bf16 v[12:15], v[142:145], v[206:209], v[12:15]
	v_mfma_f32_16x16x32_bf16 v[8:11], v[150:153], v[206:209], v[8:11]
	v_mfma_f32_16x16x32_bf16 v[60:63], v[146:149], v[186:189], v[60:63]
	v_mfma_f32_16x16x32_bf16 v[56:59], v[154:157], v[186:189], v[56:59]
	v_mfma_f32_16x16x32_bf16 v[44:47], v[146:149], v[194:197], v[44:47]
	v_mfma_f32_16x16x32_bf16 v[40:43], v[154:157], v[194:197], v[40:43]
	v_mfma_f32_16x16x32_bf16 v[28:31], v[146:149], v[202:205], v[28:31]
	v_mfma_f32_16x16x32_bf16 v[24:27], v[154:157], v[202:205], v[24:27]
	v_mfma_f32_16x16x32_bf16 v[12:15], v[146:149], v[210:213], v[12:15]
	v_mfma_f32_16x16x32_bf16 v[8:11], v[154:157], v[210:213], v[8:11]
	v_mfma_f32_16x16x32_bf16 v[52:55], v[158:161], v[182:185], v[52:55]
	v_mfma_f32_16x16x32_bf16 v[48:51], v[166:169], v[182:185], v[48:51]
	v_mfma_f32_16x16x32_bf16 v[36:39], v[158:161], v[190:193], v[36:39]
	v_mfma_f32_16x16x32_bf16 v[32:35], v[166:169], v[190:193], v[32:35]
	v_mfma_f32_16x16x32_bf16 v[20:23], v[158:161], v[198:201], v[20:23]
	v_mfma_f32_16x16x32_bf16 v[16:19], v[166:169], v[198:201], v[16:19]
	v_mfma_f32_16x16x32_bf16 v[4:7], v[158:161], v[206:209], v[4:7]
	v_mfma_f32_16x16x32_bf16 v[0:3], v[166:169], v[206:209], v[0:3]
	v_mfma_f32_16x16x32_bf16 v[52:55], v[162:165], v[186:189], v[52:55]
	v_mfma_f32_16x16x32_bf16 v[48:51], v[170:173], v[186:189], v[48:51]
	v_mfma_f32_16x16x32_bf16 v[36:39], v[162:165], v[194:197], v[36:39]
	v_mfma_f32_16x16x32_bf16 v[32:35], v[170:173], v[194:197], v[32:35]
	v_mfma_f32_16x16x32_bf16 v[20:23], v[162:165], v[202:205], v[20:23]
	v_mfma_f32_16x16x32_bf16 v[16:19], v[170:173], v[202:205], v[16:19]
	v_mfma_f32_16x16x32_bf16 v[4:7], v[162:165], v[210:213], v[4:7]
	v_mfma_f32_16x16x32_bf16 v[0:3], v[170:173], v[210:213], v[0:3]
	s_setprio 0
	s_barrier
	s_add_i32 s28, 0, 0x18000
	s_add_i32 s48, 0, 0x1c000
	v_add_u32_e32 v154, s28, v140
	v_add_u32_e32 v170, s48, v140
	ds_read_b128 v[142:145], v154
	ds_read_b128 v[146:149], v154 offset:1024
	ds_read_b128 v[150:153], v154 offset:2048
	ds_read_b128 v[154:157], v154 offset:3072
	ds_read_b128 v[158:161], v170
	ds_read_b128 v[162:165], v170 offset:1024
	ds_read_b128 v[166:169], v170 offset:2048
	ds_read_b128 v[170:173], v170 offset:3072
	s_add_u32 s38, s64, s10
	s_addc_u32 s39, s65, s11
	s_mov_b32 m0, s63
	v_lshl_add_u64 v[224:225], s[38:39], 0, v[128:129]
	ds_read_b128 v[182:185], v141 offset:32768
	ds_read_b128 v[186:189], v141 offset:33792
	ds_read_b128 v[190:193], v141 offset:34816
	ds_read_b128 v[194:197], v141 offset:35840
	ds_read_b128 v[198:201], v141 offset:36864
	ds_read_b128 v[202:205], v141 offset:37888
	ds_read_b128 v[206:209], v141 offset:38912
	ds_read_b128 v[210:213], v141 offset:39936
	global_load_lds_dwordx4 v[224:225], off
	v_lshl_add_u64 v[224:225], s[38:39], 0, v[130:131]
	s_mov_b32 m0, s66
	s_nop 0
	global_load_lds_dwordx4 v[224:225], off
	s_waitcnt vmcnt(8)
	s_waitcnt lgkmcnt(0)
	s_barrier
	s_setprio 1
	s_waitcnt lgkmcnt(0)
	v_mfma_f32_16x16x32_bf16 v[120:123], v[142:145], v[182:185], v[120:123]
	v_mfma_f32_16x16x32_bf16 v[124:127], v[150:153], v[182:185], v[124:127]
	v_mfma_f32_16x16x32_bf16 v[108:111], v[142:145], v[190:193], v[108:111]
	v_mfma_f32_16x16x32_bf16 v[104:107], v[150:153], v[190:193], v[104:107]
	v_mfma_f32_16x16x32_bf16 v[92:95], v[142:145], v[198:201], v[92:95]
	v_mfma_f32_16x16x32_bf16 v[88:91], v[150:153], v[198:201], v[88:91]
	v_mfma_f32_16x16x32_bf16 v[76:79], v[142:145], v[206:209], v[76:79]
	v_mfma_f32_16x16x32_bf16 v[72:75], v[150:153], v[206:209], v[72:75]
	v_mfma_f32_16x16x32_bf16 v[120:123], v[146:149], v[186:189], v[120:123]
	v_mfma_f32_16x16x32_bf16 v[124:127], v[154:157], v[186:189], v[124:127]
	v_mfma_f32_16x16x32_bf16 v[108:111], v[146:149], v[194:197], v[108:111]
	v_mfma_f32_16x16x32_bf16 v[104:107], v[154:157], v[194:197], v[104:107]
	v_mfma_f32_16x16x32_bf16 v[92:95], v[146:149], v[202:205], v[92:95]
	v_mfma_f32_16x16x32_bf16 v[88:91], v[154:157], v[202:205], v[88:91]
	v_mfma_f32_16x16x32_bf16 v[76:79], v[146:149], v[210:213], v[76:79]
	v_mfma_f32_16x16x32_bf16 v[72:75], v[154:157], v[210:213], v[72:75]
	v_mfma_f32_16x16x32_bf16 v[116:119], v[158:161], v[182:185], v[116:119]
	v_mfma_f32_16x16x32_bf16 v[112:115], v[166:169], v[182:185], v[112:115]
	v_mfma_f32_16x16x32_bf16 v[100:103], v[158:161], v[190:193], v[100:103]
	v_mfma_f32_16x16x32_bf16 v[96:99], v[166:169], v[190:193], v[96:99]
	v_mfma_f32_16x16x32_bf16 v[84:87], v[158:161], v[198:201], v[84:87]
	v_mfma_f32_16x16x32_bf16 v[80:83], v[166:169], v[198:201], v[80:83]
	v_mfma_f32_16x16x32_bf16 v[68:71], v[158:161], v[206:209], v[68:71]
	v_mfma_f32_16x16x32_bf16 v[64:67], v[166:169], v[206:209], v[64:67]
	v_mfma_f32_16x16x32_bf16 v[116:119], v[162:165], v[186:189], v[116:119]
	v_mfma_f32_16x16x32_bf16 v[112:115], v[170:173], v[186:189], v[112:115]
	v_mfma_f32_16x16x32_bf16 v[100:103], v[162:165], v[194:197], v[100:103]
	v_mfma_f32_16x16x32_bf16 v[96:99], v[170:173], v[194:197], v[96:99]
	v_mfma_f32_16x16x32_bf16 v[84:87], v[162:165], v[202:205], v[84:87]
	v_mfma_f32_16x16x32_bf16 v[80:83], v[170:173], v[202:205], v[80:83]
	v_mfma_f32_16x16x32_bf16 v[68:71], v[162:165], v[210:213], v[68:71]
	v_mfma_f32_16x16x32_bf16 v[64:67], v[170:173], v[210:213], v[64:67]
	s_setprio 0
	s_barrier
; #define PG8_STAGE(bufoff, gbase, voff) do { _Pragma("unroll") for (int _i = 0; _i < 2; ++_i) \
;         __builtin_amdgcn_global_load_lds((const unsigned*)((const char*)(gbase) + (voff)[_i]), (PG8_LAS unsigned*)(lds + (bufoff) + ldsw + _i * 8192), 16, 0, 0); } while (0)
; #define PG8_LDA(dst, b, h) do { _Pragma("unroll") for (int m = 0; m < 4; ++m) _Pragma("unroll") for (int k = 0; k < 2; ++k) dst[m][k] = *(const PG8_LAS bf16x8*)(lds + PG8_SA(b, h) + aoff + m * 2048 + k * 1024); } while (0)
; #define PG8_MMA(ai, bj, At, Bt) do { __builtin_amdgcn_s_setprio(1); _Pragma("unroll") for (int m = 0; m < 4; ++m) _Pragma("unroll") for (int n = 0; n < 2; ++n) _Pragma("unroll") for (int k = 0; k < 2; ++k) \
;         acc[ai][bj][m][n] = __builtin_amdgcn_mfma_f32_16x16x32_bf16(Bt[n][k], At[m][k], acc[ai][bj][m][n], 0, 0, 0); __builtin_amdgcn_s_setprio(0); } while (0)
; #define PG8_WAIT_V(n) asm volatile("s_waitcnt vmcnt(" #n ")" ::: "memory")
; #define PG8_WAIT_L(n) asm volatile("s_waitcnt lgkmcnt(" #n ")" ::: "memory")
; #define PG8_BAR __builtin_amdgcn_s_barrier()
; #define PG8_SCHED __builtin_amdgcn_sched_barrier(0)
; template <class Epi, class Sched, bool ALIGN_EPI = false, bool SP2 = false>
; __device__ __forceinline__ void gemm_phase(PG8_LAS unsigned char* lds, const Gemm g, const Sched& S, const Epi& E) {
;     ...
;             PG8_LDA(At, 1, 1); PG8_STAGE(PG8_SB(1, 0), b3, voffB); PG8_STAGE(PG8_SB(1, 1), b3 + hstep, voffB); PG8_STAGE(PG8_SA(1, 0), a3, voffA);
;             PG8_WAIT_V(8); PG8_WAIT_L(0); PG8_BAR; PG8_MMA(1, 0, At, B0); PG8_MMA(1, 1, At, B1); PG8_BAR; PG8_SCHED;
	s_add_i32 s28, s28, s24
	v_lshl_add_u64 v[174:175], v[174:175], 0, s[44:45]
	s_mov_b32 m0, s28
	ds_read_b128 v[182:185], v141 offset:49152
	ds_read_b128 v[186:189], v141 offset:50176
	ds_read_b128 v[190:193], v141 offset:51200
	ds_read_b128 v[194:197], v141 offset:52224
	ds_read_b128 v[198:201], v141 offset:53248
	ds_read_b128 v[202:205], v141 offset:54272
	ds_read_b128 v[206:209], v141 offset:55296
	ds_read_b128 v[210:213], v141 offset:56320
	global_load_lds_dwordx4 v[174:175], off
	v_lshl_add_u64 v[174:175], v[214:215], 0, s[44:45]
	s_add_i32 m0, s28, 0x2000
	s_add_i32 s28, s48, s24
	global_load_lds_dwordx4 v[174:175], off
	v_lshl_add_u64 v[174:175], v[216:217], 0, s[44:45]
	s_mov_b32 m0, s28
	s_nop 0
	global_load_lds_dwordx4 v[174:175], off
	v_lshl_add_u64 v[174:175], v[218:219], 0, s[44:45]
	s_add_i32 m0, s28, 0x2000
	s_nop 0
	global_load_lds_dwordx4 v[174:175], off
	v_lshl_add_u64 v[174:175], v[220:221], 0, s[44:45]
	s_mov_b32 m0, s72
	s_nop 0
	global_load_lds_dwordx4 v[174:175], off
	v_lshl_add_u64 v[174:175], v[222:223], 0, s[44:45]
	s_mov_b32 m0, s73
	s_nop 0
	global_load_lds_dwordx4 v[174:175], off
	s_waitcnt vmcnt(8)
	s_waitcnt lgkmcnt(0)
	s_barrier
	s_setprio 1
	s_waitcnt lgkmcnt(0)
	v_mfma_f32_16x16x32_bf16 v[60:63], v[142:145], v[182:185], v[60:63]
	v_mfma_f32_16x16x32_bf16 v[56:59], v[150:153], v[182:185], v[56:59]
	v_mfma_f32_16x16x32_bf16 v[44:47], v[142:145], v[190:193], v[44:47]
	v_mfma_f32_16x16x32_bf16 v[40:43], v[150:153], v[190:193], v[40:43]
	v_mfma_f32_16x16x32_bf16 v[28:31], v[142:145], v[198:201], v[28:31]
	v_mfma_f32_16x16x32_bf16 v[24:27], v[150:153], v[198:201], v[24:27]
	v_mfma_f32_16x16x32_bf16 v[12:15], v[142:145], v[206:209], v[12:15]
	v_mfma_f32_16x16x32_bf16 v[8:11], v[150:153], v[206:209], v[8:11]
	v_mfma_f32_16x16x32_bf16 v[60:63], v[146:149], v[186:189], v[60:63]
	v_mfma_f32_16x16x32_bf16 v[56:59], v[154:157], v[186:189], v[56:59]
	v_mfma_f32_16x16x32_bf16 v[44:47], v[146:149], v[194:197], v[44:47]
	v_mfma_f32_16x16x32_bf16 v[40:43], v[154:157], v[194:197], v[40:43]
	v_mfma_f32_16x16x32_bf16 v[28:31], v[146:149], v[202:205], v[28:31]
	v_mfma_f32_16x16x32_bf16 v[24:27], v[154:157], v[202:205], v[24:27]
	v_mfma_f32_16x16x32_bf16 v[12:15], v[146:149], v[210:213], v[12:15]
	v_mfma_f32_16x16x32_bf16 v[8:11], v[154:157], v[210:213], v[8:11]
	v_mfma_f32_16x16x32_bf16 v[52:55], v[158:161], v[182:185], v[52:55]
	v_mfma_f32_16x16x32_bf16 v[48:51], v[166:169], v[182:185], v[48:51]
	v_mfma_f32_16x16x32_bf16 v[36:39], v[158:161], v[190:193], v[36:39]
	v_mfma_f32_16x16x32_bf16 v[32:35], v[166:169], v[190:193], v[32:35]
	v_mfma_f32_16x16x32_bf16 v[20:23], v[158:161], v[198:201], v[20:23]
	v_mfma_f32_16x16x32_bf16 v[16:19], v[166:169], v[198:201], v[16:19]
	v_mfma_f32_16x16x32_bf16 v[4:7], v[158:161], v[206:209], v[4:7]
	v_mfma_f32_16x16x32_bf16 v[0:3], v[166:169], v[206:209], v[0:3]
	v_mfma_f32_16x16x32_bf16 v[52:55], v[162:165], v[186:189], v[52:55]
	v_mfma_f32_16x16x32_bf16 v[48:51], v[170:173], v[186:189], v[48:51]
	s_add_u32 s40, s40, 0x100
	v_mfma_f32_16x16x32_bf16 v[36:39], v[162:165], v[194:197], v[36:39]
	s_addc_u32 s41, s41, 0
	v_mfma_f32_16x16x32_bf16 v[32:35], v[170:173], v[194:197], v[32:35]
	s_add_u32 s78, s78, 0x100
	v_mfma_f32_16x16x32_bf16 v[20:23], v[162:165], v[202:205], v[20:23]
	s_addc_u32 s79, s79, 0
	v_mfma_f32_16x16x32_bf16 v[16:19], v[170:173], v[202:205], v[16:19]
	s_cmp_ge_i32 s80, s67
	v_mfma_f32_16x16x32_bf16 v[4:7], v[162:165], v[210:213], v[4:7]
	s_mov_b32 s64, s80
	v_mfma_f32_16x16x32_bf16 v[0:3], v[170:173], v[210:213], v[0:3]
	s_setprio 0
	s_barrier
	s_cbranch_scc0 .LBB0_375
	v_readlane_b32 s80, v254, 45
	v_readlane_b32 s78, v254, 43
	v_readlane_b32 s81, v254, 46
	v_readlane_b32 s82, v254, 47
	v_readlane_b32 s83, v254, 48
	v_readlane_b32 s84, v254, 49
	v_readlane_b32 s85, v254, 50
	v_readlane_b32 s86, v254, 51
	v_readlane_b32 s87, v254, 52
	v_readlane_b32 s88, v254, 53
	v_readlane_b32 s89, v254, 54
	v_readlane_b32 s92, v254, 57
	v_readlane_b32 s93, v254, 58
	v_readlane_b32 s94, v254, 59
	v_readlane_b32 s95, v254, 60
	v_readlane_b32 s79, v254, 44
	v_readlane_b32 s90, v254, 55
	v_readlane_b32 s91, v254, 56

; #define PG8_STAGE(bufoff, gbase, voff) do { _Pragma("unroll") for (int _i = 0; _i < 2; ++_i) \
;         __builtin_amdgcn_global_load_lds((const unsigned*)((const char*)(gbase) + (voff)[_i]), (PG8_LAS unsigned*)(lds + (bufoff) + ldsw + _i * 8192), 16, 0, 0); } while (0)
; #define PG8_LDA(dst, b, h) do { _Pragma("unroll") for (int m = 0; m < 4; ++m) _Pragma("unroll") for (int k = 0; k < 2; ++k) dst[m][k] = *(const PG8_LAS bf16x8*)(lds + PG8_SA(b, h) + aoff + m * 2048 + k * 1024); } while (0)
; #define PG8_LDB(dst, b, h) do { _Pragma("unroll") for (int n = 0; n < 2; ++n) _Pragma("unroll") for (int k = 0; k < 2; ++k) dst[n][k] = *(const PG8_LAS bf16x8*)(lds + PG8_SB(b, h) + boff + n * 2048 + k * 1024); } while (0)
; #define PG8_MMA(ai, bj, At, Bt) do { __builtin_amdgcn_s_setprio(1); _Pragma("unroll") for (int m = 0; m < 4; ++m) _Pragma("unroll") for (int n = 0; n < 2; ++n) _Pragma("unroll") for (int k = 0; k < 2; ++k) \
;         acc[ai][bj][m][n] = __builtin_amdgcn_mfma_f32_16x16x32_bf16(Bt[n][k], At[m][k], acc[ai][bj][m][n], 0, 0, 0); __builtin_amdgcn_s_setprio(0); } while (0)
; #define PG8_WAIT_V(n) asm volatile("s_waitcnt vmcnt(" #n ")" ::: "memory")
; #define PG8_WAIT_L(n) asm volatile("s_waitcnt lgkmcnt(" #n ")" ::: "memory")
; #define PG8_BAR __builtin_amdgcn_s_barrier()
; #define PG8_SCHED __builtin_amdgcn_sched_barrier(0)
; template <class Epi, class Sched, bool ALIGN_EPI = false, bool SP2 = false>
; __device__ __forceinline__ void gemm_phase(PG8_LAS unsigned char* lds, const Gemm g, const Sched& S, const Epi& E) {
;     ...
;             const bool last = (t == nt - 2);
;             const char* a1 = cA + (size_t)(t + 1) * kstep;
;             const char* a2 = last ? nA : cA + (size_t)(t + 2) * kstep; const char* b2 = last ? nB : cB + (size_t)(t + 2) * kstep;
;             const char* a3 = a2 + kstep; const char* b3 = b2 + kstep;
;             if (last && has_next) S.a_ready(nxt);
;             if constexpr (SP2) {
;             PG8_LDB(B0, 0, 0); PG8_LDB(B1, 0, 1); PG8_SCHED; PG8_LDA(At, 0, 0); PG8_STAGE(PG8_SA(1, 1), a1 + hstep, voffA);
;             PG8_WAIT_V(8); PG8_WAIT_L(0); PG8_BAR; PG8_MMA(0, 0, At, B0); PG8_MMA(0, 1, At, B1); PG8_BAR; PG8_SCHED;
;             PG8_LDA(At, 0, 1); PG8_STAGE(PG8_SB(0, 0), b2, voffB); PG8_STAGE(PG8_SB(0, 1), b2 + hstep, voffB); PG8_STAGE(PG8_SA(0, 0), a2, voffA);
.LBB0_406:
	s_add_i32 s81, s66, 2
	s_add_u32 s28, s64, 0x80
	s_addc_u32 s38, s65, 0
	s_add_i32 s48, 0, 0x10000
	s_cmp_eq_u32 s75, s66
	s_cselect_b32 s67, s7, s38
	s_cselect_b32 s66, s6, s28
	s_cselect_b32 s39, s41, s80
	s_cselect_b32 s38, s40, s79
	s_add_i32 s28, 0, 0x14000
	v_add_u32_e32 v154, s48, v148
	v_add_u32_e32 v170, s28, v148
	ds_read_b128 v[138:141], v154
	ds_read_b128 v[142:145], v154 offset:1024
	ds_read_b128 v[150:153], v154 offset:2048
	ds_read_b128 v[154:157], v154 offset:3072
	ds_read_b128 v[158:161], v170
	ds_read_b128 v[162:165], v170 offset:1024
	ds_read_b128 v[166:169], v170 offset:2048
	ds_read_b128 v[170:173], v170 offset:3072
	v_lshl_add_u64 v[174:175], s[64:65], 0, v[134:135]
	s_add_i32 m0, s43, 0xc000
	ds_read_b128 v[182:185], v149
	ds_read_b128 v[186:189], v149 offset:1024
	ds_read_b128 v[190:193], v149 offset:2048
	ds_read_b128 v[194:197], v149 offset:3072
	ds_read_b128 v[198:201], v149 offset:4096
	ds_read_b128 v[202:205], v149 offset:5120
	ds_read_b128 v[206:209], v149 offset:6144
	ds_read_b128 v[210:213], v149 offset:7168
	global_load_lds_dwordx4 v[174:175], off
	v_lshl_add_u64 v[174:175], s[64:65], 0, v[136:137]
	s_add_i32 m0, s43, 0xe000
	s_nop 0
	global_load_lds_dwordx4 v[174:175], off
	s_waitcnt vmcnt(8)
	s_waitcnt lgkmcnt(0)
	s_barrier
	s_setprio 1
	s_waitcnt lgkmcnt(0)
	v_mfma_f32_16x16x32_bf16 v[124:127], v[138:141], v[182:185], v[124:127]
	v_mfma_f32_16x16x32_bf16 v[120:123], v[150:153], v[182:185], v[120:123]
	v_mfma_f32_16x16x32_bf16 v[116:119], v[138:141], v[190:193], v[116:119]
	v_mfma_f32_16x16x32_bf16 v[112:115], v[150:153], v[190:193], v[112:115]
	v_mfma_f32_16x16x32_bf16 v[104:107], v[138:141], v[198:201], v[104:107]
	v_mfma_f32_16x16x32_bf16 v[96:99], v[150:153], v[198:201], v[96:99]
	v_mfma_f32_16x16x32_bf16 v[88:91], v[138:141], v[206:209], v[88:91]
	v_mfma_f32_16x16x32_bf16 v[80:83], v[150:153], v[206:209], v[80:83]
	v_mfma_f32_16x16x32_bf16 v[124:127], v[142:145], v[186:189], v[124:127]
	v_mfma_f32_16x16x32_bf16 v[120:123], v[154:157], v[186:189], v[120:123]
	v_mfma_f32_16x16x32_bf16 v[116:119], v[142:145], v[194:197], v[116:119]
	v_mfma_f32_16x16x32_bf16 v[112:115], v[154:157], v[194:197], v[112:115]
	v_mfma_f32_16x16x32_bf16 v[104:107], v[142:145], v[202:205], v[104:107]
	v_mfma_f32_16x16x32_bf16 v[96:99], v[154:157], v[202:205], v[96:99]
	v_mfma_f32_16x16x32_bf16 v[88:91], v[142:145], v[210:213], v[88:91]
	v_mfma_f32_16x16x32_bf16 v[80:83], v[154:157], v[210:213], v[80:83]
	v_mfma_f32_16x16x32_bf16 v[108:111], v[158:161], v[182:185], v[108:111]
	v_mfma_f32_16x16x32_bf16 v[100:103], v[166:169], v[182:185], v[100:103]
	v_mfma_f32_16x16x32_bf16 v[92:95], v[158:161], v[190:193], v[92:95]
	v_mfma_f32_16x16x32_bf16 v[84:87], v[166:169], v[190:193], v[84:87]
	v_mfma_f32_16x16x32_bf16 v[76:79], v[158:161], v[198:201], v[76:79]
	v_mfma_f32_16x16x32_bf16 v[72:75], v[166:169], v[198:201], v[72:75]
	v_mfma_f32_16x16x32_bf16 v[68:71], v[158:161], v[206:209], v[68:71]
	v_mfma_f32_16x16x32_bf16 v[64:67], v[166:169], v[206:209], v[64:67]
	v_mfma_f32_16x16x32_bf16 v[108:111], v[162:165], v[186:189], v[108:111]
	v_mfma_f32_16x16x32_bf16 v[100:103], v[170:173], v[186:189], v[100:103]
	v_mfma_f32_16x16x32_bf16 v[92:95], v[162:165], v[194:197], v[92:95]
	v_mfma_f32_16x16x32_bf16 v[84:87], v[170:173], v[194:197], v[84:87]
	v_mfma_f32_16x16x32_bf16 v[76:79], v[162:165], v[202:205], v[76:79]
	v_mfma_f32_16x16x32_bf16 v[72:75], v[170:173], v[202:205], v[72:75]
	v_mfma_f32_16x16x32_bf16 v[68:71], v[162:165], v[210:213], v[68:71]
	v_mfma_f32_16x16x32_bf16 v[64:67], v[170:173], v[210:213], v[64:67]
	s_setprio 0
	s_barrier
	s_add_i32 s48, s48, s24
	v_lshl_add_u64 v[174:175], s[38:39], 0, v[176:177]
	s_mov_b32 m0, s48
	ds_read_b128 v[182:185], v149 offset:16384
	ds_read_b128 v[186:189], v149 offset:17408
	ds_read_b128 v[190:193], v149 offset:18432
	ds_read_b128 v[194:197], v149 offset:19456
	ds_read_b128 v[198:201], v149 offset:20480
	ds_read_b128 v[202:205], v149 offset:21504
	ds_read_b128 v[206:209], v149 offset:22528
	ds_read_b128 v[210:213], v149 offset:23552
	global_load_lds_dwordx4 v[174:175], off
	s_add_i32 m0, s48, 0x2000
	v_lshl_add_u64 v[214:215], s[38:39], 0, v[132:133]
	s_add_u32 s38, s38, s10
	s_addc_u32 s39, s39, s11
	s_add_i32 s28, s28, s24
	global_load_lds_dwordx4 v[214:215], off
	v_lshl_add_u64 v[216:217], s[38:39], 0, v[176:177]
	s_mov_b32 m0, s28
	v_lshl_add_u64 v[218:219], s[38:39], 0, v[132:133]
	global_load_lds_dwordx4 v[216:217], off
	s_add_i32 m0, s28, 0x2000
	v_lshl_add_u64 v[220:221], s[66:67], 0, v[128:129]
	global_load_lds_dwordx4 v[218:219], off
	s_mov_b32 m0, s43
	v_lshl_add_u64 v[222:223], s[66:67], 0, v[130:131]
	global_load_lds_dwordx4 v[220:221], off
	s_mov_b32 m0, s46
	s_nop 0
	global_load_lds_dwordx4 v[222:223], off
	s_waitcnt vmcnt(8)
	s_waitcnt lgkmcnt(0)
	s_barrier
; #define PG8_STAGE(bufoff, gbase, voff) do { _Pragma("unroll") for (int _i = 0; _i < 2; ++_i) \
;         __builtin_amdgcn_global_load_lds((const unsigned*)((const char*)(gbase) + (voff)[_i]), (PG8_LAS unsigned*)(lds + (bufoff) + ldsw + _i * 8192), 16, 0, 0); } while (0)
; #define PG8_LDA(dst, b, h) do { _Pragma("unroll") for (int m = 0; m < 4; ++m) _Pragma("unroll") for (int k = 0; k < 2; ++k) dst[m][k] = *(const PG8_LAS bf16x8*)(lds + PG8_SA(b, h) + aoff + m * 2048 + k * 1024); } while (0)
; #define PG8_LDB(dst, b, h) do { _Pragma("unroll") for (int n = 0; n < 2; ++n) _Pragma("unroll") for (int k = 0; k < 2; ++k) dst[n][k] = *(const PG8_LAS bf16x8*)(lds + PG8_SB(b, h) + boff + n * 2048 + k * 1024); } while (0)
; #define PG8_MMA(ai, bj, At, Bt) do { __builtin_amdgcn_s_setprio(1); _Pragma("unroll") for (int m = 0; m < 4; ++m) _Pragma("unroll") for (int n = 0; n < 2; ++n) _Pragma("unroll") for (int k = 0; k < 2; ++k) \
;         acc[ai][bj][m][n] = __builtin_amdgcn_mfma_f32_16x16x32_bf16(Bt[n][k], At[m][k], acc[ai][bj][m][n], 0, 0, 0); __builtin_amdgcn_s_setprio(0); } while (0)
; #define PG8_WAIT_V(n) asm volatile("s_waitcnt vmcnt(" #n ")" ::: "memory")
; #define PG8_WAIT_L(n) asm volatile("s_waitcnt lgkmcnt(" #n ")" ::: "memory")
; #define PG8_BAR __builtin_amdgcn_s_barrier()
; #define PG8_SCHED __builtin_amdgcn_sched_barrier(0)
; template <class Epi, class Sched, bool ALIGN_EPI = false, bool SP2 = false>
; __device__ __forceinline__ void gemm_phase(PG8_LAS unsigned char* lds, const Gemm g, const Sched& S, const Epi& E) {
;     ...
;             PG8_WAIT_V(8); PG8_WAIT_L(0); PG8_BAR; PG8_MMA(1, 0, At, B0); PG8_MMA(1, 1, At, B1); PG8_BAR; PG8_SCHED;
;             PG8_LDB(B0, 1, 0); PG8_LDB(B1, 1, 1); PG8_SCHED; PG8_LDA(At, 1, 0); PG8_STAGE(PG8_SA(0, 1), a2 + hstep, voffA);
;             PG8_WAIT_V(8); PG8_WAIT_L(0); PG8_BAR; PG8_MMA(0, 0, At, B0); PG8_MMA(0, 1, At, B1); PG8_BAR; PG8_SCHED;
	s_setprio 1
	s_waitcnt lgkmcnt(0)
	v_mfma_f32_16x16x32_bf16 v[60:63], v[138:141], v[182:185], v[60:63]
	v_mfma_f32_16x16x32_bf16 v[56:59], v[150:153], v[182:185], v[56:59]
	v_mfma_f32_16x16x32_bf16 v[52:55], v[138:141], v[190:193], v[52:55]
	v_mfma_f32_16x16x32_bf16 v[48:51], v[150:153], v[190:193], v[48:51]
	v_mfma_f32_16x16x32_bf16 v[40:43], v[138:141], v[198:201], v[40:43]
	v_mfma_f32_16x16x32_bf16 v[32:35], v[150:153], v[198:201], v[32:35]
	v_mfma_f32_16x16x32_bf16 v[24:27], v[138:141], v[206:209], v[24:27]
	v_mfma_f32_16x16x32_bf16 v[16:19], v[150:153], v[206:209], v[16:19]
	v_mfma_f32_16x16x32_bf16 v[60:63], v[142:145], v[186:189], v[60:63]
	v_mfma_f32_16x16x32_bf16 v[56:59], v[154:157], v[186:189], v[56:59]
	v_mfma_f32_16x16x32_bf16 v[52:55], v[142:145], v[194:197], v[52:55]
	v_mfma_f32_16x16x32_bf16 v[48:51], v[154:157], v[194:197], v[48:51]
	v_mfma_f32_16x16x32_bf16 v[40:43], v[142:145], v[202:205], v[40:43]
	v_mfma_f32_16x16x32_bf16 v[32:35], v[154:157], v[202:205], v[32:35]
	v_mfma_f32_16x16x32_bf16 v[24:27], v[142:145], v[210:213], v[24:27]
	v_mfma_f32_16x16x32_bf16 v[16:19], v[154:157], v[210:213], v[16:19]
	v_mfma_f32_16x16x32_bf16 v[44:47], v[158:161], v[182:185], v[44:47]
	v_mfma_f32_16x16x32_bf16 v[36:39], v[166:169], v[182:185], v[36:39]
	v_mfma_f32_16x16x32_bf16 v[28:31], v[158:161], v[190:193], v[28:31]
	v_mfma_f32_16x16x32_bf16 v[20:23], v[166:169], v[190:193], v[20:23]
	v_mfma_f32_16x16x32_bf16 v[12:15], v[158:161], v[198:201], v[12:15]
	v_mfma_f32_16x16x32_bf16 v[8:11], v[166:169], v[198:201], v[8:11]
	v_mfma_f32_16x16x32_bf16 v[4:7], v[158:161], v[206:209], v[4:7]
	v_mfma_f32_16x16x32_bf16 v[0:3], v[166:169], v[206:209], v[0:3]
	v_mfma_f32_16x16x32_bf16 v[44:47], v[162:165], v[186:189], v[44:47]
	v_mfma_f32_16x16x32_bf16 v[36:39], v[170:173], v[186:189], v[36:39]
	v_mfma_f32_16x16x32_bf16 v[28:31], v[162:165], v[194:197], v[28:31]
	v_mfma_f32_16x16x32_bf16 v[20:23], v[170:173], v[194:197], v[20:23]
	v_mfma_f32_16x16x32_bf16 v[12:15], v[162:165], v[202:205], v[12:15]
	v_mfma_f32_16x16x32_bf16 v[8:11], v[170:173], v[202:205], v[8:11]
	v_mfma_f32_16x16x32_bf16 v[4:7], v[162:165], v[210:213], v[4:7]
	v_mfma_f32_16x16x32_bf16 v[0:3], v[170:173], v[210:213], v[0:3]
	s_setprio 0
	s_barrier
	s_add_i32 s28, 0, 0x18000
	s_add_i32 s48, 0, 0x1c000
	v_add_u32_e32 v154, s28, v148
	v_add_u32_e32 v170, s48, v148
	ds_read_b128 v[138:141], v154
	ds_read_b128 v[142:145], v154 offset:1024
	ds_read_b128 v[150:153], v154 offset:2048
	ds_read_b128 v[154:157], v154 offset:3072
	ds_read_b128 v[158:161], v170
	ds_read_b128 v[162:165], v170 offset:1024
	ds_read_b128 v[166:169], v170 offset:2048
	ds_read_b128 v[170:173], v170 offset:3072
	s_add_u32 s38, s66, s10
	s_addc_u32 s39, s67, s11
	s_mov_b32 m0, s63
	v_lshl_add_u64 v[224:225], s[38:39], 0, v[128:129]
	ds_read_b128 v[182:185], v149 offset:32768
	ds_read_b128 v[186:189], v149 offset:33792
	ds_read_b128 v[190:193], v149 offset:34816
	ds_read_b128 v[194:197], v149 offset:35840
	ds_read_b128 v[198:201], v149 offset:36864
	ds_read_b128 v[202:205], v149 offset:37888
	ds_read_b128 v[206:209], v149 offset:38912
	ds_read_b128 v[210:213], v149 offset:39936
	global_load_lds_dwordx4 v[224:225], off
	v_lshl_add_u64 v[224:225], s[38:39], 0, v[130:131]
	s_mov_b32 m0, s68
	s_nop 0
	global_load_lds_dwordx4 v[224:225], off
	s_waitcnt vmcnt(8)
	s_waitcnt lgkmcnt(0)
	s_barrier
	s_setprio 1
	s_waitcnt lgkmcnt(0)
	v_mfma_f32_16x16x32_bf16 v[124:127], v[138:141], v[182:185], v[124:127]
	v_mfma_f32_16x16x32_bf16 v[120:123], v[150:153], v[182:185], v[120:123]
	v_mfma_f32_16x16x32_bf16 v[116:119], v[138:141], v[190:193], v[116:119]
	v_mfma_f32_16x16x32_bf16 v[112:115], v[150:153], v[190:193], v[112:115]
	v_mfma_f32_16x16x32_bf16 v[104:107], v[138:141], v[198:201], v[104:107]
	v_mfma_f32_16x16x32_bf16 v[96:99], v[150:153], v[198:201], v[96:99]
	v_mfma_f32_16x16x32_bf16 v[88:91], v[138:141], v[206:209], v[88:91]
	v_mfma_f32_16x16x32_bf16 v[80:83], v[150:153], v[206:209], v[80:83]
	v_mfma_f32_16x16x32_bf16 v[124:127], v[142:145], v[186:189], v[124:127]
	v_mfma_f32_16x16x32_bf16 v[120:123], v[154:157], v[186:189], v[120:123]
	v_mfma_f32_16x16x32_bf16 v[116:119], v[142:145], v[194:197], v[116:119]
	v_mfma_f32_16x16x32_bf16 v[112:115], v[154:157], v[194:197], v[112:115]
	v_mfma_f32_16x16x32_bf16 v[104:107], v[142:145], v[202:205], v[104:107]
	v_mfma_f32_16x16x32_bf16 v[96:99], v[154:157], v[202:205], v[96:99]
	v_mfma_f32_16x16x32_bf16 v[88:91], v[142:145], v[210:213], v[88:91]
	v_mfma_f32_16x16x32_bf16 v[80:83], v[154:157], v[210:213], v[80:83]
	v_mfma_f32_16x16x32_bf16 v[108:111], v[158:161], v[182:185], v[108:111]
	v_mfma_f32_16x16x32_bf16 v[100:103], v[166:169], v[182:185], v[100:103]
	v_mfma_f32_16x16x32_bf16 v[92:95], v[158:161], v[190:193], v[92:95]
	v_mfma_f32_16x16x32_bf16 v[84:87], v[166:169], v[190:193], v[84:87]
	v_mfma_f32_16x16x32_bf16 v[76:79], v[158:161], v[198:201], v[76:79]
	v_mfma_f32_16x16x32_bf16 v[72:75], v[166:169], v[198:201], v[72:75]
	v_mfma_f32_16x16x32_bf16 v[68:71], v[158:161], v[206:209], v[68:71]
	v_mfma_f32_16x16x32_bf16 v[64:67], v[166:169], v[206:209], v[64:67]
	v_mfma_f32_16x16x32_bf16 v[108:111], v[162:165], v[186:189], v[108:111]
	v_mfma_f32_16x16x32_bf16 v[100:103], v[170:173], v[186:189], v[100:103]
	v_mfma_f32_16x16x32_bf16 v[92:95], v[162:165], v[194:197], v[92:95]
	v_mfma_f32_16x16x32_bf16 v[84:87], v[170:173], v[194:197], v[84:87]
	v_mfma_f32_16x16x32_bf16 v[76:79], v[162:165], v[202:205], v[76:79]
	v_mfma_f32_16x16x32_bf16 v[72:75], v[170:173], v[202:205], v[72:75]
	v_mfma_f32_16x16x32_bf16 v[68:71], v[162:165], v[210:213], v[68:71]
	v_mfma_f32_16x16x32_bf16 v[64:67], v[170:173], v[210:213], v[64:67]
	s_setprio 0
	s_barrier
; #define PG8_STAGE(bufoff, gbase, voff) do { _Pragma("unroll") for (int _i = 0; _i < 2; ++_i) \
;         __builtin_amdgcn_global_load_lds((const unsigned*)((const char*)(gbase) + (voff)[_i]), (PG8_LAS unsigned*)(lds + (bufoff) + ldsw + _i * 8192), 16, 0, 0); } while (0)
; #define PG8_LDA(dst, b, h) do { _Pragma("unroll") for (int m = 0; m < 4; ++m) _Pragma("unroll") for (int k = 0; k < 2; ++k) dst[m][k] = *(const PG8_LAS bf16x8*)(lds + PG8_SA(b, h) + aoff + m * 2048 + k * 1024); } while (0)
; #define PG8_MMA(ai, bj, At, Bt) do { __builtin_amdgcn_s_setprio(1); _Pragma("unroll") for (int m = 0; m < 4; ++m) _Pragma("unroll") for (int n = 0; n < 2; ++n) _Pragma("unroll") for (int k = 0; k < 2; ++k) \
;         acc[ai][bj][m][n] = __builtin_amdgcn_mfma_f32_16x16x32_bf16(Bt[n][k], At[m][k], acc[ai][bj][m][n], 0, 0, 0); __builtin_amdgcn_s_setprio(0); } while (0)
; #define PG8_WAIT_V(n) asm volatile("s_waitcnt vmcnt(" #n ")" ::: "memory")
; #define PG8_WAIT_L(n) asm volatile("s_waitcnt lgkmcnt(" #n ")" ::: "memory")
; #define PG8_BAR __builtin_amdgcn_s_barrier()
; #define PG8_SCHED __builtin_amdgcn_sched_barrier(0)
; template <class Epi, class Sched, bool ALIGN_EPI = false, bool SP2 = false>
; __device__ __forceinline__ void gemm_phase(PG8_LAS unsigned char* lds, const Gemm g, const Sched& S, const Epi& E) {
;     ...
;             PG8_LDA(At, 1, 1); PG8_STAGE(PG8_SB(1, 0), b3, voffB); PG8_STAGE(PG8_SB(1, 1), b3 + hstep, voffB); PG8_STAGE(PG8_SA(1, 0), a3, voffA);
;             PG8_WAIT_V(8); PG8_WAIT_L(0); PG8_BAR; PG8_MMA(1, 0, At, B0); PG8_MMA(1, 1, At, B1); PG8_BAR; PG8_SCHED;
	s_add_i32 s28, s28, s24
	v_lshl_add_u64 v[174:175], v[174:175], 0, s[44:45]
	s_mov_b32 m0, s28
	ds_read_b128 v[182:185], v149 offset:49152
	ds_read_b128 v[186:189], v149 offset:50176
	ds_read_b128 v[190:193], v149 offset:51200
	ds_read_b128 v[194:197], v149 offset:52224
	ds_read_b128 v[198:201], v149 offset:53248
	ds_read_b128 v[202:205], v149 offset:54272
	ds_read_b128 v[206:209], v149 offset:55296
	ds_read_b128 v[210:213], v149 offset:56320
	global_load_lds_dwordx4 v[174:175], off
	v_lshl_add_u64 v[174:175], v[214:215], 0, s[44:45]
	s_add_i32 m0, s28, 0x2000
	s_add_i32 s28, s48, s24
	global_load_lds_dwordx4 v[174:175], off
	v_lshl_add_u64 v[174:175], v[216:217], 0, s[44:45]
	s_mov_b32 m0, s28
	s_nop 0
	global_load_lds_dwordx4 v[174:175], off
	v_lshl_add_u64 v[174:175], v[218:219], 0, s[44:45]
	s_add_i32 m0, s28, 0x2000
	s_nop 0
	global_load_lds_dwordx4 v[174:175], off
	v_lshl_add_u64 v[174:175], v[220:221], 0, s[44:45]
	s_mov_b32 m0, s73
	s_nop 0
	global_load_lds_dwordx4 v[174:175], off
	v_lshl_add_u64 v[174:175], v[222:223], 0, s[44:45]
	s_mov_b32 m0, s74
	s_nop 0
	global_load_lds_dwordx4 v[174:175], off
	s_waitcnt vmcnt(8)
	s_waitcnt lgkmcnt(0)
	s_barrier
	s_setprio 1
	s_waitcnt lgkmcnt(0)
	v_mfma_f32_16x16x32_bf16 v[60:63], v[138:141], v[182:185], v[60:63]
	v_mfma_f32_16x16x32_bf16 v[56:59], v[150:153], v[182:185], v[56:59]
	v_mfma_f32_16x16x32_bf16 v[52:55], v[138:141], v[190:193], v[52:55]
	v_mfma_f32_16x16x32_bf16 v[48:51], v[150:153], v[190:193], v[48:51]
	v_mfma_f32_16x16x32_bf16 v[40:43], v[138:141], v[198:201], v[40:43]
	v_mfma_f32_16x16x32_bf16 v[32:35], v[150:153], v[198:201], v[32:35]
	v_mfma_f32_16x16x32_bf16 v[24:27], v[138:141], v[206:209], v[24:27]
	v_mfma_f32_16x16x32_bf16 v[16:19], v[150:153], v[206:209], v[16:19]
	v_mfma_f32_16x16x32_bf16 v[60:63], v[142:145], v[186:189], v[60:63]
	v_mfma_f32_16x16x32_bf16 v[56:59], v[154:157], v[186:189], v[56:59]
	v_mfma_f32_16x16x32_bf16 v[52:55], v[142:145], v[194:197], v[52:55]
	v_mfma_f32_16x16x32_bf16 v[48:51], v[154:157], v[194:197], v[48:51]
	v_mfma_f32_16x16x32_bf16 v[40:43], v[142:145], v[202:205], v[40:43]
	v_mfma_f32_16x16x32_bf16 v[32:35], v[154:157], v[202:205], v[32:35]
	v_mfma_f32_16x16x32_bf16 v[24:27], v[142:145], v[210:213], v[24:27]
	v_mfma_f32_16x16x32_bf16 v[16:19], v[154:157], v[210:213], v[16:19]
	v_mfma_f32_16x16x32_bf16 v[44:47], v[158:161], v[182:185], v[44:47]
	v_mfma_f32_16x16x32_bf16 v[36:39], v[166:169], v[182:185], v[36:39]
	v_mfma_f32_16x16x32_bf16 v[28:31], v[158:161], v[190:193], v[28:31]
	v_mfma_f32_16x16x32_bf16 v[20:23], v[166:169], v[190:193], v[20:23]
	v_mfma_f32_16x16x32_bf16 v[12:15], v[158:161], v[198:201], v[12:15]
	v_mfma_f32_16x16x32_bf16 v[8:11], v[166:169], v[198:201], v[8:11]
	v_mfma_f32_16x16x32_bf16 v[4:7], v[158:161], v[206:209], v[4:7]
	v_mfma_f32_16x16x32_bf16 v[0:3], v[166:169], v[206:209], v[0:3]
	v_mfma_f32_16x16x32_bf16 v[44:47], v[162:165], v[186:189], v[44:47]
	v_mfma_f32_16x16x32_bf16 v[36:39], v[170:173], v[186:189], v[36:39]
	s_add_u32 s64, s64, 0x100
	v_mfma_f32_16x16x32_bf16 v[28:31], v[162:165], v[194:197], v[28:31]
	s_addc_u32 s65, s65, 0
	v_mfma_f32_16x16x32_bf16 v[20:23], v[170:173], v[194:197], v[20:23]
	s_add_u32 s79, s79, 0x100
	v_mfma_f32_16x16x32_bf16 v[12:15], v[162:165], v[202:205], v[12:15]
	s_addc_u32 s80, s80, 0
	v_mfma_f32_16x16x32_bf16 v[8:11], v[170:173], v[202:205], v[8:11]
	s_cmp_ge_i32 s81, s69
	v_mfma_f32_16x16x32_bf16 v[4:7], v[162:165], v[210:213], v[4:7]
	s_mov_b32 s66, s81
	v_mfma_f32_16x16x32_bf16 v[0:3], v[170:173], v[210:213], v[0:3]
	s_setprio 0
	s_barrier
	s_cbranch_scc0 .LBB0_406
;     __device__ __forceinline__ void operator()(const f32x4 (&acc)[2][2][4][2], const Unit& u, int wr, int wc, int fr, int fq) const {
;     ...
;                 for (int bj = 0; bj < 2; ++bj) { f32x4 v0 = acc[ai][bj][m][0], v1 = acc[ai][bj][m][1];
;                     if (ACT == 1) {
; #pragma unroll
;                         for (int j = 0; j < 4; ++j) { float a = fmaxf(v0[j], 0.f), b = fmaxf(v1[j], 0.f); v0[j] = a * a; v1[j] = b * b; } }
;                     v0 = v0 * scale; v1 = v1 * scale;
	s_brev_b32 s28, 60
	v_readlane_b32 s80, v254, 45
	v_pk_mul_f32 v[126:127], v[126:127], s[28:29] op_sel_hi:[1,0]
	v_pk_mul_f32 v[124:125], v[124:125], s[28:29] op_sel_hi:[1,0]
	v_pk_mul_f32 v[122:123], v[122:123], s[28:29] op_sel_hi:[1,0]
	v_pk_mul_f32 v[120:121], v[120:121], s[28:29] op_sel_hi:[1,0]
	v_pk_mul_f32 v[138:139], v[110:111], s[28:29] op_sel_hi:[1,0]
	v_pk_mul_f32 v[140:141], v[108:109], s[28:29] op_sel_hi:[1,0]
	v_pk_mul_f32 v[142:143], v[102:103], s[28:29] op_sel_hi:[1,0]
	v_pk_mul_f32 v[144:145], v[100:101], s[28:29] op_sel_hi:[1,0]
	v_pk_mul_f32 v[100:101], v[118:119], s[28:29] op_sel_hi:[1,0]
	v_pk_mul_f32 v[102:103], v[116:117], s[28:29] op_sel_hi:[1,0]
	v_pk_mul_f32 v[108:109], v[114:115], s[28:29] op_sel_hi:[1,0]
	v_pk_mul_f32 v[110:111], v[112:113], s[28:29] op_sel_hi:[1,0]
	v_pk_mul_f32 v[112:113], v[94:95], s[28:29] op_sel_hi:[1,0]
	v_pk_mul_f32 v[114:115], v[92:93], s[28:29] op_sel_hi:[1,0]
	v_pk_mul_f32 v[116:117], v[86:87], s[28:29] op_sel_hi:[1,0]
	v_pk_mul_f32 v[118:119], v[84:85], s[28:29] op_sel_hi:[1,0]
	v_pk_mul_f32 v[84:85], v[106:107], s[28:29] op_sel_hi:[1,0]
	v_pk_mul_f32 v[86:87], v[104:105], s[28:29] op_sel_hi:[1,0]
	v_pk_mul_f32 v[92:93], v[98:99], s[28:29] op_sel_hi:[1,0]
	v_pk_mul_f32 v[94:95], v[96:97], s[28:29] op_sel_hi:[1,0]
	v_pk_mul_f32 v[96:97], v[78:79], s[28:29] op_sel_hi:[1,0]
	v_pk_mul_f32 v[98:99], v[76:77], s[28:29] op_sel_hi:[1,0]
	v_pk_mul_f32 v[104:105], v[74:75], s[28:29] op_sel_hi:[1,0]
	v_pk_mul_f32 v[106:107], v[72:73], s[28:29] op_sel_hi:[1,0]
	v_pk_mul_f32 v[72:73], v[90:91], s[28:29] op_sel_hi:[1,0]
	v_pk_mul_f32 v[74:75], v[88:89], s[28:29] op_sel_hi:[1,0]
	v_pk_mul_f32 v[76:77], v[82:83], s[28:29] op_sel_hi:[1,0]
	v_pk_mul_f32 v[78:79], v[80:81], s[28:29] op_sel_hi:[1,0]
	v_pk_mul_f32 v[70:71], v[70:71], s[28:29] op_sel_hi:[1,0]
	v_pk_mul_f32 v[68:69], v[68:69], s[28:29] op_sel_hi:[1,0]
	v_pk_mul_f32 v[66:67], v[66:67], s[28:29] op_sel_hi:[1,0]
	v_pk_mul_f32 v[64:65], v[64:65], s[28:29] op_sel_hi:[1,0]
	v_pk_mul_f32 v[62:63], v[62:63], s[28:29] op_sel_hi:[1,0]
	v_pk_mul_f32 v[60:61], v[60:61], s[28:29] op_sel_hi:[1,0]
	v_pk_mul_f32 v[58:59], v[58:59], s[28:29] op_sel_hi:[1,0]
	v_pk_mul_f32 v[56:57], v[56:57], s[28:29] op_sel_hi:[1,0]
	v_pk_mul_f32 v[80:81], v[46:47], s[28:29] op_sel_hi:[1,0]
	v_pk_mul_f32 v[82:83], v[44:45], s[28:29] op_sel_hi:[1,0]
	v_pk_mul_f32 v[88:89], v[38:39], s[28:29] op_sel_hi:[1,0]
	v_pk_mul_f32 v[90:91], v[36:37], s[28:29] op_sel_hi:[1,0]
	v_pk_mul_f32 v[36:37], v[54:55], s[28:29] op_sel_hi:[1,0]
	v_pk_mul_f32 v[38:39], v[52:53], s[28:29] op_sel_hi:[1,0]
	v_pk_mul_f32 v[44:45], v[50:51], s[28:29] op_sel_hi:[1,0]
	v_pk_mul_f32 v[46:47], v[48:49], s[28:29] op_sel_hi:[1,0]
	v_pk_mul_f32 v[48:49], v[30:31], s[28:29] op_sel_hi:[1,0]
	v_pk_mul_f32 v[50:51], v[28:29], s[28:29] op_sel_hi:[1,0]
	v_pk_mul_f32 v[52:53], v[22:23], s[28:29] op_sel_hi:[1,0]
	v_pk_mul_f32 v[54:55], v[20:21], s[28:29] op_sel_hi:[1,0]
	v_pk_mul_f32 v[20:21], v[42:43], s[28:29] op_sel_hi:[1,0]
	v_pk_mul_f32 v[22:23], v[40:41], s[28:29] op_sel_hi:[1,0]
	v_pk_mul_f32 v[28:29], v[34:35], s[28:29] op_sel_hi:[1,0]
	v_pk_mul_f32 v[30:31], v[32:33], s[28:29] op_sel_hi:[1,0]
	v_pk_mul_f32 v[32:33], v[14:15], s[28:29] op_sel_hi:[1,0]
	v_pk_mul_f32 v[34:35], v[12:13], s[28:29] op_sel_hi:[1,0]
	v_pk_mul_f32 v[40:41], v[10:11], s[28:29] op_sel_hi:[1,0]
	v_pk_mul_f32 v[42:43], v[8:9], s[28:29] op_sel_hi:[1,0]
	v_pk_mul_f32 v[8:9], v[26:27], s[28:29] op_sel_hi:[1,0]
	v_pk_mul_f32 v[10:11], v[24:25], s[28:29] op_sel_hi:[1,0]
	v_pk_mul_f32 v[12:13], v[18:19], s[28:29] op_sel_hi:[1,0]
	v_pk_mul_f32 v[14:15], v[16:17], s[28:29] op_sel_hi:[1,0]
	v_pk_mul_f32 v[6:7], v[6:7], s[28:29] op_sel_hi:[1,0]
	v_pk_mul_f32 v[4:5], v[4:5], s[28:29] op_sel_hi:[1,0]
	v_pk_mul_f32 v[2:3], v[2:3], s[28:29] op_sel_hi:[1,0]
	v_pk_mul_f32 v[0:1], v[0:1], s[28:29] op_sel_hi:[1,0]
	v_readlane_b32 s81, v254, 46
	v_readlane_b32 s82, v254, 47
	v_readlane_b32 s83, v254, 48
	v_readlane_b32 s84, v254, 49
	v_readlane_b32 s85, v254, 50
	v_readlane_b32 s86, v254, 51
	v_readlane_b32 s87, v254, 52
	v_readlane_b32 s88, v254, 53
	v_readlane_b32 s89, v254, 54
	v_readlane_b32 s92, v254, 57
	v_readlane_b32 s93, v254, 58
	v_readlane_b32 s94, v254, 59
	v_readlane_b32 s95, v254, 60
	v_readlane_b32 s90, v254, 55
	v_readlane_b32 s91, v254, 56

; #define PG8_STAGE(bufoff, gbase, voff) do { _Pragma("unroll") for (int _i = 0; _i < 2; ++_i) \
;         __builtin_amdgcn_global_load_lds((const unsigned*)((const char*)(gbase) + (voff)[_i]), (PG8_LAS unsigned*)(lds + (bufoff) + ldsw + _i * 8192), 16, 0, 0); } while (0)
; #define PG8_LDA(dst, b, h) do { _Pragma("unroll") for (int m = 0; m < 4; ++m) _Pragma("unroll") for (int k = 0; k < 2; ++k) dst[m][k] = *(const PG8_LAS bf16x8*)(lds + PG8_SA(b, h) + aoff + m * 2048 + k * 1024); } while (0)
; #define PG8_LDB(dst, b, h) do { _Pragma("unroll") for (int n = 0; n < 2; ++n) _Pragma("unroll") for (int k = 0; k < 2; ++k) dst[n][k] = *(const PG8_LAS bf16x8*)(lds + PG8_SB(b, h) + boff + n * 2048 + k * 1024); } while (0)
; #define PG8_MMA(ai, bj, At, Bt) do { __builtin_amdgcn_s_setprio(1); _Pragma("unroll") for (int m = 0; m < 4; ++m) _Pragma("unroll") for (int n = 0; n < 2; ++n) _Pragma("unroll") for (int k = 0; k < 2; ++k) \
;         acc[ai][bj][m][n] = __builtin_amdgcn_mfma_f32_16x16x32_bf16(Bt[n][k], At[m][k], acc[ai][bj][m][n], 0, 0, 0); __builtin_amdgcn_s_setprio(0); } while (0)
; #define PG8_WAIT_V(n) asm volatile("s_waitcnt vmcnt(" #n ")" ::: "memory")
; #define PG8_WAIT_L(n) asm volatile("s_waitcnt lgkmcnt(" #n ")" ::: "memory")
; #define PG8_BAR __builtin_amdgcn_s_barrier()
; #define PG8_SCHED __builtin_amdgcn_sched_barrier(0)
; template <class Epi, class Sched, bool ALIGN_EPI = false, bool SP2 = false>
; __device__ __forceinline__ void gemm_phase(PG8_LAS unsigned char* lds, const Gemm g, const Sched& S, const Epi& E) {
;     ...
;             const bool last = (t == nt - 2);
;             const char* a1 = cA + (size_t)(t + 1) * kstep;
;             const char* a2 = last ? nA : cA + (size_t)(t + 2) * kstep; const char* b2 = last ? nB : cB + (size_t)(t + 2) * kstep;
;             const char* a3 = a2 + kstep; const char* b3 = b2 + kstep;
;             if (last && has_next) S.a_ready(nxt);
;             if constexpr (SP2) {
;             PG8_LDB(B0, 0, 0); PG8_LDB(B1, 0, 1); PG8_SCHED; PG8_LDA(At, 0, 0); PG8_STAGE(PG8_SA(1, 1), a1 + hstep, voffA);
;             PG8_WAIT_V(8); PG8_WAIT_L(0); PG8_BAR; PG8_MMA(0, 0, At, B0); PG8_MMA(0, 1, At, B1); PG8_BAR; PG8_SCHED;
;             PG8_LDA(At, 0, 1); PG8_STAGE(PG8_SB(0, 0), b2, voffB); PG8_STAGE(PG8_SB(0, 1), b2 + hstep, voffB); PG8_STAGE(PG8_SA(0, 0), a2, voffA);
.LBB0_570:
	s_add_u32 s4, s40, 0xfffc0080
	s_addc_u32 s5, s41, -1
	s_add_i32 s28, 0, 0x10000
	s_cmp_eq_u32 s72, 12
	s_cselect_b32 s65, s18, s5
	s_cselect_b32 s64, s19, s4
	v_add_u32_e32 v138, s28, v142
	s_cselect_b32 s5, s13, s71
	s_cselect_b32 s4, s27, s70
	s_add_i32 s48, 0, 0x14000
	ds_read_b128 v[144:147], v138
	ds_read_b128 v[148:151], v138 offset:1024
	ds_read_b128 v[152:155], v138 offset:2048
	ds_read_b128 v[156:159], v138 offset:3072
	v_add_u32_e32 v138, s48, v142
	ds_read_b128 v[160:163], v138
	ds_read_b128 v[164:167], v138 offset:1024
	ds_read_b128 v[168:171], v138 offset:2048
	ds_read_b128 v[172:175], v138 offset:3072
	v_lshl_add_u64 v[138:139], s[40:41], 0, v[134:135]
	s_add_i32 m0, s25, 0xc000
	ds_read_b128 v[182:185], v143
	ds_read_b128 v[186:189], v143 offset:1024
	ds_read_b128 v[190:193], v143 offset:2048
	ds_read_b128 v[194:197], v143 offset:3072
	ds_read_b128 v[198:201], v143 offset:4096
	ds_read_b128 v[202:205], v143 offset:5120
	ds_read_b128 v[206:209], v143 offset:6144
	ds_read_b128 v[210:213], v143 offset:7168
	global_load_lds_dwordx4 v[138:139], off
	v_lshl_add_u64 v[138:139], s[40:41], 0, v[136:137]
	s_add_i32 m0, s25, 0xe000
	s_nop 0
	global_load_lds_dwordx4 v[138:139], off
	s_waitcnt vmcnt(8)
	s_waitcnt lgkmcnt(0)
	s_barrier
	s_setprio 1
	s_waitcnt lgkmcnt(0)
	v_mfma_f32_16x16x32_bf16 v[124:127], v[144:147], v[182:185], v[124:127]
	v_mfma_f32_16x16x32_bf16 v[120:123], v[152:155], v[182:185], v[120:123]
	v_mfma_f32_16x16x32_bf16 v[116:119], v[144:147], v[190:193], v[116:119]
	v_mfma_f32_16x16x32_bf16 v[108:111], v[152:155], v[190:193], v[108:111]
	v_mfma_f32_16x16x32_bf16 v[100:103], v[144:147], v[198:201], v[100:103]
	v_mfma_f32_16x16x32_bf16 v[92:95], v[152:155], v[198:201], v[92:95]
	v_mfma_f32_16x16x32_bf16 v[84:87], v[144:147], v[206:209], v[84:87]
	v_mfma_f32_16x16x32_bf16 v[76:79], v[152:155], v[206:209], v[76:79]
	v_mfma_f32_16x16x32_bf16 v[124:127], v[148:151], v[186:189], v[124:127]
	v_mfma_f32_16x16x32_bf16 v[120:123], v[156:159], v[186:189], v[120:123]
	v_mfma_f32_16x16x32_bf16 v[116:119], v[148:151], v[194:197], v[116:119]
	v_mfma_f32_16x16x32_bf16 v[108:111], v[156:159], v[194:197], v[108:111]
	v_mfma_f32_16x16x32_bf16 v[100:103], v[148:151], v[202:205], v[100:103]
	v_mfma_f32_16x16x32_bf16 v[92:95], v[156:159], v[202:205], v[92:95]
	v_mfma_f32_16x16x32_bf16 v[84:87], v[148:151], v[210:213], v[84:87]
	v_mfma_f32_16x16x32_bf16 v[76:79], v[156:159], v[210:213], v[76:79]
	v_mfma_f32_16x16x32_bf16 v[112:115], v[160:163], v[182:185], v[112:115]
	v_mfma_f32_16x16x32_bf16 v[104:107], v[168:171], v[182:185], v[104:107]
	v_mfma_f32_16x16x32_bf16 v[96:99], v[160:163], v[190:193], v[96:99]
	v_mfma_f32_16x16x32_bf16 v[88:91], v[168:171], v[190:193], v[88:91]
	v_mfma_f32_16x16x32_bf16 v[80:83], v[160:163], v[198:201], v[80:83]
	v_mfma_f32_16x16x32_bf16 v[72:75], v[168:171], v[198:201], v[72:75]
	v_mfma_f32_16x16x32_bf16 v[68:71], v[160:163], v[206:209], v[68:71]
	v_mfma_f32_16x16x32_bf16 v[64:67], v[168:171], v[206:209], v[64:67]
	v_mfma_f32_16x16x32_bf16 v[112:115], v[164:167], v[186:189], v[112:115]
	v_mfma_f32_16x16x32_bf16 v[104:107], v[172:175], v[186:189], v[104:107]
	v_mfma_f32_16x16x32_bf16 v[96:99], v[164:167], v[194:197], v[96:99]
	v_mfma_f32_16x16x32_bf16 v[88:91], v[172:175], v[194:197], v[88:91]
	v_mfma_f32_16x16x32_bf16 v[80:83], v[164:167], v[202:205], v[80:83]
	v_mfma_f32_16x16x32_bf16 v[72:75], v[172:175], v[202:205], v[72:75]
	v_mfma_f32_16x16x32_bf16 v[68:71], v[164:167], v[210:213], v[68:71]
	v_mfma_f32_16x16x32_bf16 v[64:67], v[172:175], v[210:213], v[64:67]
	s_setprio 0
	s_barrier
	s_add_i32 s28, s28, s24
	v_lshl_add_u64 v[138:139], s[4:5], 0, v[176:177]
	s_mov_b32 m0, s28
	ds_read_b128 v[182:185], v143 offset:16384
	ds_read_b128 v[186:189], v143 offset:17408
	ds_read_b128 v[190:193], v143 offset:18432
	ds_read_b128 v[194:197], v143 offset:19456
	ds_read_b128 v[198:201], v143 offset:20480
	ds_read_b128 v[202:205], v143 offset:21504
	ds_read_b128 v[206:209], v143 offset:22528
	ds_read_b128 v[210:213], v143 offset:23552
	global_load_lds_dwordx4 v[138:139], off
	s_add_i32 m0, s28, 0x2000
	s_add_u32 s38, s4, 0x40000
	v_lshl_add_u64 v[214:215], s[4:5], 0, v[128:129]
	s_addc_u32 s39, s5, 0
	s_add_i32 s28, s48, s24
	global_load_lds_dwordx4 v[214:215], off
	v_lshl_add_u64 v[216:217], s[38:39], 0, v[176:177]
	s_mov_b32 m0, s28
	v_lshl_add_u64 v[218:219], s[64:65], 0, v[130:131]
	global_load_lds_dwordx4 v[216:217], off
	v_lshl_add_u64 v[216:217], s[38:39], 0, v[128:129]
	s_add_i32 m0, s28, 0x2000
	s_nop 0
	global_load_lds_dwordx4 v[216:217], off
	v_lshl_add_u64 v[216:217], s[64:65], 0, v[132:133]
	s_mov_b32 m0, s25
	s_nop 0
	global_load_lds_dwordx4 v[216:217], off
	s_mov_b32 m0, s30
	s_nop 0
	global_load_lds_dwordx4 v[218:219], off
	s_waitcnt vmcnt(8)
	s_waitcnt lgkmcnt(0)
	s_barrier
; #define PG8_STAGE(bufoff, gbase, voff) do { _Pragma("unroll") for (int _i = 0; _i < 2; ++_i) \
;         __builtin_amdgcn_global_load_lds((const unsigned*)((const char*)(gbase) + (voff)[_i]), (PG8_LAS unsigned*)(lds + (bufoff) + ldsw + _i * 8192), 16, 0, 0); } while (0)
; #define PG8_LDA(dst, b, h) do { _Pragma("unroll") for (int m = 0; m < 4; ++m) _Pragma("unroll") for (int k = 0; k < 2; ++k) dst[m][k] = *(const PG8_LAS bf16x8*)(lds + PG8_SA(b, h) + aoff + m * 2048 + k * 1024); } while (0)
; #define PG8_LDB(dst, b, h) do { _Pragma("unroll") for (int n = 0; n < 2; ++n) _Pragma("unroll") for (int k = 0; k < 2; ++k) dst[n][k] = *(const PG8_LAS bf16x8*)(lds + PG8_SB(b, h) + boff + n * 2048 + k * 1024); } while (0)
; #define PG8_MMA(ai, bj, At, Bt) do { __builtin_amdgcn_s_setprio(1); _Pragma("unroll") for (int m = 0; m < 4; ++m) _Pragma("unroll") for (int n = 0; n < 2; ++n) _Pragma("unroll") for (int k = 0; k < 2; ++k) \
;         acc[ai][bj][m][n] = __builtin_amdgcn_mfma_f32_16x16x32_bf16(Bt[n][k], At[m][k], acc[ai][bj][m][n], 0, 0, 0); __builtin_amdgcn_s_setprio(0); } while (0)
; #define PG8_WAIT_V(n) asm volatile("s_waitcnt vmcnt(" #n ")" ::: "memory")
; #define PG8_WAIT_L(n) asm volatile("s_waitcnt lgkmcnt(" #n ")" ::: "memory")
; #define PG8_BAR __builtin_amdgcn_s_barrier()
; #define PG8_SCHED __builtin_amdgcn_sched_barrier(0)
; template <class Epi, class Sched, bool ALIGN_EPI = false, bool SP2 = false>
; __device__ __forceinline__ void gemm_phase(PG8_LAS unsigned char* lds, const Gemm g, const Sched& S, const Epi& E) {
;     ...
;             PG8_WAIT_V(8); PG8_WAIT_L(0); PG8_BAR; PG8_MMA(1, 0, At, B0); PG8_MMA(1, 1, At, B1); PG8_BAR; PG8_SCHED;
;             PG8_LDB(B0, 1, 0); PG8_LDB(B1, 1, 1); PG8_SCHED; PG8_LDA(At, 1, 0); PG8_STAGE(PG8_SA(0, 1), a2 + hstep, voffA);
;             PG8_WAIT_V(8); PG8_WAIT_L(0); PG8_BAR; PG8_MMA(0, 0, At, B0); PG8_MMA(0, 1, At, B1); PG8_BAR; PG8_SCHED;
	s_setprio 1
	s_waitcnt lgkmcnt(0)
	v_mfma_f32_16x16x32_bf16 v[60:63], v[144:147], v[182:185], v[60:63]
	v_mfma_f32_16x16x32_bf16 v[56:59], v[152:155], v[182:185], v[56:59]
	v_mfma_f32_16x16x32_bf16 v[52:55], v[144:147], v[190:193], v[52:55]
	v_mfma_f32_16x16x32_bf16 v[44:47], v[152:155], v[190:193], v[44:47]
	v_mfma_f32_16x16x32_bf16 v[36:39], v[144:147], v[198:201], v[36:39]
	v_mfma_f32_16x16x32_bf16 v[28:31], v[152:155], v[198:201], v[28:31]
	v_mfma_f32_16x16x32_bf16 v[20:23], v[144:147], v[206:209], v[20:23]
	v_mfma_f32_16x16x32_bf16 v[12:15], v[152:155], v[206:209], v[12:15]
	v_mfma_f32_16x16x32_bf16 v[60:63], v[148:151], v[186:189], v[60:63]
	v_mfma_f32_16x16x32_bf16 v[56:59], v[156:159], v[186:189], v[56:59]
	v_mfma_f32_16x16x32_bf16 v[52:55], v[148:151], v[194:197], v[52:55]
	v_mfma_f32_16x16x32_bf16 v[44:47], v[156:159], v[194:197], v[44:47]
	v_mfma_f32_16x16x32_bf16 v[36:39], v[148:151], v[202:205], v[36:39]
	v_mfma_f32_16x16x32_bf16 v[28:31], v[156:159], v[202:205], v[28:31]
	v_mfma_f32_16x16x32_bf16 v[20:23], v[148:151], v[210:213], v[20:23]
	v_mfma_f32_16x16x32_bf16 v[12:15], v[156:159], v[210:213], v[12:15]
	v_mfma_f32_16x16x32_bf16 v[48:51], v[160:163], v[182:185], v[48:51]
	v_mfma_f32_16x16x32_bf16 v[40:43], v[168:171], v[182:185], v[40:43]
	v_mfma_f32_16x16x32_bf16 v[32:35], v[160:163], v[190:193], v[32:35]
	v_mfma_f32_16x16x32_bf16 v[24:27], v[168:171], v[190:193], v[24:27]
	v_mfma_f32_16x16x32_bf16 v[16:19], v[160:163], v[198:201], v[16:19]
	v_mfma_f32_16x16x32_bf16 v[8:11], v[168:171], v[198:201], v[8:11]
	v_mfma_f32_16x16x32_bf16 v[4:7], v[160:163], v[206:209], v[4:7]
	v_mfma_f32_16x16x32_bf16 v[0:3], v[168:171], v[206:209], v[0:3]
	v_mfma_f32_16x16x32_bf16 v[48:51], v[164:167], v[186:189], v[48:51]
	v_mfma_f32_16x16x32_bf16 v[40:43], v[172:175], v[186:189], v[40:43]
	v_mfma_f32_16x16x32_bf16 v[32:35], v[164:167], v[194:197], v[32:35]
	v_mfma_f32_16x16x32_bf16 v[24:27], v[172:175], v[194:197], v[24:27]
	v_mfma_f32_16x16x32_bf16 v[16:19], v[164:167], v[202:205], v[16:19]
	v_mfma_f32_16x16x32_bf16 v[8:11], v[172:175], v[202:205], v[8:11]
	v_mfma_f32_16x16x32_bf16 v[4:7], v[164:167], v[210:213], v[4:7]
	v_mfma_f32_16x16x32_bf16 v[0:3], v[172:175], v[210:213], v[0:3]
	s_setprio 0
	s_barrier
	s_add_i32 s28, 0, 0x18000
	s_add_i32 s48, 0, 0x1c000
	v_add_u32_e32 v156, s28, v142
	v_add_u32_e32 v172, s48, v142
	ds_read_b128 v[144:147], v156
	ds_read_b128 v[148:151], v156 offset:1024
	ds_read_b128 v[152:155], v156 offset:2048
	ds_read_b128 v[156:159], v156 offset:3072
	ds_read_b128 v[160:163], v172
	ds_read_b128 v[164:167], v172 offset:1024
	ds_read_b128 v[168:171], v172 offset:2048
	ds_read_b128 v[172:175], v172 offset:3072
	s_add_u32 s38, s64, 0x40000
	s_addc_u32 s39, s65, 0
	s_mov_b32 m0, s31
	v_lshl_add_u64 v[220:221], s[38:39], 0, v[132:133]
	ds_read_b128 v[182:185], v143 offset:32768
	ds_read_b128 v[186:189], v143 offset:33792
	ds_read_b128 v[190:193], v143 offset:34816
	ds_read_b128 v[194:197], v143 offset:35840
	ds_read_b128 v[198:201], v143 offset:36864
	ds_read_b128 v[202:205], v143 offset:37888
	ds_read_b128 v[206:209], v143 offset:38912
	ds_read_b128 v[210:213], v143 offset:39936
	global_load_lds_dwordx4 v[220:221], off
	v_lshl_add_u64 v[220:221], s[38:39], 0, v[130:131]
	s_mov_b32 m0, s42
	s_nop 0
	global_load_lds_dwordx4 v[220:221], off
	s_waitcnt vmcnt(8)
	s_waitcnt lgkmcnt(0)
	s_barrier
	s_setprio 1
	s_waitcnt lgkmcnt(0)
	v_mfma_f32_16x16x32_bf16 v[124:127], v[144:147], v[182:185], v[124:127]
	v_mfma_f32_16x16x32_bf16 v[120:123], v[152:155], v[182:185], v[120:123]
	v_mfma_f32_16x16x32_bf16 v[116:119], v[144:147], v[190:193], v[116:119]
	v_mfma_f32_16x16x32_bf16 v[108:111], v[152:155], v[190:193], v[108:111]
	v_mfma_f32_16x16x32_bf16 v[100:103], v[144:147], v[198:201], v[100:103]
	v_mfma_f32_16x16x32_bf16 v[92:95], v[152:155], v[198:201], v[92:95]
	v_mfma_f32_16x16x32_bf16 v[84:87], v[144:147], v[206:209], v[84:87]
	v_mfma_f32_16x16x32_bf16 v[76:79], v[152:155], v[206:209], v[76:79]
	v_mfma_f32_16x16x32_bf16 v[124:127], v[148:151], v[186:189], v[124:127]
	v_mfma_f32_16x16x32_bf16 v[120:123], v[156:159], v[186:189], v[120:123]
	v_mfma_f32_16x16x32_bf16 v[116:119], v[148:151], v[194:197], v[116:119]
	v_mfma_f32_16x16x32_bf16 v[108:111], v[156:159], v[194:197], v[108:111]
	v_mfma_f32_16x16x32_bf16 v[100:103], v[148:151], v[202:205], v[100:103]
	v_mfma_f32_16x16x32_bf16 v[92:95], v[156:159], v[202:205], v[92:95]
	v_mfma_f32_16x16x32_bf16 v[84:87], v[148:151], v[210:213], v[84:87]
	v_mfma_f32_16x16x32_bf16 v[76:79], v[156:159], v[210:213], v[76:79]
	v_mfma_f32_16x16x32_bf16 v[112:115], v[160:163], v[182:185], v[112:115]
	v_mfma_f32_16x16x32_bf16 v[104:107], v[168:171], v[182:185], v[104:107]
	v_mfma_f32_16x16x32_bf16 v[96:99], v[160:163], v[190:193], v[96:99]
	v_mfma_f32_16x16x32_bf16 v[88:91], v[168:171], v[190:193], v[88:91]
	v_mfma_f32_16x16x32_bf16 v[80:83], v[160:163], v[198:201], v[80:83]
	v_mfma_f32_16x16x32_bf16 v[72:75], v[168:171], v[198:201], v[72:75]
	v_mfma_f32_16x16x32_bf16 v[68:71], v[160:163], v[206:209], v[68:71]
	v_mfma_f32_16x16x32_bf16 v[64:67], v[168:171], v[206:209], v[64:67]
	v_mfma_f32_16x16x32_bf16 v[112:115], v[164:167], v[186:189], v[112:115]
	v_mfma_f32_16x16x32_bf16 v[104:107], v[172:175], v[186:189], v[104:107]
	v_mfma_f32_16x16x32_bf16 v[96:99], v[164:167], v[194:197], v[96:99]
	v_mfma_f32_16x16x32_bf16 v[88:91], v[172:175], v[194:197], v[88:91]
	v_mfma_f32_16x16x32_bf16 v[80:83], v[164:167], v[202:205], v[80:83]
	v_mfma_f32_16x16x32_bf16 v[72:75], v[172:175], v[202:205], v[72:75]
	v_mfma_f32_16x16x32_bf16 v[68:71], v[164:167], v[210:213], v[68:71]
	v_mfma_f32_16x16x32_bf16 v[64:67], v[172:175], v[210:213], v[64:67]
	s_setprio 0
	s_barrier
; #define PG8_STAGE(bufoff, gbase, voff) do { _Pragma("unroll") for (int _i = 0; _i < 2; ++_i) \
;         __builtin_amdgcn_global_load_lds((const unsigned*)((const char*)(gbase) + (voff)[_i]), (PG8_LAS unsigned*)(lds + (bufoff) + ldsw + _i * 8192), 16, 0, 0); } while (0)
; #define PG8_LDA(dst, b, h) do { _Pragma("unroll") for (int m = 0; m < 4; ++m) _Pragma("unroll") for (int k = 0; k < 2; ++k) dst[m][k] = *(const PG8_LAS bf16x8*)(lds + PG8_SA(b, h) + aoff + m * 2048 + k * 1024); } while (0)
; #define PG8_MMA(ai, bj, At, Bt) do { __builtin_amdgcn_s_setprio(1); _Pragma("unroll") for (int m = 0; m < 4; ++m) _Pragma("unroll") for (int n = 0; n < 2; ++n) _Pragma("unroll") for (int k = 0; k < 2; ++k) \
;         acc[ai][bj][m][n] = __builtin_amdgcn_mfma_f32_16x16x32_bf16(Bt[n][k], At[m][k], acc[ai][bj][m][n], 0, 0, 0); __builtin_amdgcn_s_setprio(0); } while (0)
; #define PG8_WAIT_V(n) asm volatile("s_waitcnt vmcnt(" #n ")" ::: "memory")
; #define PG8_WAIT_L(n) asm volatile("s_waitcnt lgkmcnt(" #n ")" ::: "memory")
; #define PG8_BAR __builtin_amdgcn_s_barrier()
; #define PG8_SCHED __builtin_amdgcn_sched_barrier(0)
; template <class Epi, class Sched, bool ALIGN_EPI = false, bool SP2 = false>
; __device__ __forceinline__ void gemm_phase(PG8_LAS unsigned char* lds, const Gemm g, const Sched& S, const Epi& E) {
;     ...
;             PG8_LDA(At, 1, 1); PG8_STAGE(PG8_SB(1, 0), b3, voffB); PG8_STAGE(PG8_SB(1, 1), b3 + hstep, voffB); PG8_STAGE(PG8_SA(1, 0), a3, voffA);
;             PG8_WAIT_V(8); PG8_WAIT_L(0); PG8_BAR; PG8_MMA(1, 0, At, B0); PG8_MMA(1, 1, At, B1); PG8_BAR; PG8_SCHED;
	s_add_i32 s28, s28, s24
	v_lshl_add_u64 v[138:139], v[138:139], 0, s[44:45]
	s_mov_b32 m0, s28
	ds_read_b128 v[182:185], v143 offset:49152
	ds_read_b128 v[186:189], v143 offset:50176
	ds_read_b128 v[190:193], v143 offset:51200
	ds_read_b128 v[194:197], v143 offset:52224
	ds_read_b128 v[198:201], v143 offset:53248
	ds_read_b128 v[202:205], v143 offset:54272
	ds_read_b128 v[206:209], v143 offset:55296
	ds_read_b128 v[210:213], v143 offset:56320
	global_load_lds_dwordx4 v[138:139], off
	s_add_i32 m0, s28, 0x2000
	s_add_u32 s4, s4, 0x40080
	v_lshl_add_u64 v[138:139], v[214:215], 0, s[44:45]
	s_addc_u32 s5, s5, 0
	s_add_i32 s28, s48, s24
	global_load_lds_dwordx4 v[138:139], off
	v_lshl_add_u64 v[138:139], s[4:5], 0, v[176:177]
	s_mov_b32 m0, s28
	s_nop 0
	global_load_lds_dwordx4 v[138:139], off
	v_lshl_add_u64 v[138:139], s[4:5], 0, v[128:129]
	s_add_i32 m0, s28, 0x2000
	s_nop 0
	global_load_lds_dwordx4 v[138:139], off
	v_lshl_add_u64 v[138:139], v[216:217], 0, s[44:45]
	s_mov_b32 m0, s63
	s_nop 0
	global_load_lds_dwordx4 v[138:139], off
	v_lshl_add_u64 v[138:139], v[218:219], 0, s[44:45]
	s_mov_b32 m0, s66
	s_nop 0
	global_load_lds_dwordx4 v[138:139], off
	s_waitcnt vmcnt(8)
	s_waitcnt lgkmcnt(0)
	s_barrier
	s_setprio 1
	s_waitcnt lgkmcnt(0)
	v_mfma_f32_16x16x32_bf16 v[60:63], v[144:147], v[182:185], v[60:63]
	v_mfma_f32_16x16x32_bf16 v[56:59], v[152:155], v[182:185], v[56:59]
	v_mfma_f32_16x16x32_bf16 v[52:55], v[144:147], v[190:193], v[52:55]
	v_mfma_f32_16x16x32_bf16 v[44:47], v[152:155], v[190:193], v[44:47]
	v_mfma_f32_16x16x32_bf16 v[36:39], v[144:147], v[198:201], v[36:39]
	v_mfma_f32_16x16x32_bf16 v[28:31], v[152:155], v[198:201], v[28:31]
	v_mfma_f32_16x16x32_bf16 v[20:23], v[144:147], v[206:209], v[20:23]
	v_mfma_f32_16x16x32_bf16 v[12:15], v[152:155], v[206:209], v[12:15]
	v_mfma_f32_16x16x32_bf16 v[60:63], v[148:151], v[186:189], v[60:63]
	v_mfma_f32_16x16x32_bf16 v[56:59], v[156:159], v[186:189], v[56:59]
	v_mfma_f32_16x16x32_bf16 v[52:55], v[148:151], v[194:197], v[52:55]
	v_mfma_f32_16x16x32_bf16 v[44:47], v[156:159], v[194:197], v[44:47]
	v_mfma_f32_16x16x32_bf16 v[36:39], v[148:151], v[202:205], v[36:39]
	v_mfma_f32_16x16x32_bf16 v[28:31], v[156:159], v[202:205], v[28:31]
	v_mfma_f32_16x16x32_bf16 v[20:23], v[148:151], v[210:213], v[20:23]
	v_mfma_f32_16x16x32_bf16 v[12:15], v[156:159], v[210:213], v[12:15]
	v_mfma_f32_16x16x32_bf16 v[48:51], v[160:163], v[182:185], v[48:51]
	v_mfma_f32_16x16x32_bf16 v[40:43], v[168:171], v[182:185], v[40:43]
	v_mfma_f32_16x16x32_bf16 v[32:35], v[160:163], v[190:193], v[32:35]
	v_mfma_f32_16x16x32_bf16 v[24:27], v[168:171], v[190:193], v[24:27]
	v_mfma_f32_16x16x32_bf16 v[16:19], v[160:163], v[198:201], v[16:19]
	v_mfma_f32_16x16x32_bf16 v[8:11], v[168:171], v[198:201], v[8:11]
	v_mfma_f32_16x16x32_bf16 v[4:7], v[160:163], v[206:209], v[4:7]
	v_mfma_f32_16x16x32_bf16 v[0:3], v[168:171], v[206:209], v[0:3]
	v_mfma_f32_16x16x32_bf16 v[48:51], v[164:167], v[186:189], v[48:51]
	v_mfma_f32_16x16x32_bf16 v[40:43], v[172:175], v[186:189], v[40:43]
	s_add_i32 s72, s72, 2
	v_mfma_f32_16x16x32_bf16 v[32:35], v[164:167], v[194:197], v[32:35]
	s_add_u32 s40, s40, 0x100
	v_mfma_f32_16x16x32_bf16 v[24:27], v[172:175], v[194:197], v[24:27]
	s_addc_u32 s41, s41, 0
	v_mfma_f32_16x16x32_bf16 v[16:19], v[164:167], v[202:205], v[16:19]
	s_add_u32 s70, s70, 0x100
	v_mfma_f32_16x16x32_bf16 v[8:11], v[172:175], v[202:205], v[8:11]
	s_addc_u32 s71, s71, 0
	v_mfma_f32_16x16x32_bf16 v[4:7], v[164:167], v[210:213], v[4:7]
	s_cmp_gt_u32 s72, 13
	v_mfma_f32_16x16x32_bf16 v[0:3], v[172:175], v[210:213], v[0:3]
	s_setprio 0
	s_barrier
	s_cbranch_scc0 .LBB0_570

; #define PG8_STAGE(bufoff, gbase, voff) do { _Pragma("unroll") for (int _i = 0; _i < 2; ++_i) \
;         __builtin_amdgcn_global_load_lds((const unsigned*)((const char*)(gbase) + (voff)[_i]), (PG8_LAS unsigned*)(lds + (bufoff) + ldsw + _i * 8192), 16, 0, 0); } while (0)
; #define PG8_LDA(dst, b, h) do { _Pragma("unroll") for (int m = 0; m < 4; ++m) _Pragma("unroll") for (int k = 0; k < 2; ++k) dst[m][k] = *(const PG8_LAS bf16x8*)(lds + PG8_SA(b, h) + aoff + m * 2048 + k * 1024); } while (0)
; #define PG8_LDB(dst, b, h) do { _Pragma("unroll") for (int n = 0; n < 2; ++n) _Pragma("unroll") for (int k = 0; k < 2; ++k) dst[n][k] = *(const PG8_LAS bf16x8*)(lds + PG8_SB(b, h) + boff + n * 2048 + k * 1024); } while (0)
; #define PG8_MMA(ai, bj, At, Bt) do { __builtin_amdgcn_s_setprio(1); _Pragma("unroll") for (int m = 0; m < 4; ++m) _Pragma("unroll") for (int n = 0; n < 2; ++n) _Pragma("unroll") for (int k = 0; k < 2; ++k) \
;         acc[ai][bj][m][n] = __builtin_amdgcn_mfma_f32_16x16x32_bf16(Bt[n][k], At[m][k], acc[ai][bj][m][n], 0, 0, 0); __builtin_amdgcn_s_setprio(0); } while (0)
; #define PG8_WAIT_V(n) asm volatile("s_waitcnt vmcnt(" #n ")" ::: "memory")
; #define PG8_WAIT_L(n) asm volatile("s_waitcnt lgkmcnt(" #n ")" ::: "memory")
; #define PG8_BAR __builtin_amdgcn_s_barrier()
; #define PG8_SCHED __builtin_amdgcn_sched_barrier(0)
; template <class Epi, class Sched, bool ALIGN_EPI = false, bool SP2 = false>
; __device__ __forceinline__ void gemm_phase(PG8_LAS unsigned char* lds, const Gemm g, const Sched& S, const Epi& E) {
;     ...
;             PG8_LDB(B0, 0, 0); PG8_LDB(B1, 0, 1); PG8_SCHED; PG8_LDA(At, 0, 0); PG8_STAGE(PG8_SA(1, 1), a1 + hstep, voffA);
;             PG8_WAIT_V(8); PG8_WAIT_L(0); PG8_BAR; PG8_MMA(0, 0, At, B0); PG8_MMA(0, 1, At, B1); PG8_BAR; PG8_SCHED;
;             PG8_LDA(At, 0, 1); PG8_STAGE(PG8_SB(0, 0), b2, voffB); PG8_STAGE(PG8_SB(0, 1), b2 + hstep, voffB); PG8_STAGE(PG8_SA(0, 0), a2, voffA);
.Lg2_peel:
	s_add_u32 s4, s40, 0xfffc0080
	s_addc_u32 s5, s41, -1
	s_add_i32 s28, 0, 0x10000
	s_cmp_eq_u32 s72, 12
	s_cselect_b32 s65, s18, s5
	s_cselect_b32 s64, s19, s4
	v_add_u32_e32 v138, s28, v142
	s_cselect_b32 s5, s13, s71
	s_cselect_b32 s4, s27, s70
	s_add_i32 s48, 0, 0x14000
	ds_read_b128 v[144:147], v138
	ds_read_b128 v[148:151], v138 offset:1024
	ds_read_b128 v[152:155], v138 offset:2048
	ds_read_b128 v[156:159], v138 offset:3072
	v_add_u32_e32 v138, s48, v142
	ds_read_b128 v[160:163], v138
	ds_read_b128 v[164:167], v138 offset:1024
	ds_read_b128 v[168:171], v138 offset:2048
	ds_read_b128 v[172:175], v138 offset:3072
	v_lshl_add_u64 v[138:139], s[40:41], 0, v[134:135]
	s_add_i32 m0, s25, 0xc000
	ds_read_b128 v[182:185], v143
	ds_read_b128 v[186:189], v143 offset:1024
	ds_read_b128 v[190:193], v143 offset:2048
	ds_read_b128 v[194:197], v143 offset:3072
	ds_read_b128 v[198:201], v143 offset:4096
	ds_read_b128 v[202:205], v143 offset:5120
	ds_read_b128 v[206:209], v143 offset:6144
	ds_read_b128 v[210:213], v143 offset:7168
	global_load_lds_dwordx4 v[138:139], off
	v_lshl_add_u64 v[138:139], s[40:41], 0, v[136:137]
	s_add_i32 m0, s25, 0xe000
	s_nop 0
	global_load_lds_dwordx4 v[138:139], off
	s_waitcnt vmcnt(24)
	s_waitcnt lgkmcnt(0)
	s_barrier
	s_setprio 1
	s_waitcnt lgkmcnt(0)
	v_mfma_f32_16x16x32_bf16 v[124:127], v[144:147], v[182:185], 0
	v_mfma_f32_16x16x32_bf16 v[120:123], v[152:155], v[182:185], 0
	v_mfma_f32_16x16x32_bf16 v[116:119], v[144:147], v[190:193], 0
	v_mfma_f32_16x16x32_bf16 v[108:111], v[152:155], v[190:193], 0
	v_mfma_f32_16x16x32_bf16 v[100:103], v[144:147], v[198:201], 0
	v_mfma_f32_16x16x32_bf16 v[92:95], v[152:155], v[198:201], 0
	v_mfma_f32_16x16x32_bf16 v[84:87], v[144:147], v[206:209], 0
	v_mfma_f32_16x16x32_bf16 v[76:79], v[152:155], v[206:209], 0
	v_mfma_f32_16x16x32_bf16 v[124:127], v[148:151], v[186:189], v[124:127]
	v_mfma_f32_16x16x32_bf16 v[120:123], v[156:159], v[186:189], v[120:123]
	v_mfma_f32_16x16x32_bf16 v[116:119], v[148:151], v[194:197], v[116:119]
	v_mfma_f32_16x16x32_bf16 v[108:111], v[156:159], v[194:197], v[108:111]
	v_mfma_f32_16x16x32_bf16 v[100:103], v[148:151], v[202:205], v[100:103]
	v_mfma_f32_16x16x32_bf16 v[92:95], v[156:159], v[202:205], v[92:95]
	v_mfma_f32_16x16x32_bf16 v[84:87], v[148:151], v[210:213], v[84:87]
	v_mfma_f32_16x16x32_bf16 v[76:79], v[156:159], v[210:213], v[76:79]
	v_mfma_f32_16x16x32_bf16 v[112:115], v[160:163], v[182:185], 0
	v_mfma_f32_16x16x32_bf16 v[104:107], v[168:171], v[182:185], 0
	v_mfma_f32_16x16x32_bf16 v[96:99], v[160:163], v[190:193], 0
	v_mfma_f32_16x16x32_bf16 v[88:91], v[168:171], v[190:193], 0
	v_mfma_f32_16x16x32_bf16 v[80:83], v[160:163], v[198:201], 0
	v_mfma_f32_16x16x32_bf16 v[72:75], v[168:171], v[198:201], 0
	v_mfma_f32_16x16x32_bf16 v[68:71], v[160:163], v[206:209], 0
	v_mfma_f32_16x16x32_bf16 v[64:67], v[168:171], v[206:209], 0
	v_mfma_f32_16x16x32_bf16 v[112:115], v[164:167], v[186:189], v[112:115]
	v_mfma_f32_16x16x32_bf16 v[104:107], v[172:175], v[186:189], v[104:107]
	v_mfma_f32_16x16x32_bf16 v[96:99], v[164:167], v[194:197], v[96:99]
	v_mfma_f32_16x16x32_bf16 v[88:91], v[172:175], v[194:197], v[88:91]
	v_mfma_f32_16x16x32_bf16 v[80:83], v[164:167], v[202:205], v[80:83]
	v_mfma_f32_16x16x32_bf16 v[72:75], v[172:175], v[202:205], v[72:75]
	v_mfma_f32_16x16x32_bf16 v[68:71], v[164:167], v[210:213], v[68:71]
	v_mfma_f32_16x16x32_bf16 v[64:67], v[172:175], v[210:213], v[64:67]
	s_setprio 0
	s_barrier
	s_add_i32 s28, s28, s24
	v_lshl_add_u64 v[138:139], s[4:5], 0, v[176:177]
	s_mov_b32 m0, s28
	ds_read_b128 v[182:185], v143 offset:16384
	ds_read_b128 v[186:189], v143 offset:17408
	ds_read_b128 v[190:193], v143 offset:18432
	ds_read_b128 v[194:197], v143 offset:19456
	ds_read_b128 v[198:201], v143 offset:20480
	ds_read_b128 v[202:205], v143 offset:21504
	ds_read_b128 v[206:209], v143 offset:22528
	ds_read_b128 v[210:213], v143 offset:23552
	global_load_lds_dwordx4 v[138:139], off
	s_add_i32 m0, s28, 0x2000
	s_add_u32 s38, s4, 0x40000
	v_lshl_add_u64 v[214:215], s[4:5], 0, v[128:129]
	s_addc_u32 s39, s5, 0
	s_add_i32 s28, s48, s24
	global_load_lds_dwordx4 v[214:215], off
	v_lshl_add_u64 v[216:217], s[38:39], 0, v[176:177]
	s_mov_b32 m0, s28
	v_lshl_add_u64 v[218:219], s[64:65], 0, v[130:131]
	global_load_lds_dwordx4 v[216:217], off
	v_lshl_add_u64 v[216:217], s[38:39], 0, v[128:129]
	s_add_i32 m0, s28, 0x2000
	s_nop 0
	global_load_lds_dwordx4 v[216:217], off
	v_lshl_add_u64 v[216:217], s[64:65], 0, v[132:133]
	s_mov_b32 m0, s25
	s_nop 0
	global_load_lds_dwordx4 v[216:217], off
	s_mov_b32 m0, s30
	s_nop 0
	global_load_lds_dwordx4 v[218:219], off
	s_waitcnt vmcnt(24)
	s_waitcnt lgkmcnt(0)
	s_barrier
; #define PG8_STAGE(bufoff, gbase, voff) do { _Pragma("unroll") for (int _i = 0; _i < 2; ++_i) \
;         __builtin_amdgcn_global_load_lds((const unsigned*)((const char*)(gbase) + (voff)[_i]), (PG8_LAS unsigned*)(lds + (bufoff) + ldsw + _i * 8192), 16, 0, 0); } while (0)
; #define PG8_LDA(dst, b, h) do { _Pragma("unroll") for (int m = 0; m < 4; ++m) _Pragma("unroll") for (int k = 0; k < 2; ++k) dst[m][k] = *(const PG8_LAS bf16x8*)(lds + PG8_SA(b, h) + aoff + m * 2048 + k * 1024); } while (0)
; #define PG8_LDB(dst, b, h) do { _Pragma("unroll") for (int n = 0; n < 2; ++n) _Pragma("unroll") for (int k = 0; k < 2; ++k) dst[n][k] = *(const PG8_LAS bf16x8*)(lds + PG8_SB(b, h) + boff + n * 2048 + k * 1024); } while (0)
; #define PG8_MMA(ai, bj, At, Bt) do { __builtin_amdgcn_s_setprio(1); _Pragma("unroll") for (int m = 0; m < 4; ++m) _Pragma("unroll") for (int n = 0; n < 2; ++n) _Pragma("unroll") for (int k = 0; k < 2; ++k) \
;         acc[ai][bj][m][n] = __builtin_amdgcn_mfma_f32_16x16x32_bf16(Bt[n][k], At[m][k], acc[ai][bj][m][n], 0, 0, 0); __builtin_amdgcn_s_setprio(0); } while (0)
; #define PG8_WAIT_V(n) asm volatile("s_waitcnt vmcnt(" #n ")" ::: "memory")
; #define PG8_WAIT_L(n) asm volatile("s_waitcnt lgkmcnt(" #n ")" ::: "memory")
; #define PG8_BAR __builtin_amdgcn_s_barrier()
; #define PG8_SCHED __builtin_amdgcn_sched_barrier(0)
; template <class Epi, class Sched, bool ALIGN_EPI = false, bool SP2 = false>
; __device__ __forceinline__ void gemm_phase(PG8_LAS unsigned char* lds, const Gemm g, const Sched& S, const Epi& E) {
;     ...
;             PG8_WAIT_V(8); PG8_WAIT_L(0); PG8_BAR; PG8_MMA(1, 0, At, B0); PG8_MMA(1, 1, At, B1); PG8_BAR; PG8_SCHED;
;             PG8_LDB(B0, 1, 0); PG8_LDB(B1, 1, 1); PG8_SCHED; PG8_LDA(At, 1, 0); PG8_STAGE(PG8_SA(0, 1), a2 + hstep, voffA);
;             PG8_WAIT_V(8); PG8_WAIT_L(0); PG8_BAR; PG8_MMA(0, 0, At, B0); PG8_MMA(0, 1, At, B1); PG8_BAR; PG8_SCHED;
	s_setprio 1
	s_waitcnt lgkmcnt(0)
	v_mfma_f32_16x16x32_bf16 v[60:63], v[144:147], v[182:185], 0
	v_mfma_f32_16x16x32_bf16 v[56:59], v[152:155], v[182:185], 0
	v_mfma_f32_16x16x32_bf16 v[52:55], v[144:147], v[190:193], 0
	v_mfma_f32_16x16x32_bf16 v[44:47], v[152:155], v[190:193], 0
	v_mfma_f32_16x16x32_bf16 v[36:39], v[144:147], v[198:201], 0
	v_mfma_f32_16x16x32_bf16 v[28:31], v[152:155], v[198:201], 0
	v_mfma_f32_16x16x32_bf16 v[20:23], v[144:147], v[206:209], 0
	v_mfma_f32_16x16x32_bf16 v[12:15], v[152:155], v[206:209], 0
	v_mfma_f32_16x16x32_bf16 v[60:63], v[148:151], v[186:189], v[60:63]
	v_mfma_f32_16x16x32_bf16 v[56:59], v[156:159], v[186:189], v[56:59]
	v_mfma_f32_16x16x32_bf16 v[52:55], v[148:151], v[194:197], v[52:55]
	v_mfma_f32_16x16x32_bf16 v[44:47], v[156:159], v[194:197], v[44:47]
	v_mfma_f32_16x16x32_bf16 v[36:39], v[148:151], v[202:205], v[36:39]
	v_mfma_f32_16x16x32_bf16 v[28:31], v[156:159], v[202:205], v[28:31]
	v_mfma_f32_16x16x32_bf16 v[20:23], v[148:151], v[210:213], v[20:23]
	v_mfma_f32_16x16x32_bf16 v[12:15], v[156:159], v[210:213], v[12:15]
	v_mfma_f32_16x16x32_bf16 v[48:51], v[160:163], v[182:185], 0
	v_mfma_f32_16x16x32_bf16 v[40:43], v[168:171], v[182:185], 0
	v_mfma_f32_16x16x32_bf16 v[32:35], v[160:163], v[190:193], 0
	v_mfma_f32_16x16x32_bf16 v[24:27], v[168:171], v[190:193], 0
	v_mfma_f32_16x16x32_bf16 v[16:19], v[160:163], v[198:201], 0
	v_mfma_f32_16x16x32_bf16 v[8:11], v[168:171], v[198:201], 0
	v_mfma_f32_16x16x32_bf16 v[4:7], v[160:163], v[206:209], 0
	v_mfma_f32_16x16x32_bf16 v[0:3], v[168:171], v[206:209], 0
	v_mfma_f32_16x16x32_bf16 v[48:51], v[164:167], v[186:189], v[48:51]
	v_mfma_f32_16x16x32_bf16 v[40:43], v[172:175], v[186:189], v[40:43]
	v_mfma_f32_16x16x32_bf16 v[32:35], v[164:167], v[194:197], v[32:35]
	v_mfma_f32_16x16x32_bf16 v[24:27], v[172:175], v[194:197], v[24:27]
	v_mfma_f32_16x16x32_bf16 v[16:19], v[164:167], v[202:205], v[16:19]
	v_mfma_f32_16x16x32_bf16 v[8:11], v[172:175], v[202:205], v[8:11]
	v_mfma_f32_16x16x32_bf16 v[4:7], v[164:167], v[210:213], v[4:7]
	v_mfma_f32_16x16x32_bf16 v[0:3], v[172:175], v[210:213], v[0:3]
	s_setprio 0
	s_barrier
	s_add_i32 s28, 0, 0x18000
	s_add_i32 s48, 0, 0x1c000
	v_add_u32_e32 v156, s28, v142
	v_add_u32_e32 v172, s48, v142
	ds_read_b128 v[144:147], v156
	ds_read_b128 v[148:151], v156 offset:1024
	ds_read_b128 v[152:155], v156 offset:2048
	ds_read_b128 v[156:159], v156 offset:3072
	ds_read_b128 v[160:163], v172
	ds_read_b128 v[164:167], v172 offset:1024
	ds_read_b128 v[168:171], v172 offset:2048
	ds_read_b128 v[172:175], v172 offset:3072
	s_add_u32 s38, s64, 0x40000
	s_addc_u32 s39, s65, 0
	s_mov_b32 m0, s31
	v_lshl_add_u64 v[220:221], s[38:39], 0, v[132:133]
	ds_read_b128 v[182:185], v143 offset:32768
	ds_read_b128 v[186:189], v143 offset:33792
	ds_read_b128 v[190:193], v143 offset:34816
	ds_read_b128 v[194:197], v143 offset:35840
	ds_read_b128 v[198:201], v143 offset:36864
	ds_read_b128 v[202:205], v143 offset:37888
	ds_read_b128 v[206:209], v143 offset:38912
	ds_read_b128 v[210:213], v143 offset:39936
	global_load_lds_dwordx4 v[220:221], off
	v_lshl_add_u64 v[220:221], s[38:39], 0, v[130:131]
	s_mov_b32 m0, s42
	s_nop 0
	global_load_lds_dwordx4 v[220:221], off
	s_waitcnt vmcnt(8)
	s_waitcnt lgkmcnt(0)
	s_barrier
	s_setprio 1
	s_waitcnt lgkmcnt(0)
	v_mfma_f32_16x16x32_bf16 v[124:127], v[144:147], v[182:185], v[124:127]
	v_mfma_f32_16x16x32_bf16 v[120:123], v[152:155], v[182:185], v[120:123]
	v_mfma_f32_16x16x32_bf16 v[116:119], v[144:147], v[190:193], v[116:119]
	v_mfma_f32_16x16x32_bf16 v[108:111], v[152:155], v[190:193], v[108:111]
	v_mfma_f32_16x16x32_bf16 v[100:103], v[144:147], v[198:201], v[100:103]
	v_mfma_f32_16x16x32_bf16 v[92:95], v[152:155], v[198:201], v[92:95]
	v_mfma_f32_16x16x32_bf16 v[84:87], v[144:147], v[206:209], v[84:87]
	v_mfma_f32_16x16x32_bf16 v[76:79], v[152:155], v[206:209], v[76:79]
	v_mfma_f32_16x16x32_bf16 v[124:127], v[148:151], v[186:189], v[124:127]
	v_mfma_f32_16x16x32_bf16 v[120:123], v[156:159], v[186:189], v[120:123]
	v_mfma_f32_16x16x32_bf16 v[116:119], v[148:151], v[194:197], v[116:119]
	v_mfma_f32_16x16x32_bf16 v[108:111], v[156:159], v[194:197], v[108:111]
	v_mfma_f32_16x16x32_bf16 v[100:103], v[148:151], v[202:205], v[100:103]
	v_mfma_f32_16x16x32_bf16 v[92:95], v[156:159], v[202:205], v[92:95]
	v_mfma_f32_16x16x32_bf16 v[84:87], v[148:151], v[210:213], v[84:87]
	v_mfma_f32_16x16x32_bf16 v[76:79], v[156:159], v[210:213], v[76:79]
	v_mfma_f32_16x16x32_bf16 v[112:115], v[160:163], v[182:185], v[112:115]
	v_mfma_f32_16x16x32_bf16 v[104:107], v[168:171], v[182:185], v[104:107]
	v_mfma_f32_16x16x32_bf16 v[96:99], v[160:163], v[190:193], v[96:99]
	v_mfma_f32_16x16x32_bf16 v[88:91], v[168:171], v[190:193], v[88:91]
	v_mfma_f32_16x16x32_bf16 v[80:83], v[160:163], v[198:201], v[80:83]
	v_mfma_f32_16x16x32_bf16 v[72:75], v[168:171], v[198:201], v[72:75]
	v_mfma_f32_16x16x32_bf16 v[68:71], v[160:163], v[206:209], v[68:71]
	v_mfma_f32_16x16x32_bf16 v[64:67], v[168:171], v[206:209], v[64:67]
	v_mfma_f32_16x16x32_bf16 v[112:115], v[164:167], v[186:189], v[112:115]
	v_mfma_f32_16x16x32_bf16 v[104:107], v[172:175], v[186:189], v[104:107]
	v_mfma_f32_16x16x32_bf16 v[96:99], v[164:167], v[194:197], v[96:99]
	v_mfma_f32_16x16x32_bf16 v[88:91], v[172:175], v[194:197], v[88:91]
	v_mfma_f32_16x16x32_bf16 v[80:83], v[164:167], v[202:205], v[80:83]
	v_mfma_f32_16x16x32_bf16 v[72:75], v[172:175], v[202:205], v[72:75]
	v_mfma_f32_16x16x32_bf16 v[68:71], v[164:167], v[210:213], v[68:71]
	v_mfma_f32_16x16x32_bf16 v[64:67], v[172:175], v[210:213], v[64:67]
	s_setprio 0
	s_barrier
; #define PG8_STAGE(bufoff, gbase, voff) do { _Pragma("unroll") for (int _i = 0; _i < 2; ++_i) \
;         __builtin_amdgcn_global_load_lds((const unsigned*)((const char*)(gbase) + (voff)[_i]), (PG8_LAS unsigned*)(lds + (bufoff) + ldsw + _i * 8192), 16, 0, 0); } while (0)
; #define PG8_LDA(dst, b, h) do { _Pragma("unroll") for (int m = 0; m < 4; ++m) _Pragma("unroll") for (int k = 0; k < 2; ++k) dst[m][k] = *(const PG8_LAS bf16x8*)(lds + PG8_SA(b, h) + aoff + m * 2048 + k * 1024); } while (0)
; #define PG8_MMA(ai, bj, At, Bt) do { __builtin_amdgcn_s_setprio(1); _Pragma("unroll") for (int m = 0; m < 4; ++m) _Pragma("unroll") for (int n = 0; n < 2; ++n) _Pragma("unroll") for (int k = 0; k < 2; ++k) \
;         acc[ai][bj][m][n] = __builtin_amdgcn_mfma_f32_16x16x32_bf16(Bt[n][k], At[m][k], acc[ai][bj][m][n], 0, 0, 0); __builtin_amdgcn_s_setprio(0); } while (0)
; #define PG8_WAIT_V(n) asm volatile("s_waitcnt vmcnt(" #n ")" ::: "memory")
; #define PG8_WAIT_L(n) asm volatile("s_waitcnt lgkmcnt(" #n ")" ::: "memory")
; #define PG8_BAR __builtin_amdgcn_s_barrier()
; #define PG8_SCHED __builtin_amdgcn_sched_barrier(0)
; template <class Epi, class Sched, bool ALIGN_EPI = false, bool SP2 = false>
; __device__ __forceinline__ void gemm_phase(PG8_LAS unsigned char* lds, const Gemm g, const Sched& S, const Epi& E) {
;     ...
;             PG8_LDA(At, 1, 1); PG8_STAGE(PG8_SB(1, 0), b3, voffB); PG8_STAGE(PG8_SB(1, 1), b3 + hstep, voffB); PG8_STAGE(PG8_SA(1, 0), a3, voffA);
;             PG8_WAIT_V(8); PG8_WAIT_L(0); PG8_BAR; PG8_MMA(1, 0, At, B0); PG8_MMA(1, 1, At, B1); PG8_BAR; PG8_SCHED;
	s_add_i32 s28, s28, s24
	v_lshl_add_u64 v[138:139], v[138:139], 0, s[44:45]
	s_mov_b32 m0, s28
	ds_read_b128 v[182:185], v143 offset:49152
	ds_read_b128 v[186:189], v143 offset:50176
	ds_read_b128 v[190:193], v143 offset:51200
	ds_read_b128 v[194:197], v143 offset:52224
	ds_read_b128 v[198:201], v143 offset:53248
	ds_read_b128 v[202:205], v143 offset:54272
	ds_read_b128 v[206:209], v143 offset:55296
	ds_read_b128 v[210:213], v143 offset:56320
	global_load_lds_dwordx4 v[138:139], off
	s_add_i32 m0, s28, 0x2000
	s_add_u32 s4, s4, 0x40080
	v_lshl_add_u64 v[138:139], v[214:215], 0, s[44:45]
	s_addc_u32 s5, s5, 0
	s_add_i32 s28, s48, s24
	global_load_lds_dwordx4 v[138:139], off
	v_lshl_add_u64 v[138:139], s[4:5], 0, v[176:177]
	s_mov_b32 m0, s28
	s_nop 0
	global_load_lds_dwordx4 v[138:139], off
	v_lshl_add_u64 v[138:139], s[4:5], 0, v[128:129]
	s_add_i32 m0, s28, 0x2000
	s_nop 0
	global_load_lds_dwordx4 v[138:139], off
	v_lshl_add_u64 v[138:139], v[216:217], 0, s[44:45]
	s_mov_b32 m0, s63
	s_nop 0
	global_load_lds_dwordx4 v[138:139], off
	v_lshl_add_u64 v[138:139], v[218:219], 0, s[44:45]
	s_mov_b32 m0, s66
	s_nop 0
	global_load_lds_dwordx4 v[138:139], off
	s_waitcnt vmcnt(8)
	s_waitcnt lgkmcnt(0)
	s_barrier
	s_setprio 1
	s_waitcnt lgkmcnt(0)
	v_mfma_f32_16x16x32_bf16 v[60:63], v[144:147], v[182:185], v[60:63]
	v_mfma_f32_16x16x32_bf16 v[56:59], v[152:155], v[182:185], v[56:59]
	v_mfma_f32_16x16x32_bf16 v[52:55], v[144:147], v[190:193], v[52:55]
	v_mfma_f32_16x16x32_bf16 v[44:47], v[152:155], v[190:193], v[44:47]
	v_mfma_f32_16x16x32_bf16 v[36:39], v[144:147], v[198:201], v[36:39]
	v_mfma_f32_16x16x32_bf16 v[28:31], v[152:155], v[198:201], v[28:31]
	v_mfma_f32_16x16x32_bf16 v[20:23], v[144:147], v[206:209], v[20:23]
	v_mfma_f32_16x16x32_bf16 v[12:15], v[152:155], v[206:209], v[12:15]
	v_mfma_f32_16x16x32_bf16 v[60:63], v[148:151], v[186:189], v[60:63]
	v_mfma_f32_16x16x32_bf16 v[56:59], v[156:159], v[186:189], v[56:59]
	v_mfma_f32_16x16x32_bf16 v[52:55], v[148:151], v[194:197], v[52:55]
	v_mfma_f32_16x16x32_bf16 v[44:47], v[156:159], v[194:197], v[44:47]
	v_mfma_f32_16x16x32_bf16 v[36:39], v[148:151], v[202:205], v[36:39]
	v_mfma_f32_16x16x32_bf16 v[28:31], v[156:159], v[202:205], v[28:31]
	v_mfma_f32_16x16x32_bf16 v[20:23], v[148:151], v[210:213], v[20:23]
	v_mfma_f32_16x16x32_bf16 v[12:15], v[156:159], v[210:213], v[12:15]
	v_mfma_f32_16x16x32_bf16 v[48:51], v[160:163], v[182:185], v[48:51]
	v_mfma_f32_16x16x32_bf16 v[40:43], v[168:171], v[182:185], v[40:43]
	v_mfma_f32_16x16x32_bf16 v[32:35], v[160:163], v[190:193], v[32:35]
	v_mfma_f32_16x16x32_bf16 v[24:27], v[168:171], v[190:193], v[24:27]
	v_mfma_f32_16x16x32_bf16 v[16:19], v[160:163], v[198:201], v[16:19]
	v_mfma_f32_16x16x32_bf16 v[8:11], v[168:171], v[198:201], v[8:11]
	v_mfma_f32_16x16x32_bf16 v[4:7], v[160:163], v[206:209], v[4:7]
	v_mfma_f32_16x16x32_bf16 v[0:3], v[168:171], v[206:209], v[0:3]
	v_mfma_f32_16x16x32_bf16 v[48:51], v[164:167], v[186:189], v[48:51]
	v_mfma_f32_16x16x32_bf16 v[40:43], v[172:175], v[186:189], v[40:43]
	s_add_i32 s72, s72, 2
	v_mfma_f32_16x16x32_bf16 v[32:35], v[164:167], v[194:197], v[32:35]
	s_add_u32 s40, s40, 0x100
	v_mfma_f32_16x16x32_bf16 v[24:27], v[172:175], v[194:197], v[24:27]
	s_addc_u32 s41, s41, 0
	v_mfma_f32_16x16x32_bf16 v[16:19], v[164:167], v[202:205], v[16:19]
	s_add_u32 s70, s70, 0x100
	v_mfma_f32_16x16x32_bf16 v[8:11], v[172:175], v[202:205], v[8:11]
	s_addc_u32 s71, s71, 0
	v_mfma_f32_16x16x32_bf16 v[4:7], v[164:167], v[210:213], v[4:7]
	s_cmp_gt_u32 s72, 13
	v_mfma_f32_16x16x32_bf16 v[0:3], v[172:175], v[210:213], v[0:3]
	s_setprio 0
	s_barrier
	s_cbranch_scc0 .LBB0_570
	s_branch .Lg2_post

; #define PG8_STAGE(bufoff, gbase, voff) do { _Pragma("unroll") for (int _i = 0; _i < 2; ++_i) \
;         __builtin_amdgcn_global_load_lds((const unsigned*)((const char*)(gbase) + (voff)[_i]), (PG8_LAS unsigned*)(lds + (bufoff) + ldsw + _i * 8192), 16, 0, 0); } while (0)
; #define PG8_LDA(dst, b, h) do { _Pragma("unroll") for (int m = 0; m < 4; ++m) _Pragma("unroll") for (int k = 0; k < 2; ++k) dst[m][k] = *(const PG8_LAS bf16x8*)(lds + PG8_SA(b, h) + aoff + m * 2048 + k * 1024); } while (0)
; #define PG8_LDB(dst, b, h) do { _Pragma("unroll") for (int n = 0; n < 2; ++n) _Pragma("unroll") for (int k = 0; k < 2; ++k) dst[n][k] = *(const PG8_LAS bf16x8*)(lds + PG8_SB(b, h) + boff + n * 2048 + k * 1024); } while (0)
; #define PG8_MMA(ai, bj, At, Bt) do { __builtin_amdgcn_s_setprio(1); _Pragma("unroll") for (int m = 0; m < 4; ++m) _Pragma("unroll") for (int n = 0; n < 2; ++n) _Pragma("unroll") for (int k = 0; k < 2; ++k) \
;         acc[ai][bj][m][n] = __builtin_amdgcn_mfma_f32_16x16x32_bf16(Bt[n][k], At[m][k], acc[ai][bj][m][n], 0, 0, 0); __builtin_amdgcn_s_setprio(0); } while (0)
; #define PG8_WAIT_V(n) asm volatile("s_waitcnt vmcnt(" #n ")" ::: "memory")
; #define PG8_WAIT_L(n) asm volatile("s_waitcnt lgkmcnt(" #n ")" ::: "memory")
; #define PG8_BAR __builtin_amdgcn_s_barrier()
; #define PG8_SCHED __builtin_amdgcn_sched_barrier(0)
; template <class Epi, class Sched, bool ALIGN_EPI = false, bool SP2 = false>
; __device__ __forceinline__ void gemm_phase(PG8_LAS unsigned char* lds, const Gemm g, const Sched& S, const Epi& E) {
;     ...
;             const bool last = (t == nt - 2);
;             const char* a1 = cA + (size_t)(t + 1) * kstep;
;             const char* a2 = last ? nA : cA + (size_t)(t + 2) * kstep; const char* b2 = last ? nB : cB + (size_t)(t + 2) * kstep;
;             const char* a3 = a2 + kstep; const char* b3 = b2 + kstep;
;             if (last && has_next) S.a_ready(nxt);
;             if constexpr (SP2) {
;             PG8_LDB(B0, 0, 0); PG8_LDB(B1, 0, 1); PG8_SCHED; PG8_LDA(At, 0, 0); PG8_STAGE(PG8_SA(1, 1), a1 + hstep, voffA);
;             PG8_WAIT_V(8); PG8_WAIT_L(0); PG8_BAR; PG8_MMA(0, 0, At, B0); PG8_MMA(0, 1, At, B1); PG8_BAR; PG8_SCHED;
;             PG8_LDA(At, 0, 1); PG8_STAGE(PG8_SB(0, 0), b2, voffB); PG8_STAGE(PG8_SB(0, 1), b2 + hstep, voffB); PG8_STAGE(PG8_SA(0, 0), a2, voffA);
.LBB0_592:
	s_add_i32 s81, s4, 2
	s_add_u32 s28, s66, 0x80
	s_addc_u32 s5, s67, 0
	s_add_i32 s48, 0, 0x10000
	s_cmp_eq_u32 s70, s4
	s_cselect_b32 s5, s41, s5
	s_cselect_b32 s4, s40, s28
	s_cselect_b32 s39, s65, s69
	s_cselect_b32 s38, s64, s68
	s_add_i32 s28, 0, 0x14000
	v_add_u32_e32 v154, s48, v140
	v_add_u32_e32 v170, s28, v140
	ds_read_b128 v[142:145], v154
	ds_read_b128 v[146:149], v154 offset:1024
	ds_read_b128 v[150:153], v154 offset:2048
	ds_read_b128 v[154:157], v154 offset:3072
	ds_read_b128 v[158:161], v170
	ds_read_b128 v[162:165], v170 offset:1024
	ds_read_b128 v[166:169], v170 offset:2048
	ds_read_b128 v[170:173], v170 offset:3072
	v_lshl_add_u64 v[174:175], s[66:67], 0, v[134:135]
	s_add_i32 m0, s19, 0xc000
	ds_read_b128 v[182:185], v141
	ds_read_b128 v[186:189], v141 offset:1024
	ds_read_b128 v[190:193], v141 offset:2048
	ds_read_b128 v[194:197], v141 offset:3072
	ds_read_b128 v[198:201], v141 offset:4096
	ds_read_b128 v[202:205], v141 offset:5120
	ds_read_b128 v[206:209], v141 offset:6144
	ds_read_b128 v[210:213], v141 offset:7168
	global_load_lds_dwordx4 v[174:175], off
	v_lshl_add_u64 v[174:175], s[66:67], 0, v[136:137]
	s_add_i32 m0, s19, 0xe000
	s_nop 0
	global_load_lds_dwordx4 v[174:175], off
	s_waitcnt vmcnt(8)
	s_waitcnt lgkmcnt(0)
	s_barrier
	s_setprio 1
	s_waitcnt lgkmcnt(0)
	v_mfma_f32_16x16x32_bf16 v[124:127], v[142:145], v[182:185], v[124:127]
	v_mfma_f32_16x16x32_bf16 v[120:123], v[150:153], v[182:185], v[120:123]
	v_mfma_f32_16x16x32_bf16 v[108:111], v[142:145], v[190:193], v[108:111]
	v_mfma_f32_16x16x32_bf16 v[104:107], v[150:153], v[190:193], v[104:107]
	v_mfma_f32_16x16x32_bf16 v[92:95], v[142:145], v[198:201], v[92:95]
	v_mfma_f32_16x16x32_bf16 v[88:91], v[150:153], v[198:201], v[88:91]
	v_mfma_f32_16x16x32_bf16 v[76:79], v[142:145], v[206:209], v[76:79]
	v_mfma_f32_16x16x32_bf16 v[72:75], v[150:153], v[206:209], v[72:75]
	v_mfma_f32_16x16x32_bf16 v[124:127], v[146:149], v[186:189], v[124:127]
	v_mfma_f32_16x16x32_bf16 v[120:123], v[154:157], v[186:189], v[120:123]
	v_mfma_f32_16x16x32_bf16 v[108:111], v[146:149], v[194:197], v[108:111]
	v_mfma_f32_16x16x32_bf16 v[104:107], v[154:157], v[194:197], v[104:107]
	v_mfma_f32_16x16x32_bf16 v[92:95], v[146:149], v[202:205], v[92:95]
	v_mfma_f32_16x16x32_bf16 v[88:91], v[154:157], v[202:205], v[88:91]
	v_mfma_f32_16x16x32_bf16 v[76:79], v[146:149], v[210:213], v[76:79]
	v_mfma_f32_16x16x32_bf16 v[72:75], v[154:157], v[210:213], v[72:75]
	v_mfma_f32_16x16x32_bf16 v[116:119], v[158:161], v[182:185], v[116:119]
	v_mfma_f32_16x16x32_bf16 v[112:115], v[166:169], v[182:185], v[112:115]
	v_mfma_f32_16x16x32_bf16 v[100:103], v[158:161], v[190:193], v[100:103]
	v_mfma_f32_16x16x32_bf16 v[96:99], v[166:169], v[190:193], v[96:99]
	v_mfma_f32_16x16x32_bf16 v[84:87], v[158:161], v[198:201], v[84:87]
	v_mfma_f32_16x16x32_bf16 v[80:83], v[166:169], v[198:201], v[80:83]
	v_mfma_f32_16x16x32_bf16 v[68:71], v[158:161], v[206:209], v[68:71]
	v_mfma_f32_16x16x32_bf16 v[64:67], v[166:169], v[206:209], v[64:67]
	v_mfma_f32_16x16x32_bf16 v[116:119], v[162:165], v[186:189], v[116:119]
	v_mfma_f32_16x16x32_bf16 v[112:115], v[170:173], v[186:189], v[112:115]
	v_mfma_f32_16x16x32_bf16 v[100:103], v[162:165], v[194:197], v[100:103]
	v_mfma_f32_16x16x32_bf16 v[96:99], v[170:173], v[194:197], v[96:99]
	v_mfma_f32_16x16x32_bf16 v[84:87], v[162:165], v[202:205], v[84:87]
	v_mfma_f32_16x16x32_bf16 v[80:83], v[170:173], v[202:205], v[80:83]
	v_mfma_f32_16x16x32_bf16 v[68:71], v[162:165], v[210:213], v[68:71]
	v_mfma_f32_16x16x32_bf16 v[64:67], v[170:173], v[210:213], v[64:67]
	s_setprio 0
	s_barrier
	s_add_i32 s48, s48, s18
	v_lshl_add_u64 v[174:175], s[38:39], 0, v[176:177]
	s_mov_b32 m0, s48
	ds_read_b128 v[182:185], v141 offset:16384
	ds_read_b128 v[186:189], v141 offset:17408
	ds_read_b128 v[190:193], v141 offset:18432
	ds_read_b128 v[194:197], v141 offset:19456
	ds_read_b128 v[198:201], v141 offset:20480
	ds_read_b128 v[202:205], v141 offset:21504
	ds_read_b128 v[206:209], v141 offset:22528
	ds_read_b128 v[210:213], v141 offset:23552
	global_load_lds_dwordx4 v[174:175], off
	s_add_i32 m0, s48, 0x2000
	v_lshl_add_u64 v[214:215], s[38:39], 0, v[128:129]
	s_add_u32 s38, s38, s0
	s_addc_u32 s39, s39, s1
	s_add_i32 s28, s28, s18
	global_load_lds_dwordx4 v[214:215], off
	v_lshl_add_u64 v[216:217], s[38:39], 0, v[176:177]
	s_mov_b32 m0, s28
	v_lshl_add_u64 v[218:219], s[38:39], 0, v[128:129]
	global_load_lds_dwordx4 v[216:217], off
	s_add_i32 m0, s28, 0x2000
	v_lshl_add_u64 v[220:221], s[4:5], 0, v[132:133]
	global_load_lds_dwordx4 v[218:219], off
	s_mov_b32 m0, s19
	v_lshl_add_u64 v[222:223], s[4:5], 0, v[130:131]
	global_load_lds_dwordx4 v[220:221], off
	s_mov_b32 m0, s24
	s_nop 0
	global_load_lds_dwordx4 v[222:223], off
	s_waitcnt vmcnt(8)
	s_waitcnt lgkmcnt(0)
	s_barrier
; #define PG8_STAGE(bufoff, gbase, voff) do { _Pragma("unroll") for (int _i = 0; _i < 2; ++_i) \
;         __builtin_amdgcn_global_load_lds((const unsigned*)((const char*)(gbase) + (voff)[_i]), (PG8_LAS unsigned*)(lds + (bufoff) + ldsw + _i * 8192), 16, 0, 0); } while (0)
; #define PG8_LDA(dst, b, h) do { _Pragma("unroll") for (int m = 0; m < 4; ++m) _Pragma("unroll") for (int k = 0; k < 2; ++k) dst[m][k] = *(const PG8_LAS bf16x8*)(lds + PG8_SA(b, h) + aoff + m * 2048 + k * 1024); } while (0)
; #define PG8_LDB(dst, b, h) do { _Pragma("unroll") for (int n = 0; n < 2; ++n) _Pragma("unroll") for (int k = 0; k < 2; ++k) dst[n][k] = *(const PG8_LAS bf16x8*)(lds + PG8_SB(b, h) + boff + n * 2048 + k * 1024); } while (0)
; #define PG8_MMA(ai, bj, At, Bt) do { __builtin_amdgcn_s_setprio(1); _Pragma("unroll") for (int m = 0; m < 4; ++m) _Pragma("unroll") for (int n = 0; n < 2; ++n) _Pragma("unroll") for (int k = 0; k < 2; ++k) \
;         acc[ai][bj][m][n] = __builtin_amdgcn_mfma_f32_16x16x32_bf16(Bt[n][k], At[m][k], acc[ai][bj][m][n], 0, 0, 0); __builtin_amdgcn_s_setprio(0); } while (0)
; #define PG8_WAIT_V(n) asm volatile("s_waitcnt vmcnt(" #n ")" ::: "memory")
; #define PG8_WAIT_L(n) asm volatile("s_waitcnt lgkmcnt(" #n ")" ::: "memory")
; #define PG8_BAR __builtin_amdgcn_s_barrier()
; #define PG8_SCHED __builtin_amdgcn_sched_barrier(0)
; template <class Epi, class Sched, bool ALIGN_EPI = false, bool SP2 = false>
; __device__ __forceinline__ void gemm_phase(PG8_LAS unsigned char* lds, const Gemm g, const Sched& S, const Epi& E) {
;     ...
;             PG8_WAIT_V(8); PG8_WAIT_L(0); PG8_BAR; PG8_MMA(1, 0, At, B0); PG8_MMA(1, 1, At, B1); PG8_BAR; PG8_SCHED;
;             PG8_LDB(B0, 1, 0); PG8_LDB(B1, 1, 1); PG8_SCHED; PG8_LDA(At, 1, 0); PG8_STAGE(PG8_SA(0, 1), a2 + hstep, voffA);
;             PG8_WAIT_V(8); PG8_WAIT_L(0); PG8_BAR; PG8_MMA(0, 0, At, B0); PG8_MMA(0, 1, At, B1); PG8_BAR; PG8_SCHED;
	s_setprio 1
	s_waitcnt lgkmcnt(0)
	v_mfma_f32_16x16x32_bf16 v[60:63], v[142:145], v[182:185], v[60:63]
	v_mfma_f32_16x16x32_bf16 v[56:59], v[150:153], v[182:185], v[56:59]
	v_mfma_f32_16x16x32_bf16 v[44:47], v[142:145], v[190:193], v[44:47]
	v_mfma_f32_16x16x32_bf16 v[40:43], v[150:153], v[190:193], v[40:43]
	v_mfma_f32_16x16x32_bf16 v[28:31], v[142:145], v[198:201], v[28:31]
	v_mfma_f32_16x16x32_bf16 v[24:27], v[150:153], v[198:201], v[24:27]
	v_mfma_f32_16x16x32_bf16 v[12:15], v[142:145], v[206:209], v[12:15]
	v_mfma_f32_16x16x32_bf16 v[8:11], v[150:153], v[206:209], v[8:11]
	v_mfma_f32_16x16x32_bf16 v[60:63], v[146:149], v[186:189], v[60:63]
	v_mfma_f32_16x16x32_bf16 v[56:59], v[154:157], v[186:189], v[56:59]
	v_mfma_f32_16x16x32_bf16 v[44:47], v[146:149], v[194:197], v[44:47]
	v_mfma_f32_16x16x32_bf16 v[40:43], v[154:157], v[194:197], v[40:43]
	v_mfma_f32_16x16x32_bf16 v[28:31], v[146:149], v[202:205], v[28:31]
	v_mfma_f32_16x16x32_bf16 v[24:27], v[154:157], v[202:205], v[24:27]
	v_mfma_f32_16x16x32_bf16 v[12:15], v[146:149], v[210:213], v[12:15]
	v_mfma_f32_16x16x32_bf16 v[8:11], v[154:157], v[210:213], v[8:11]
	v_mfma_f32_16x16x32_bf16 v[52:55], v[158:161], v[182:185], v[52:55]
	v_mfma_f32_16x16x32_bf16 v[48:51], v[166:169], v[182:185], v[48:51]
	v_mfma_f32_16x16x32_bf16 v[36:39], v[158:161], v[190:193], v[36:39]
	v_mfma_f32_16x16x32_bf16 v[32:35], v[166:169], v[190:193], v[32:35]
	v_mfma_f32_16x16x32_bf16 v[20:23], v[158:161], v[198:201], v[20:23]
	v_mfma_f32_16x16x32_bf16 v[16:19], v[166:169], v[198:201], v[16:19]
	v_mfma_f32_16x16x32_bf16 v[4:7], v[158:161], v[206:209], v[4:7]
	v_mfma_f32_16x16x32_bf16 v[0:3], v[166:169], v[206:209], v[0:3]
	v_mfma_f32_16x16x32_bf16 v[52:55], v[162:165], v[186:189], v[52:55]
	v_mfma_f32_16x16x32_bf16 v[48:51], v[170:173], v[186:189], v[48:51]
	v_mfma_f32_16x16x32_bf16 v[36:39], v[162:165], v[194:197], v[36:39]
	v_mfma_f32_16x16x32_bf16 v[32:35], v[170:173], v[194:197], v[32:35]
	v_mfma_f32_16x16x32_bf16 v[20:23], v[162:165], v[202:205], v[20:23]
	v_mfma_f32_16x16x32_bf16 v[16:19], v[170:173], v[202:205], v[16:19]
	v_mfma_f32_16x16x32_bf16 v[4:7], v[162:165], v[210:213], v[4:7]
	v_mfma_f32_16x16x32_bf16 v[0:3], v[170:173], v[210:213], v[0:3]
	s_setprio 0
	s_barrier
	s_add_i32 s28, 0, 0x18000
	s_add_i32 s38, 0, 0x1c000
	v_add_u32_e32 v154, s28, v140
	v_add_u32_e32 v170, s38, v140
	ds_read_b128 v[142:145], v154
	ds_read_b128 v[146:149], v154 offset:1024
	ds_read_b128 v[150:153], v154 offset:2048
	ds_read_b128 v[154:157], v154 offset:3072
	ds_read_b128 v[158:161], v170
	ds_read_b128 v[162:165], v170 offset:1024
	ds_read_b128 v[166:169], v170 offset:2048
	ds_read_b128 v[170:173], v170 offset:3072
	s_add_u32 s4, s4, s0
	s_addc_u32 s5, s5, s1
	s_mov_b32 m0, s25
	v_lshl_add_u64 v[224:225], s[4:5], 0, v[132:133]
	ds_read_b128 v[182:185], v141 offset:32768
	ds_read_b128 v[186:189], v141 offset:33792
	ds_read_b128 v[190:193], v141 offset:34816
	ds_read_b128 v[194:197], v141 offset:35840
	ds_read_b128 v[198:201], v141 offset:36864
	ds_read_b128 v[202:205], v141 offset:37888
	ds_read_b128 v[206:209], v141 offset:38912
	ds_read_b128 v[210:213], v141 offset:39936
	global_load_lds_dwordx4 v[224:225], off
	v_lshl_add_u64 v[224:225], s[4:5], 0, v[130:131]
	s_mov_b32 m0, s30
	s_nop 0
	global_load_lds_dwordx4 v[224:225], off
	s_waitcnt vmcnt(8)
	s_waitcnt lgkmcnt(0)
	s_barrier
	s_setprio 1
	s_waitcnt lgkmcnt(0)
	v_mfma_f32_16x16x32_bf16 v[124:127], v[142:145], v[182:185], v[124:127]
	v_mfma_f32_16x16x32_bf16 v[120:123], v[150:153], v[182:185], v[120:123]
	v_mfma_f32_16x16x32_bf16 v[108:111], v[142:145], v[190:193], v[108:111]
	v_mfma_f32_16x16x32_bf16 v[104:107], v[150:153], v[190:193], v[104:107]
	v_mfma_f32_16x16x32_bf16 v[92:95], v[142:145], v[198:201], v[92:95]
	v_mfma_f32_16x16x32_bf16 v[88:91], v[150:153], v[198:201], v[88:91]
	v_mfma_f32_16x16x32_bf16 v[76:79], v[142:145], v[206:209], v[76:79]
	v_mfma_f32_16x16x32_bf16 v[72:75], v[150:153], v[206:209], v[72:75]
	v_mfma_f32_16x16x32_bf16 v[124:127], v[146:149], v[186:189], v[124:127]
	v_mfma_f32_16x16x32_bf16 v[120:123], v[154:157], v[186:189], v[120:123]
	v_mfma_f32_16x16x32_bf16 v[108:111], v[146:149], v[194:197], v[108:111]
	v_mfma_f32_16x16x32_bf16 v[104:107], v[154:157], v[194:197], v[104:107]
	v_mfma_f32_16x16x32_bf16 v[92:95], v[146:149], v[202:205], v[92:95]
	v_mfma_f32_16x16x32_bf16 v[88:91], v[154:157], v[202:205], v[88:91]
	v_mfma_f32_16x16x32_bf16 v[76:79], v[146:149], v[210:213], v[76:79]
	v_mfma_f32_16x16x32_bf16 v[72:75], v[154:157], v[210:213], v[72:75]
	v_mfma_f32_16x16x32_bf16 v[116:119], v[158:161], v[182:185], v[116:119]
	v_mfma_f32_16x16x32_bf16 v[112:115], v[166:169], v[182:185], v[112:115]
	v_mfma_f32_16x16x32_bf16 v[100:103], v[158:161], v[190:193], v[100:103]
	v_mfma_f32_16x16x32_bf16 v[96:99], v[166:169], v[190:193], v[96:99]
	v_mfma_f32_16x16x32_bf16 v[84:87], v[158:161], v[198:201], v[84:87]
	v_mfma_f32_16x16x32_bf16 v[80:83], v[166:169], v[198:201], v[80:83]
	v_mfma_f32_16x16x32_bf16 v[68:71], v[158:161], v[206:209], v[68:71]
	v_mfma_f32_16x16x32_bf16 v[64:67], v[166:169], v[206:209], v[64:67]
	v_mfma_f32_16x16x32_bf16 v[116:119], v[162:165], v[186:189], v[116:119]
	v_mfma_f32_16x16x32_bf16 v[112:115], v[170:173], v[186:189], v[112:115]
	v_mfma_f32_16x16x32_bf16 v[100:103], v[162:165], v[194:197], v[100:103]
	v_mfma_f32_16x16x32_bf16 v[96:99], v[170:173], v[194:197], v[96:99]
	v_mfma_f32_16x16x32_bf16 v[84:87], v[162:165], v[202:205], v[84:87]
	v_mfma_f32_16x16x32_bf16 v[80:83], v[170:173], v[202:205], v[80:83]
	v_mfma_f32_16x16x32_bf16 v[68:71], v[162:165], v[210:213], v[68:71]
	v_mfma_f32_16x16x32_bf16 v[64:67], v[170:173], v[210:213], v[64:67]
	s_setprio 0
	s_barrier
; #define PG8_STAGE(bufoff, gbase, voff) do { _Pragma("unroll") for (int _i = 0; _i < 2; ++_i) \
;         __builtin_amdgcn_global_load_lds((const unsigned*)((const char*)(gbase) + (voff)[_i]), (PG8_LAS unsigned*)(lds + (bufoff) + ldsw + _i * 8192), 16, 0, 0); } while (0)
; #define PG8_LDA(dst, b, h) do { _Pragma("unroll") for (int m = 0; m < 4; ++m) _Pragma("unroll") for (int k = 0; k < 2; ++k) dst[m][k] = *(const PG8_LAS bf16x8*)(lds + PG8_SA(b, h) + aoff + m * 2048 + k * 1024); } while (0)
; #define PG8_MMA(ai, bj, At, Bt) do { __builtin_amdgcn_s_setprio(1); _Pragma("unroll") for (int m = 0; m < 4; ++m) _Pragma("unroll") for (int n = 0; n < 2; ++n) _Pragma("unroll") for (int k = 0; k < 2; ++k) \
;         acc[ai][bj][m][n] = __builtin_amdgcn_mfma_f32_16x16x32_bf16(Bt[n][k], At[m][k], acc[ai][bj][m][n], 0, 0, 0); __builtin_amdgcn_s_setprio(0); } while (0)
; #define PG8_WAIT_V(n) asm volatile("s_waitcnt vmcnt(" #n ")" ::: "memory")
; #define PG8_WAIT_L(n) asm volatile("s_waitcnt lgkmcnt(" #n ")" ::: "memory")
; #define PG8_BAR __builtin_amdgcn_s_barrier()
; #define PG8_SCHED __builtin_amdgcn_sched_barrier(0)
; template <class Epi, class Sched, bool ALIGN_EPI = false, bool SP2 = false>
; __device__ __forceinline__ void gemm_phase(PG8_LAS unsigned char* lds, const Gemm g, const Sched& S, const Epi& E) {
;     ...
;             PG8_LDA(At, 1, 1); PG8_STAGE(PG8_SB(1, 0), b3, voffB); PG8_STAGE(PG8_SB(1, 1), b3 + hstep, voffB); PG8_STAGE(PG8_SA(1, 0), a3, voffA);
;             PG8_WAIT_V(8); PG8_WAIT_L(0); PG8_BAR; PG8_MMA(1, 0, At, B0); PG8_MMA(1, 1, At, B1); PG8_BAR; PG8_SCHED;
	s_add_i32 s4, s28, s18
	v_lshl_add_u64 v[174:175], v[174:175], 0, s[44:45]
	s_mov_b32 m0, s4
	ds_read_b128 v[182:185], v141 offset:49152
	ds_read_b128 v[186:189], v141 offset:50176
	ds_read_b128 v[190:193], v141 offset:51200
	ds_read_b128 v[194:197], v141 offset:52224
	ds_read_b128 v[198:201], v141 offset:53248
	ds_read_b128 v[202:205], v141 offset:54272
	ds_read_b128 v[206:209], v141 offset:55296
	ds_read_b128 v[210:213], v141 offset:56320
	global_load_lds_dwordx4 v[174:175], off
	v_lshl_add_u64 v[174:175], v[214:215], 0, s[44:45]
	s_add_i32 m0, s4, 0x2000
	s_add_i32 s4, s38, s18
	global_load_lds_dwordx4 v[174:175], off
	v_lshl_add_u64 v[174:175], v[216:217], 0, s[44:45]
	s_mov_b32 m0, s4
	s_nop 0
	global_load_lds_dwordx4 v[174:175], off
	v_lshl_add_u64 v[174:175], v[218:219], 0, s[44:45]
	s_add_i32 m0, s4, 0x2000
	s_nop 0
	global_load_lds_dwordx4 v[174:175], off
	v_lshl_add_u64 v[174:175], v[220:221], 0, s[44:45]
	s_mov_b32 m0, s43
	s_nop 0
	global_load_lds_dwordx4 v[174:175], off
	v_lshl_add_u64 v[174:175], v[222:223], 0, s[44:45]
	s_mov_b32 m0, s46
	s_nop 0
	global_load_lds_dwordx4 v[174:175], off
	s_waitcnt vmcnt(8)
	s_waitcnt lgkmcnt(0)
	s_barrier
	s_setprio 1
	s_waitcnt lgkmcnt(0)
	v_mfma_f32_16x16x32_bf16 v[60:63], v[142:145], v[182:185], v[60:63]
	v_mfma_f32_16x16x32_bf16 v[56:59], v[150:153], v[182:185], v[56:59]
	v_mfma_f32_16x16x32_bf16 v[44:47], v[142:145], v[190:193], v[44:47]
	v_mfma_f32_16x16x32_bf16 v[40:43], v[150:153], v[190:193], v[40:43]
	v_mfma_f32_16x16x32_bf16 v[28:31], v[142:145], v[198:201], v[28:31]
	v_mfma_f32_16x16x32_bf16 v[24:27], v[150:153], v[198:201], v[24:27]
	v_mfma_f32_16x16x32_bf16 v[12:15], v[142:145], v[206:209], v[12:15]
	v_mfma_f32_16x16x32_bf16 v[8:11], v[150:153], v[206:209], v[8:11]
	v_mfma_f32_16x16x32_bf16 v[60:63], v[146:149], v[186:189], v[60:63]
	v_mfma_f32_16x16x32_bf16 v[56:59], v[154:157], v[186:189], v[56:59]
	v_mfma_f32_16x16x32_bf16 v[44:47], v[146:149], v[194:197], v[44:47]
	v_mfma_f32_16x16x32_bf16 v[40:43], v[154:157], v[194:197], v[40:43]
	v_mfma_f32_16x16x32_bf16 v[28:31], v[146:149], v[202:205], v[28:31]
	v_mfma_f32_16x16x32_bf16 v[24:27], v[154:157], v[202:205], v[24:27]
	v_mfma_f32_16x16x32_bf16 v[12:15], v[146:149], v[210:213], v[12:15]
	v_mfma_f32_16x16x32_bf16 v[8:11], v[154:157], v[210:213], v[8:11]
	v_mfma_f32_16x16x32_bf16 v[52:55], v[158:161], v[182:185], v[52:55]
	v_mfma_f32_16x16x32_bf16 v[48:51], v[166:169], v[182:185], v[48:51]
	v_mfma_f32_16x16x32_bf16 v[36:39], v[158:161], v[190:193], v[36:39]
	v_mfma_f32_16x16x32_bf16 v[32:35], v[166:169], v[190:193], v[32:35]
	v_mfma_f32_16x16x32_bf16 v[20:23], v[158:161], v[198:201], v[20:23]
	v_mfma_f32_16x16x32_bf16 v[16:19], v[166:169], v[198:201], v[16:19]
	v_mfma_f32_16x16x32_bf16 v[4:7], v[158:161], v[206:209], v[4:7]
	v_mfma_f32_16x16x32_bf16 v[0:3], v[166:169], v[206:209], v[0:3]
	v_mfma_f32_16x16x32_bf16 v[52:55], v[162:165], v[186:189], v[52:55]
	v_mfma_f32_16x16x32_bf16 v[48:51], v[170:173], v[186:189], v[48:51]
	s_add_u32 s66, s66, 0x100
	v_mfma_f32_16x16x32_bf16 v[36:39], v[162:165], v[194:197], v[36:39]
	s_addc_u32 s67, s67, 0
	v_mfma_f32_16x16x32_bf16 v[32:35], v[170:173], v[194:197], v[32:35]
	s_add_u32 s68, s68, 0x100
	v_mfma_f32_16x16x32_bf16 v[20:23], v[162:165], v[202:205], v[20:23]
	s_addc_u32 s69, s69, 0
	v_mfma_f32_16x16x32_bf16 v[16:19], v[170:173], v[202:205], v[16:19]
	s_cmp_ge_i32 s81, s31
	v_mfma_f32_16x16x32_bf16 v[4:7], v[162:165], v[210:213], v[4:7]
	s_mov_b32 s4, s81
	v_mfma_f32_16x16x32_bf16 v[0:3], v[170:173], v[210:213], v[0:3]
	s_setprio 0
	s_barrier
	s_cbranch_scc0 .LBB0_592

; #define PG8_STAGE(bufoff, gbase, voff) do { _Pragma("unroll") for (int _i = 0; _i < 2; ++_i) \
;         __builtin_amdgcn_global_load_lds((const unsigned*)((const char*)(gbase) + (voff)[_i]), (PG8_LAS unsigned*)(lds + (bufoff) + ldsw + _i * 8192), 16, 0, 0); } while (0)
; #define PG8_LDA(dst, b, h) do { _Pragma("unroll") for (int m = 0; m < 4; ++m) _Pragma("unroll") for (int k = 0; k < 2; ++k) dst[m][k] = *(const PG8_LAS bf16x8*)(lds + PG8_SA(b, h) + aoff + m * 2048 + k * 1024); } while (0)
; #define PG8_LDB(dst, b, h) do { _Pragma("unroll") for (int n = 0; n < 2; ++n) _Pragma("unroll") for (int k = 0; k < 2; ++k) dst[n][k] = *(const PG8_LAS bf16x8*)(lds + PG8_SB(b, h) + boff + n * 2048 + k * 1024); } while (0)
; #define PG8_MMA(ai, bj, At, Bt) do { __builtin_amdgcn_s_setprio(1); _Pragma("unroll") for (int m = 0; m < 4; ++m) _Pragma("unroll") for (int n = 0; n < 2; ++n) _Pragma("unroll") for (int k = 0; k < 2; ++k) \
;         acc[ai][bj][m][n] = __builtin_amdgcn_mfma_f32_16x16x32_bf16(Bt[n][k], At[m][k], acc[ai][bj][m][n], 0, 0, 0); __builtin_amdgcn_s_setprio(0); } while (0)
; #define PG8_WAIT_V(n) asm volatile("s_waitcnt vmcnt(" #n ")" ::: "memory")
; #define PG8_WAIT_L(n) asm volatile("s_waitcnt lgkmcnt(" #n ")" ::: "memory")
; #define PG8_BAR __builtin_amdgcn_s_barrier()
; #define PG8_SCHED __builtin_amdgcn_sched_barrier(0)
; template <class Epi, class Sched, bool ALIGN_EPI = false, bool SP2 = false>
; __device__ __forceinline__ void gemm_phase(PG8_LAS unsigned char* lds, const Gemm g, const Sched& S, const Epi& E) {
;     ...
;             const bool last = (t == nt - 2);
;             const char* a1 = cA + (size_t)(t + 1) * kstep;
;             const char* a2 = last ? nA : cA + (size_t)(t + 2) * kstep; const char* b2 = last ? nB : cB + (size_t)(t + 2) * kstep;
;             const char* a3 = a2 + kstep; const char* b3 = b2 + kstep;
;             if (last && has_next) S.a_ready(nxt);
;             if constexpr (SP2) {
;             PG8_LDB(B0, 0, 0); PG8_LDB(B1, 0, 1); PG8_SCHED; PG8_LDA(At, 0, 0); PG8_STAGE(PG8_SA(1, 1), a1 + hstep, voffA);
;             PG8_WAIT_V(8); PG8_WAIT_L(0); PG8_BAR; PG8_MMA(0, 0, At, B0); PG8_MMA(0, 1, At, B1); PG8_BAR; PG8_SCHED;
;             PG8_LDA(At, 0, 1); PG8_STAGE(PG8_SB(0, 0), b2, voffB); PG8_STAGE(PG8_SB(0, 1), b2 + hstep, voffB); PG8_STAGE(PG8_SA(0, 0), a2, voffA);
.LBB0_718:
	s_add_u32 s28, vcc_lo, 0xfffc0080
	s_addc_u32 s38, vcc_hi, -1
	s_add_i32 s39, 0, 0x10000
	s_cmp_eq_u32 s80, 12
	s_cselect_b32 s67, s41, s38
	s_cselect_b32 s66, s76, s28
	v_add_u32_e32 v138, s39, v142
	s_cselect_b32 s65, s37, s79
	s_cselect_b32 s64, s77, s78
	s_add_i32 s28, 0, 0x14000
	ds_read_b128 v[144:147], v138
	ds_read_b128 v[148:151], v138 offset:1024
	ds_read_b128 v[152:155], v138 offset:2048
	ds_read_b128 v[156:159], v138 offset:3072
	v_add_u32_e32 v138, s28, v142
	ds_read_b128 v[160:163], v138
	ds_read_b128 v[164:167], v138 offset:1024
	ds_read_b128 v[168:171], v138 offset:2048
	ds_read_b128 v[172:175], v138 offset:3072
	v_lshl_add_u64 v[138:139], vcc, 0, v[134:135]
	s_add_i32 m0, s30, 0xc000
	ds_read_b128 v[182:185], v143
	ds_read_b128 v[186:189], v143 offset:1024
	ds_read_b128 v[190:193], v143 offset:2048
	ds_read_b128 v[194:197], v143 offset:3072
	ds_read_b128 v[198:201], v143 offset:4096
	ds_read_b128 v[202:205], v143 offset:5120
	ds_read_b128 v[206:209], v143 offset:6144
	ds_read_b128 v[210:213], v143 offset:7168
	global_load_lds_dwordx4 v[138:139], off
	v_lshl_add_u64 v[138:139], vcc, 0, v[136:137]
	s_add_i32 m0, s30, 0xe000
	s_nop 0
	global_load_lds_dwordx4 v[138:139], off
	s_waitcnt vmcnt(8)
	s_waitcnt lgkmcnt(0)
	s_barrier
	s_setprio 1
	s_waitcnt lgkmcnt(0)
	v_mfma_f32_16x16x32_bf16 v[124:127], v[144:147], v[182:185], v[124:127]
	v_mfma_f32_16x16x32_bf16 v[120:123], v[152:155], v[182:185], v[120:123]
	v_mfma_f32_16x16x32_bf16 v[108:111], v[144:147], v[190:193], v[108:111]
	v_mfma_f32_16x16x32_bf16 v[104:107], v[152:155], v[190:193], v[104:107]
	v_mfma_f32_16x16x32_bf16 v[92:95], v[144:147], v[198:201], v[92:95]
	v_mfma_f32_16x16x32_bf16 v[88:91], v[152:155], v[198:201], v[88:91]
	v_mfma_f32_16x16x32_bf16 v[76:79], v[144:147], v[206:209], v[76:79]
	v_mfma_f32_16x16x32_bf16 v[72:75], v[152:155], v[206:209], v[72:75]
	v_mfma_f32_16x16x32_bf16 v[124:127], v[148:151], v[186:189], v[124:127]
	v_mfma_f32_16x16x32_bf16 v[120:123], v[156:159], v[186:189], v[120:123]
	v_mfma_f32_16x16x32_bf16 v[108:111], v[148:151], v[194:197], v[108:111]
	v_mfma_f32_16x16x32_bf16 v[104:107], v[156:159], v[194:197], v[104:107]
	v_mfma_f32_16x16x32_bf16 v[92:95], v[148:151], v[202:205], v[92:95]
	v_mfma_f32_16x16x32_bf16 v[88:91], v[156:159], v[202:205], v[88:91]
	v_mfma_f32_16x16x32_bf16 v[76:79], v[148:151], v[210:213], v[76:79]
	v_mfma_f32_16x16x32_bf16 v[72:75], v[156:159], v[210:213], v[72:75]
	v_mfma_f32_16x16x32_bf16 v[116:119], v[160:163], v[182:185], v[116:119]
	v_mfma_f32_16x16x32_bf16 v[112:115], v[168:171], v[182:185], v[112:115]
	v_mfma_f32_16x16x32_bf16 v[100:103], v[160:163], v[190:193], v[100:103]
	v_mfma_f32_16x16x32_bf16 v[96:99], v[168:171], v[190:193], v[96:99]
	v_mfma_f32_16x16x32_bf16 v[84:87], v[160:163], v[198:201], v[84:87]
	v_mfma_f32_16x16x32_bf16 v[80:83], v[168:171], v[198:201], v[80:83]
	v_mfma_f32_16x16x32_bf16 v[68:71], v[160:163], v[206:209], v[68:71]
	v_mfma_f32_16x16x32_bf16 v[64:67], v[168:171], v[206:209], v[64:67]
	v_mfma_f32_16x16x32_bf16 v[116:119], v[164:167], v[186:189], v[116:119]
	v_mfma_f32_16x16x32_bf16 v[112:115], v[172:175], v[186:189], v[112:115]
	v_mfma_f32_16x16x32_bf16 v[100:103], v[164:167], v[194:197], v[100:103]
	v_mfma_f32_16x16x32_bf16 v[96:99], v[172:175], v[194:197], v[96:99]
	v_mfma_f32_16x16x32_bf16 v[84:87], v[164:167], v[202:205], v[84:87]
	v_mfma_f32_16x16x32_bf16 v[80:83], v[172:175], v[202:205], v[80:83]
	v_mfma_f32_16x16x32_bf16 v[68:71], v[164:167], v[210:213], v[68:71]
	v_mfma_f32_16x16x32_bf16 v[64:67], v[172:175], v[210:213], v[64:67]
	s_setprio 0
	s_barrier
	s_add_i32 s38, s39, s23
	v_lshl_add_u64 v[138:139], s[64:65], 0, v[176:177]
	s_mov_b32 m0, s38
	ds_read_b128 v[182:185], v143 offset:16384
	ds_read_b128 v[186:189], v143 offset:17408
	ds_read_b128 v[190:193], v143 offset:18432
	ds_read_b128 v[194:197], v143 offset:19456
	ds_read_b128 v[198:201], v143 offset:20480
	ds_read_b128 v[202:205], v143 offset:21504
	ds_read_b128 v[206:209], v143 offset:22528
	ds_read_b128 v[210:213], v143 offset:23552
	global_load_lds_dwordx4 v[138:139], off
	s_add_i32 m0, s38, 0x2000
	s_add_u32 s38, s64, 0x40000
	v_lshl_add_u64 v[214:215], s[64:65], 0, v[128:129]
	s_addc_u32 s39, s65, 0
	s_add_i32 s28, s28, s23
	global_load_lds_dwordx4 v[214:215], off
	v_lshl_add_u64 v[216:217], s[38:39], 0, v[176:177]
	s_mov_b32 m0, s28
	v_lshl_add_u64 v[218:219], s[66:67], 0, v[130:131]
	global_load_lds_dwordx4 v[216:217], off
	v_lshl_add_u64 v[216:217], s[38:39], 0, v[128:129]
	s_add_i32 m0, s28, 0x2000
	s_nop 0
	global_load_lds_dwordx4 v[216:217], off
	v_lshl_add_u64 v[216:217], s[66:67], 0, v[132:133]
	s_mov_b32 m0, s30
	s_nop 0
	global_load_lds_dwordx4 v[216:217], off
	s_mov_b32 m0, s31
	s_nop 0
	global_load_lds_dwordx4 v[218:219], off
	s_waitcnt vmcnt(8)
	s_waitcnt lgkmcnt(0)
	s_barrier
; #define PG8_STAGE(bufoff, gbase, voff) do { _Pragma("unroll") for (int _i = 0; _i < 2; ++_i) \
;         __builtin_amdgcn_global_load_lds((const unsigned*)((const char*)(gbase) + (voff)[_i]), (PG8_LAS unsigned*)(lds + (bufoff) + ldsw + _i * 8192), 16, 0, 0); } while (0)
; #define PG8_LDA(dst, b, h) do { _Pragma("unroll") for (int m = 0; m < 4; ++m) _Pragma("unroll") for (int k = 0; k < 2; ++k) dst[m][k] = *(const PG8_LAS bf16x8*)(lds + PG8_SA(b, h) + aoff + m * 2048 + k * 1024); } while (0)
; #define PG8_LDB(dst, b, h) do { _Pragma("unroll") for (int n = 0; n < 2; ++n) _Pragma("unroll") for (int k = 0; k < 2; ++k) dst[n][k] = *(const PG8_LAS bf16x8*)(lds + PG8_SB(b, h) + boff + n * 2048 + k * 1024); } while (0)
; #define PG8_MMA(ai, bj, At, Bt) do { __builtin_amdgcn_s_setprio(1); _Pragma("unroll") for (int m = 0; m < 4; ++m) _Pragma("unroll") for (int n = 0; n < 2; ++n) _Pragma("unroll") for (int k = 0; k < 2; ++k) \
;         acc[ai][bj][m][n] = __builtin_amdgcn_mfma_f32_16x16x32_bf16(Bt[n][k], At[m][k], acc[ai][bj][m][n], 0, 0, 0); __builtin_amdgcn_s_setprio(0); } while (0)
; #define PG8_WAIT_V(n) asm volatile("s_waitcnt vmcnt(" #n ")" ::: "memory")
; #define PG8_WAIT_L(n) asm volatile("s_waitcnt lgkmcnt(" #n ")" ::: "memory")
; #define PG8_BAR __builtin_amdgcn_s_barrier()
; #define PG8_SCHED __builtin_amdgcn_sched_barrier(0)
; template <class Epi, class Sched, bool ALIGN_EPI = false, bool SP2 = false>
; __device__ __forceinline__ void gemm_phase(PG8_LAS unsigned char* lds, const Gemm g, const Sched& S, const Epi& E) {
;     ...
;             PG8_WAIT_V(8); PG8_WAIT_L(0); PG8_BAR; PG8_MMA(1, 0, At, B0); PG8_MMA(1, 1, At, B1); PG8_BAR; PG8_SCHED;
;             PG8_LDB(B0, 1, 0); PG8_LDB(B1, 1, 1); PG8_SCHED; PG8_LDA(At, 1, 0); PG8_STAGE(PG8_SA(0, 1), a2 + hstep, voffA);
;             PG8_WAIT_V(8); PG8_WAIT_L(0); PG8_BAR; PG8_MMA(0, 0, At, B0); PG8_MMA(0, 1, At, B1); PG8_BAR; PG8_SCHED;
	s_setprio 1
	s_waitcnt lgkmcnt(0)
	v_mfma_f32_16x16x32_bf16 v[60:63], v[144:147], v[182:185], v[60:63]
	v_mfma_f32_16x16x32_bf16 v[56:59], v[152:155], v[182:185], v[56:59]
	v_mfma_f32_16x16x32_bf16 v[44:47], v[144:147], v[190:193], v[44:47]
	v_mfma_f32_16x16x32_bf16 v[40:43], v[152:155], v[190:193], v[40:43]
	v_mfma_f32_16x16x32_bf16 v[28:31], v[144:147], v[198:201], v[28:31]
	v_mfma_f32_16x16x32_bf16 v[24:27], v[152:155], v[198:201], v[24:27]
	v_mfma_f32_16x16x32_bf16 v[12:15], v[144:147], v[206:209], v[12:15]
	v_mfma_f32_16x16x32_bf16 v[8:11], v[152:155], v[206:209], v[8:11]
	v_mfma_f32_16x16x32_bf16 v[60:63], v[148:151], v[186:189], v[60:63]
	v_mfma_f32_16x16x32_bf16 v[56:59], v[156:159], v[186:189], v[56:59]
	v_mfma_f32_16x16x32_bf16 v[44:47], v[148:151], v[194:197], v[44:47]
	v_mfma_f32_16x16x32_bf16 v[40:43], v[156:159], v[194:197], v[40:43]
	v_mfma_f32_16x16x32_bf16 v[28:31], v[148:151], v[202:205], v[28:31]
	v_mfma_f32_16x16x32_bf16 v[24:27], v[156:159], v[202:205], v[24:27]
	v_mfma_f32_16x16x32_bf16 v[12:15], v[148:151], v[210:213], v[12:15]
	v_mfma_f32_16x16x32_bf16 v[8:11], v[156:159], v[210:213], v[8:11]
	v_mfma_f32_16x16x32_bf16 v[52:55], v[160:163], v[182:185], v[52:55]
	v_mfma_f32_16x16x32_bf16 v[48:51], v[168:171], v[182:185], v[48:51]
	v_mfma_f32_16x16x32_bf16 v[36:39], v[160:163], v[190:193], v[36:39]
	v_mfma_f32_16x16x32_bf16 v[32:35], v[168:171], v[190:193], v[32:35]
	v_mfma_f32_16x16x32_bf16 v[20:23], v[160:163], v[198:201], v[20:23]
	v_mfma_f32_16x16x32_bf16 v[16:19], v[168:171], v[198:201], v[16:19]
	v_mfma_f32_16x16x32_bf16 v[4:7], v[160:163], v[206:209], v[4:7]
	v_mfma_f32_16x16x32_bf16 v[0:3], v[168:171], v[206:209], v[0:3]
	v_mfma_f32_16x16x32_bf16 v[52:55], v[164:167], v[186:189], v[52:55]
	v_mfma_f32_16x16x32_bf16 v[48:51], v[172:175], v[186:189], v[48:51]
	v_mfma_f32_16x16x32_bf16 v[36:39], v[164:167], v[194:197], v[36:39]
	v_mfma_f32_16x16x32_bf16 v[32:35], v[172:175], v[194:197], v[32:35]
	v_mfma_f32_16x16x32_bf16 v[20:23], v[164:167], v[202:205], v[20:23]
	v_mfma_f32_16x16x32_bf16 v[16:19], v[172:175], v[202:205], v[16:19]
	v_mfma_f32_16x16x32_bf16 v[4:7], v[164:167], v[210:213], v[4:7]
	v_mfma_f32_16x16x32_bf16 v[0:3], v[172:175], v[210:213], v[0:3]
	s_setprio 0
	s_barrier
	s_add_i32 s28, 0, 0x18000
	s_add_i32 s48, 0, 0x1c000
	v_add_u32_e32 v156, s28, v142
	v_add_u32_e32 v172, s48, v142
	ds_read_b128 v[144:147], v156
	ds_read_b128 v[148:151], v156 offset:1024
	ds_read_b128 v[152:155], v156 offset:2048
	ds_read_b128 v[156:159], v156 offset:3072
	ds_read_b128 v[160:163], v172
	ds_read_b128 v[164:167], v172 offset:1024
	ds_read_b128 v[168:171], v172 offset:2048
	ds_read_b128 v[172:175], v172 offset:3072
	s_add_u32 s38, s66, 0x40000
	s_addc_u32 s39, s67, 0
	s_mov_b32 m0, s63
	v_lshl_add_u64 v[220:221], s[38:39], 0, v[132:133]
	ds_read_b128 v[182:185], v143 offset:32768
	ds_read_b128 v[186:189], v143 offset:33792
	ds_read_b128 v[190:193], v143 offset:34816
	ds_read_b128 v[194:197], v143 offset:35840
	ds_read_b128 v[198:201], v143 offset:36864
	ds_read_b128 v[202:205], v143 offset:37888
	ds_read_b128 v[206:209], v143 offset:38912
	ds_read_b128 v[210:213], v143 offset:39936
	global_load_lds_dwordx4 v[220:221], off
	v_lshl_add_u64 v[220:221], s[38:39], 0, v[130:131]
	s_mov_b32 m0, s69
	s_nop 0
	global_load_lds_dwordx4 v[220:221], off
	s_waitcnt vmcnt(8)
	s_waitcnt lgkmcnt(0)
	s_barrier
	s_setprio 1
	s_waitcnt lgkmcnt(0)
	v_mfma_f32_16x16x32_bf16 v[124:127], v[144:147], v[182:185], v[124:127]
	v_mfma_f32_16x16x32_bf16 v[120:123], v[152:155], v[182:185], v[120:123]
	v_mfma_f32_16x16x32_bf16 v[108:111], v[144:147], v[190:193], v[108:111]
	v_mfma_f32_16x16x32_bf16 v[104:107], v[152:155], v[190:193], v[104:107]
	v_mfma_f32_16x16x32_bf16 v[92:95], v[144:147], v[198:201], v[92:95]
	v_mfma_f32_16x16x32_bf16 v[88:91], v[152:155], v[198:201], v[88:91]
	v_mfma_f32_16x16x32_bf16 v[76:79], v[144:147], v[206:209], v[76:79]
	v_mfma_f32_16x16x32_bf16 v[72:75], v[152:155], v[206:209], v[72:75]
	v_mfma_f32_16x16x32_bf16 v[124:127], v[148:151], v[186:189], v[124:127]
	v_mfma_f32_16x16x32_bf16 v[120:123], v[156:159], v[186:189], v[120:123]
	v_mfma_f32_16x16x32_bf16 v[108:111], v[148:151], v[194:197], v[108:111]
	v_mfma_f32_16x16x32_bf16 v[104:107], v[156:159], v[194:197], v[104:107]
	v_mfma_f32_16x16x32_bf16 v[92:95], v[148:151], v[202:205], v[92:95]
	v_mfma_f32_16x16x32_bf16 v[88:91], v[156:159], v[202:205], v[88:91]
	v_mfma_f32_16x16x32_bf16 v[76:79], v[148:151], v[210:213], v[76:79]
	v_mfma_f32_16x16x32_bf16 v[72:75], v[156:159], v[210:213], v[72:75]
	v_mfma_f32_16x16x32_bf16 v[116:119], v[160:163], v[182:185], v[116:119]
	v_mfma_f32_16x16x32_bf16 v[112:115], v[168:171], v[182:185], v[112:115]
	v_mfma_f32_16x16x32_bf16 v[100:103], v[160:163], v[190:193], v[100:103]
	v_mfma_f32_16x16x32_bf16 v[96:99], v[168:171], v[190:193], v[96:99]
	v_mfma_f32_16x16x32_bf16 v[84:87], v[160:163], v[198:201], v[84:87]
	v_mfma_f32_16x16x32_bf16 v[80:83], v[168:171], v[198:201], v[80:83]
	v_mfma_f32_16x16x32_bf16 v[68:71], v[160:163], v[206:209], v[68:71]
	v_mfma_f32_16x16x32_bf16 v[64:67], v[168:171], v[206:209], v[64:67]
	v_mfma_f32_16x16x32_bf16 v[116:119], v[164:167], v[186:189], v[116:119]
	v_mfma_f32_16x16x32_bf16 v[112:115], v[172:175], v[186:189], v[112:115]
	v_mfma_f32_16x16x32_bf16 v[100:103], v[164:167], v[194:197], v[100:103]
	v_mfma_f32_16x16x32_bf16 v[96:99], v[172:175], v[194:197], v[96:99]
	v_mfma_f32_16x16x32_bf16 v[84:87], v[164:167], v[202:205], v[84:87]
	v_mfma_f32_16x16x32_bf16 v[80:83], v[172:175], v[202:205], v[80:83]
	v_mfma_f32_16x16x32_bf16 v[68:71], v[164:167], v[210:213], v[68:71]
	v_mfma_f32_16x16x32_bf16 v[64:67], v[172:175], v[210:213], v[64:67]
	s_setprio 0
	s_barrier
; #define PG8_STAGE(bufoff, gbase, voff) do { _Pragma("unroll") for (int _i = 0; _i < 2; ++_i) \
;         __builtin_amdgcn_global_load_lds((const unsigned*)((const char*)(gbase) + (voff)[_i]), (PG8_LAS unsigned*)(lds + (bufoff) + ldsw + _i * 8192), 16, 0, 0); } while (0)
; #define PG8_LDA(dst, b, h) do { _Pragma("unroll") for (int m = 0; m < 4; ++m) _Pragma("unroll") for (int k = 0; k < 2; ++k) dst[m][k] = *(const PG8_LAS bf16x8*)(lds + PG8_SA(b, h) + aoff + m * 2048 + k * 1024); } while (0)
; #define PG8_MMA(ai, bj, At, Bt) do { __builtin_amdgcn_s_setprio(1); _Pragma("unroll") for (int m = 0; m < 4; ++m) _Pragma("unroll") for (int n = 0; n < 2; ++n) _Pragma("unroll") for (int k = 0; k < 2; ++k) \
;         acc[ai][bj][m][n] = __builtin_amdgcn_mfma_f32_16x16x32_bf16(Bt[n][k], At[m][k], acc[ai][bj][m][n], 0, 0, 0); __builtin_amdgcn_s_setprio(0); } while (0)
; #define PG8_WAIT_V(n) asm volatile("s_waitcnt vmcnt(" #n ")" ::: "memory")
; #define PG8_WAIT_L(n) asm volatile("s_waitcnt lgkmcnt(" #n ")" ::: "memory")
; #define PG8_BAR __builtin_amdgcn_s_barrier()
; #define PG8_SCHED __builtin_amdgcn_sched_barrier(0)
; template <class Epi, class Sched, bool ALIGN_EPI = false, bool SP2 = false>
; __device__ __forceinline__ void gemm_phase(PG8_LAS unsigned char* lds, const Gemm g, const Sched& S, const Epi& E) {
;     ...
;             PG8_LDA(At, 1, 1); PG8_STAGE(PG8_SB(1, 0), b3, voffB); PG8_STAGE(PG8_SB(1, 1), b3 + hstep, voffB); PG8_STAGE(PG8_SA(1, 0), a3, voffA);
;             PG8_WAIT_V(8); PG8_WAIT_L(0); PG8_BAR; PG8_MMA(1, 0, At, B0); PG8_MMA(1, 1, At, B1); PG8_BAR; PG8_SCHED;
	s_add_i32 s28, s28, s23
	v_lshl_add_u64 v[138:139], v[138:139], 0, s[44:45]
	s_mov_b32 m0, s28
	ds_read_b128 v[182:185], v143 offset:49152
	ds_read_b128 v[186:189], v143 offset:50176
	ds_read_b128 v[190:193], v143 offset:51200
	ds_read_b128 v[194:197], v143 offset:52224
	ds_read_b128 v[198:201], v143 offset:53248
	ds_read_b128 v[202:205], v143 offset:54272
	ds_read_b128 v[206:209], v143 offset:55296
	ds_read_b128 v[210:213], v143 offset:56320
	global_load_lds_dwordx4 v[138:139], off
	s_add_i32 m0, s28, 0x2000
	s_add_u32 s38, s64, 0x40080
	v_lshl_add_u64 v[138:139], v[214:215], 0, s[44:45]
	s_addc_u32 s39, s65, 0
	s_add_i32 s28, s48, s23
	global_load_lds_dwordx4 v[138:139], off
	v_lshl_add_u64 v[138:139], s[38:39], 0, v[176:177]
	s_mov_b32 m0, s28
	s_nop 0
	global_load_lds_dwordx4 v[138:139], off
	v_lshl_add_u64 v[138:139], s[38:39], 0, v[128:129]
	s_add_i32 m0, s28, 0x2000
	s_nop 0
	global_load_lds_dwordx4 v[138:139], off
	v_lshl_add_u64 v[138:139], v[216:217], 0, s[44:45]
	s_mov_b32 m0, s73
	s_nop 0
	global_load_lds_dwordx4 v[138:139], off
	v_lshl_add_u64 v[138:139], v[218:219], 0, s[44:45]
	s_mov_b32 m0, s74
	s_nop 0
	global_load_lds_dwordx4 v[138:139], off
	s_waitcnt vmcnt(8)
	s_waitcnt lgkmcnt(0)
	s_barrier
	s_setprio 1
	s_waitcnt lgkmcnt(0)
	v_mfma_f32_16x16x32_bf16 v[60:63], v[144:147], v[182:185], v[60:63]
	v_mfma_f32_16x16x32_bf16 v[56:59], v[152:155], v[182:185], v[56:59]
	v_mfma_f32_16x16x32_bf16 v[44:47], v[144:147], v[190:193], v[44:47]
	v_mfma_f32_16x16x32_bf16 v[40:43], v[152:155], v[190:193], v[40:43]
	v_mfma_f32_16x16x32_bf16 v[28:31], v[144:147], v[198:201], v[28:31]
	v_mfma_f32_16x16x32_bf16 v[24:27], v[152:155], v[198:201], v[24:27]
	v_mfma_f32_16x16x32_bf16 v[12:15], v[144:147], v[206:209], v[12:15]
	v_mfma_f32_16x16x32_bf16 v[8:11], v[152:155], v[206:209], v[8:11]
	v_mfma_f32_16x16x32_bf16 v[60:63], v[148:151], v[186:189], v[60:63]
	v_mfma_f32_16x16x32_bf16 v[56:59], v[156:159], v[186:189], v[56:59]
	v_mfma_f32_16x16x32_bf16 v[44:47], v[148:151], v[194:197], v[44:47]
	v_mfma_f32_16x16x32_bf16 v[40:43], v[156:159], v[194:197], v[40:43]
	v_mfma_f32_16x16x32_bf16 v[28:31], v[148:151], v[202:205], v[28:31]
	v_mfma_f32_16x16x32_bf16 v[24:27], v[156:159], v[202:205], v[24:27]
	v_mfma_f32_16x16x32_bf16 v[12:15], v[148:151], v[210:213], v[12:15]
	v_mfma_f32_16x16x32_bf16 v[8:11], v[156:159], v[210:213], v[8:11]
	v_mfma_f32_16x16x32_bf16 v[52:55], v[160:163], v[182:185], v[52:55]
	v_mfma_f32_16x16x32_bf16 v[48:51], v[168:171], v[182:185], v[48:51]
	v_mfma_f32_16x16x32_bf16 v[36:39], v[160:163], v[190:193], v[36:39]
	v_mfma_f32_16x16x32_bf16 v[32:35], v[168:171], v[190:193], v[32:35]
	v_mfma_f32_16x16x32_bf16 v[20:23], v[160:163], v[198:201], v[20:23]
	v_mfma_f32_16x16x32_bf16 v[16:19], v[168:171], v[198:201], v[16:19]
	v_mfma_f32_16x16x32_bf16 v[4:7], v[160:163], v[206:209], v[4:7]
	v_mfma_f32_16x16x32_bf16 v[0:3], v[168:171], v[206:209], v[0:3]
	v_mfma_f32_16x16x32_bf16 v[52:55], v[164:167], v[186:189], v[52:55]
	v_mfma_f32_16x16x32_bf16 v[48:51], v[172:175], v[186:189], v[48:51]
	s_add_i32 s80, s80, 2
	v_mfma_f32_16x16x32_bf16 v[36:39], v[164:167], v[194:197], v[36:39]
	s_add_u32 vcc_lo, vcc_lo, 0x100
	v_mfma_f32_16x16x32_bf16 v[32:35], v[172:175], v[194:197], v[32:35]
	s_addc_u32 vcc_hi, vcc_hi, 0
	v_mfma_f32_16x16x32_bf16 v[20:23], v[164:167], v[202:205], v[20:23]
	s_add_u32 s78, s78, 0x100
	v_mfma_f32_16x16x32_bf16 v[16:19], v[172:175], v[202:205], v[16:19]
	s_addc_u32 s79, s79, 0
	v_mfma_f32_16x16x32_bf16 v[4:7], v[164:167], v[210:213], v[4:7]
	s_cmp_gt_u32 s80, 13
	v_mfma_f32_16x16x32_bf16 v[0:3], v[172:175], v[210:213], v[0:3]
	s_setprio 0
	s_barrier
	s_cbranch_scc0 .LBB0_718

; #define PG8_STAGE(bufoff, gbase, voff) do { _Pragma("unroll") for (int _i = 0; _i < 2; ++_i) \
;         __builtin_amdgcn_global_load_lds((const unsigned*)((const char*)(gbase) + (voff)[_i]), (PG8_LAS unsigned*)(lds + (bufoff) + ldsw + _i * 8192), 16, 0, 0); } while (0)
; #define PG8_LDA(dst, b, h) do { _Pragma("unroll") for (int m = 0; m < 4; ++m) _Pragma("unroll") for (int k = 0; k < 2; ++k) dst[m][k] = *(const PG8_LAS bf16x8*)(lds + PG8_SA(b, h) + aoff + m * 2048 + k * 1024); } while (0)
; #define PG8_LDB(dst, b, h) do { _Pragma("unroll") for (int n = 0; n < 2; ++n) _Pragma("unroll") for (int k = 0; k < 2; ++k) dst[n][k] = *(const PG8_LAS bf16x8*)(lds + PG8_SB(b, h) + boff + n * 2048 + k * 1024); } while (0)
; #define PG8_MMA(ai, bj, At, Bt) do { __builtin_amdgcn_s_setprio(1); _Pragma("unroll") for (int m = 0; m < 4; ++m) _Pragma("unroll") for (int n = 0; n < 2; ++n) _Pragma("unroll") for (int k = 0; k < 2; ++k) \
;         acc[ai][bj][m][n] = __builtin_amdgcn_mfma_f32_16x16x32_bf16(Bt[n][k], At[m][k], acc[ai][bj][m][n], 0, 0, 0); __builtin_amdgcn_s_setprio(0); } while (0)
; #define PG8_WAIT_V(n) asm volatile("s_waitcnt vmcnt(" #n ")" ::: "memory")
; #define PG8_WAIT_L(n) asm volatile("s_waitcnt lgkmcnt(" #n ")" ::: "memory")
; template <class Epi, class Sched, bool ALIGN_EPI = false, bool SP2 = false>
; __device__ __forceinline__ void gemm_phase(PG8_LAS unsigned char* lds, const Gemm g, const Sched& S, const Epi& E) {
;     ...
;             if (last && has_next) S.a_ready(nxt);
;             if constexpr (SP2) {
;             PG8_LDB(B0, 0, 0); PG8_LDB(B1, 0, 1); PG8_SCHED; PG8_LDA(At, 0, 0); PG8_STAGE(PG8_SA(1, 1), a1 + hstep, voffA);
;             PG8_WAIT_V(8); PG8_WAIT_L(0); PG8_BAR; PG8_MMA(0, 0, At, B0); PG8_MMA(0, 1, At, B1); PG8_BAR; PG8_SCHED;
;             PG8_LDA(At, 0, 1); PG8_STAGE(PG8_SB(0, 0), b2, voffB); PG8_STAGE(PG8_SB(0, 1), b2 + hstep, voffB); PG8_STAGE(PG8_SA(0, 0), a2, voffA);
;             PG8_WAIT_V(8); PG8_WAIT_L(0); PG8_BAR; PG8_MMA(1, 0, At, B0); PG8_MMA(1, 1, At, B1); PG8_BAR; PG8_SCHED;
;     ...
; #pragma unroll
;         for (int a = 0; a < 2; ++a)
; #pragma unroll
;             for (int b = 0; b < 2; ++b)
; #pragma unroll
;                 for (int m = 0; m < 4; ++m)
; #pragma unroll
;                     for (int n = 0; n < 2; ++n) acc[a][b][m][n] = (f32x4){0.f, 0.f, 0.f, 0.f};
;         cur = nxt; cA = nA; cB = nB; ++ui;
.Lg3_peel:
	s_add_u32 s28, vcc_lo, 0xfffc0080
	s_addc_u32 s38, vcc_hi, -1
	s_add_i32 s39, 0, 0x10000
	s_cmp_eq_u32 s80, 12
	s_cselect_b32 s67, s41, s38
	s_cselect_b32 s66, s76, s28
	v_add_u32_e32 v138, s39, v142
	s_cselect_b32 s65, s37, s79
	s_cselect_b32 s64, s77, s78
	s_add_i32 s28, 0, 0x14000
	ds_read_b128 v[144:147], v138
	ds_read_b128 v[148:151], v138 offset:1024
	ds_read_b128 v[152:155], v138 offset:2048
	ds_read_b128 v[156:159], v138 offset:3072
	v_add_u32_e32 v138, s28, v142
	ds_read_b128 v[160:163], v138
	ds_read_b128 v[164:167], v138 offset:1024
	ds_read_b128 v[168:171], v138 offset:2048
	ds_read_b128 v[172:175], v138 offset:3072
	v_lshl_add_u64 v[138:139], vcc, 0, v[134:135]
	s_add_i32 m0, s30, 0xc000
	ds_read_b128 v[182:185], v143
	ds_read_b128 v[186:189], v143 offset:1024
	ds_read_b128 v[190:193], v143 offset:2048
	ds_read_b128 v[194:197], v143 offset:3072
	ds_read_b128 v[198:201], v143 offset:4096
	ds_read_b128 v[202:205], v143 offset:5120
	ds_read_b128 v[206:209], v143 offset:6144
	ds_read_b128 v[210:213], v143 offset:7168
	global_load_lds_dwordx4 v[138:139], off
	v_lshl_add_u64 v[138:139], vcc, 0, v[136:137]
	s_add_i32 m0, s30, 0xe000
	s_nop 0
	global_load_lds_dwordx4 v[138:139], off
	s_waitcnt vmcnt(24)
	s_waitcnt lgkmcnt(0)
	s_barrier
	s_setprio 1
	s_waitcnt lgkmcnt(0)
	v_mfma_f32_16x16x32_bf16 v[124:127], v[144:147], v[182:185], 0
	v_mfma_f32_16x16x32_bf16 v[120:123], v[152:155], v[182:185], 0
	v_mfma_f32_16x16x32_bf16 v[108:111], v[144:147], v[190:193], 0
	v_mfma_f32_16x16x32_bf16 v[104:107], v[152:155], v[190:193], 0
	v_mfma_f32_16x16x32_bf16 v[92:95], v[144:147], v[198:201], 0
	v_mfma_f32_16x16x32_bf16 v[88:91], v[152:155], v[198:201], 0
	v_mfma_f32_16x16x32_bf16 v[76:79], v[144:147], v[206:209], 0
	v_mfma_f32_16x16x32_bf16 v[72:75], v[152:155], v[206:209], 0
	v_mfma_f32_16x16x32_bf16 v[124:127], v[148:151], v[186:189], v[124:127]
	v_mfma_f32_16x16x32_bf16 v[120:123], v[156:159], v[186:189], v[120:123]
	v_mfma_f32_16x16x32_bf16 v[108:111], v[148:151], v[194:197], v[108:111]
	v_mfma_f32_16x16x32_bf16 v[104:107], v[156:159], v[194:197], v[104:107]
	v_mfma_f32_16x16x32_bf16 v[92:95], v[148:151], v[202:205], v[92:95]
	v_mfma_f32_16x16x32_bf16 v[88:91], v[156:159], v[202:205], v[88:91]
	v_mfma_f32_16x16x32_bf16 v[76:79], v[148:151], v[210:213], v[76:79]
	v_mfma_f32_16x16x32_bf16 v[72:75], v[156:159], v[210:213], v[72:75]
	v_mfma_f32_16x16x32_bf16 v[116:119], v[160:163], v[182:185], 0
	v_mfma_f32_16x16x32_bf16 v[112:115], v[168:171], v[182:185], 0
	v_mfma_f32_16x16x32_bf16 v[100:103], v[160:163], v[190:193], 0
	v_mfma_f32_16x16x32_bf16 v[96:99], v[168:171], v[190:193], 0
	v_mfma_f32_16x16x32_bf16 v[84:87], v[160:163], v[198:201], 0
	v_mfma_f32_16x16x32_bf16 v[80:83], v[168:171], v[198:201], 0
	v_mfma_f32_16x16x32_bf16 v[68:71], v[160:163], v[206:209], 0
	v_mfma_f32_16x16x32_bf16 v[64:67], v[168:171], v[206:209], 0
	v_mfma_f32_16x16x32_bf16 v[116:119], v[164:167], v[186:189], v[116:119]
	v_mfma_f32_16x16x32_bf16 v[112:115], v[172:175], v[186:189], v[112:115]
	v_mfma_f32_16x16x32_bf16 v[100:103], v[164:167], v[194:197], v[100:103]
	v_mfma_f32_16x16x32_bf16 v[96:99], v[172:175], v[194:197], v[96:99]
	v_mfma_f32_16x16x32_bf16 v[84:87], v[164:167], v[202:205], v[84:87]
	v_mfma_f32_16x16x32_bf16 v[80:83], v[172:175], v[202:205], v[80:83]
	v_mfma_f32_16x16x32_bf16 v[68:71], v[164:167], v[210:213], v[68:71]
	v_mfma_f32_16x16x32_bf16 v[64:67], v[172:175], v[210:213], v[64:67]
	s_setprio 0
	s_barrier
	s_add_i32 s38, s39, s23
	v_lshl_add_u64 v[138:139], s[64:65], 0, v[176:177]
	s_mov_b32 m0, s38
	ds_read_b128 v[182:185], v143 offset:16384
	ds_read_b128 v[186:189], v143 offset:17408
	ds_read_b128 v[190:193], v143 offset:18432
	ds_read_b128 v[194:197], v143 offset:19456
	ds_read_b128 v[198:201], v143 offset:20480
	ds_read_b128 v[202:205], v143 offset:21504
	ds_read_b128 v[206:209], v143 offset:22528
	ds_read_b128 v[210:213], v143 offset:23552
	global_load_lds_dwordx4 v[138:139], off
	s_add_i32 m0, s38, 0x2000
	s_add_u32 s38, s64, 0x40000
	v_lshl_add_u64 v[214:215], s[64:65], 0, v[128:129]
	s_addc_u32 s39, s65, 0
	s_add_i32 s28, s28, s23
	global_load_lds_dwordx4 v[214:215], off
	v_lshl_add_u64 v[216:217], s[38:39], 0, v[176:177]
	s_mov_b32 m0, s28
	v_lshl_add_u64 v[218:219], s[66:67], 0, v[130:131]
	global_load_lds_dwordx4 v[216:217], off
	v_lshl_add_u64 v[216:217], s[38:39], 0, v[128:129]
	s_add_i32 m0, s28, 0x2000
	s_nop 0
	global_load_lds_dwordx4 v[216:217], off
	v_lshl_add_u64 v[216:217], s[66:67], 0, v[132:133]
	s_mov_b32 m0, s30
	s_nop 0
	global_load_lds_dwordx4 v[216:217], off
	s_mov_b32 m0, s31
	s_nop 0
	global_load_lds_dwordx4 v[218:219], off
	s_waitcnt vmcnt(24)
	s_waitcnt lgkmcnt(0)
	s_barrier
; #define PG8_STAGE(bufoff, gbase, voff) do { _Pragma("unroll") for (int _i = 0; _i < 2; ++_i) \
;         __builtin_amdgcn_global_load_lds((const unsigned*)((const char*)(gbase) + (voff)[_i]), (PG8_LAS unsigned*)(lds + (bufoff) + ldsw + _i * 8192), 16, 0, 0); } while (0)
; #define PG8_LDA(dst, b, h) do { _Pragma("unroll") for (int m = 0; m < 4; ++m) _Pragma("unroll") for (int k = 0; k < 2; ++k) dst[m][k] = *(const PG8_LAS bf16x8*)(lds + PG8_SA(b, h) + aoff + m * 2048 + k * 1024); } while (0)
; #define PG8_LDB(dst, b, h) do { _Pragma("unroll") for (int n = 0; n < 2; ++n) _Pragma("unroll") for (int k = 0; k < 2; ++k) dst[n][k] = *(const PG8_LAS bf16x8*)(lds + PG8_SB(b, h) + boff + n * 2048 + k * 1024); } while (0)
; #define PG8_MMA(ai, bj, At, Bt) do { __builtin_amdgcn_s_setprio(1); _Pragma("unroll") for (int m = 0; m < 4; ++m) _Pragma("unroll") for (int n = 0; n < 2; ++n) _Pragma("unroll") for (int k = 0; k < 2; ++k) \
;         acc[ai][bj][m][n] = __builtin_amdgcn_mfma_f32_16x16x32_bf16(Bt[n][k], At[m][k], acc[ai][bj][m][n], 0, 0, 0); __builtin_amdgcn_s_setprio(0); } while (0)
; #define PG8_WAIT_V(n) asm volatile("s_waitcnt vmcnt(" #n ")" ::: "memory")
; #define PG8_WAIT_L(n) asm volatile("s_waitcnt lgkmcnt(" #n ")" ::: "memory")
; #define PG8_BAR __builtin_amdgcn_s_barrier()
; #define PG8_SCHED __builtin_amdgcn_sched_barrier(0)
; template <class Epi, class Sched, bool ALIGN_EPI = false, bool SP2 = false>
; __device__ __forceinline__ void gemm_phase(PG8_LAS unsigned char* lds, const Gemm g, const Sched& S, const Epi& E) {
;     ...
;             PG8_WAIT_V(8); PG8_WAIT_L(0); PG8_BAR; PG8_MMA(1, 0, At, B0); PG8_MMA(1, 1, At, B1); PG8_BAR; PG8_SCHED;
;             PG8_LDB(B0, 1, 0); PG8_LDB(B1, 1, 1); PG8_SCHED; PG8_LDA(At, 1, 0); PG8_STAGE(PG8_SA(0, 1), a2 + hstep, voffA);
;             PG8_WAIT_V(8); PG8_WAIT_L(0); PG8_BAR; PG8_MMA(0, 0, At, B0); PG8_MMA(0, 1, At, B1); PG8_BAR; PG8_SCHED;
	s_setprio 1
	s_waitcnt lgkmcnt(0)
	v_mfma_f32_16x16x32_bf16 v[60:63], v[144:147], v[182:185], 0
	v_mfma_f32_16x16x32_bf16 v[56:59], v[152:155], v[182:185], 0
	v_mfma_f32_16x16x32_bf16 v[44:47], v[144:147], v[190:193], 0
	v_mfma_f32_16x16x32_bf16 v[40:43], v[152:155], v[190:193], 0
	v_mfma_f32_16x16x32_bf16 v[28:31], v[144:147], v[198:201], 0
	v_mfma_f32_16x16x32_bf16 v[24:27], v[152:155], v[198:201], 0
	v_mfma_f32_16x16x32_bf16 v[12:15], v[144:147], v[206:209], 0
	v_mfma_f32_16x16x32_bf16 v[8:11], v[152:155], v[206:209], 0
	v_mfma_f32_16x16x32_bf16 v[60:63], v[148:151], v[186:189], v[60:63]
	v_mfma_f32_16x16x32_bf16 v[56:59], v[156:159], v[186:189], v[56:59]
	v_mfma_f32_16x16x32_bf16 v[44:47], v[148:151], v[194:197], v[44:47]
	v_mfma_f32_16x16x32_bf16 v[40:43], v[156:159], v[194:197], v[40:43]
	v_mfma_f32_16x16x32_bf16 v[28:31], v[148:151], v[202:205], v[28:31]
	v_mfma_f32_16x16x32_bf16 v[24:27], v[156:159], v[202:205], v[24:27]
	v_mfma_f32_16x16x32_bf16 v[12:15], v[148:151], v[210:213], v[12:15]
	v_mfma_f32_16x16x32_bf16 v[8:11], v[156:159], v[210:213], v[8:11]
	v_mfma_f32_16x16x32_bf16 v[52:55], v[160:163], v[182:185], 0
	v_mfma_f32_16x16x32_bf16 v[48:51], v[168:171], v[182:185], 0
	v_mfma_f32_16x16x32_bf16 v[36:39], v[160:163], v[190:193], 0
	v_mfma_f32_16x16x32_bf16 v[32:35], v[168:171], v[190:193], 0
	v_mfma_f32_16x16x32_bf16 v[20:23], v[160:163], v[198:201], 0
	v_mfma_f32_16x16x32_bf16 v[16:19], v[168:171], v[198:201], 0
	v_mfma_f32_16x16x32_bf16 v[4:7], v[160:163], v[206:209], 0
	v_mfma_f32_16x16x32_bf16 v[0:3], v[168:171], v[206:209], 0
	v_mfma_f32_16x16x32_bf16 v[52:55], v[164:167], v[186:189], v[52:55]
	v_mfma_f32_16x16x32_bf16 v[48:51], v[172:175], v[186:189], v[48:51]
	v_mfma_f32_16x16x32_bf16 v[36:39], v[164:167], v[194:197], v[36:39]
	v_mfma_f32_16x16x32_bf16 v[32:35], v[172:175], v[194:197], v[32:35]
	v_mfma_f32_16x16x32_bf16 v[20:23], v[164:167], v[202:205], v[20:23]
	v_mfma_f32_16x16x32_bf16 v[16:19], v[172:175], v[202:205], v[16:19]
	v_mfma_f32_16x16x32_bf16 v[4:7], v[164:167], v[210:213], v[4:7]
	v_mfma_f32_16x16x32_bf16 v[0:3], v[172:175], v[210:213], v[0:3]
	s_setprio 0
	s_barrier
	s_add_i32 s28, 0, 0x18000
	s_add_i32 s48, 0, 0x1c000
	v_add_u32_e32 v156, s28, v142
	v_add_u32_e32 v172, s48, v142
	ds_read_b128 v[144:147], v156
	ds_read_b128 v[148:151], v156 offset:1024
	ds_read_b128 v[152:155], v156 offset:2048
	ds_read_b128 v[156:159], v156 offset:3072
	ds_read_b128 v[160:163], v172
	ds_read_b128 v[164:167], v172 offset:1024
	ds_read_b128 v[168:171], v172 offset:2048
	ds_read_b128 v[172:175], v172 offset:3072
	s_add_u32 s38, s66, 0x40000
	s_addc_u32 s39, s67, 0
	s_mov_b32 m0, s63
	v_lshl_add_u64 v[220:221], s[38:39], 0, v[132:133]
	ds_read_b128 v[182:185], v143 offset:32768
	ds_read_b128 v[186:189], v143 offset:33792
	ds_read_b128 v[190:193], v143 offset:34816
	ds_read_b128 v[194:197], v143 offset:35840
	ds_read_b128 v[198:201], v143 offset:36864
	ds_read_b128 v[202:205], v143 offset:37888
	ds_read_b128 v[206:209], v143 offset:38912
	ds_read_b128 v[210:213], v143 offset:39936
	global_load_lds_dwordx4 v[220:221], off
	v_lshl_add_u64 v[220:221], s[38:39], 0, v[130:131]
	s_mov_b32 m0, s69
	s_nop 0
	global_load_lds_dwordx4 v[220:221], off
	s_waitcnt vmcnt(8)
	s_waitcnt lgkmcnt(0)
	s_barrier
	s_setprio 1
	s_waitcnt lgkmcnt(0)
	v_mfma_f32_16x16x32_bf16 v[124:127], v[144:147], v[182:185], v[124:127]
	v_mfma_f32_16x16x32_bf16 v[120:123], v[152:155], v[182:185], v[120:123]
	v_mfma_f32_16x16x32_bf16 v[108:111], v[144:147], v[190:193], v[108:111]
	v_mfma_f32_16x16x32_bf16 v[104:107], v[152:155], v[190:193], v[104:107]
	v_mfma_f32_16x16x32_bf16 v[92:95], v[144:147], v[198:201], v[92:95]
	v_mfma_f32_16x16x32_bf16 v[88:91], v[152:155], v[198:201], v[88:91]
	v_mfma_f32_16x16x32_bf16 v[76:79], v[144:147], v[206:209], v[76:79]
	v_mfma_f32_16x16x32_bf16 v[72:75], v[152:155], v[206:209], v[72:75]
	v_mfma_f32_16x16x32_bf16 v[124:127], v[148:151], v[186:189], v[124:127]
	v_mfma_f32_16x16x32_bf16 v[120:123], v[156:159], v[186:189], v[120:123]
	v_mfma_f32_16x16x32_bf16 v[108:111], v[148:151], v[194:197], v[108:111]
	v_mfma_f32_16x16x32_bf16 v[104:107], v[156:159], v[194:197], v[104:107]
	v_mfma_f32_16x16x32_bf16 v[92:95], v[148:151], v[202:205], v[92:95]
	v_mfma_f32_16x16x32_bf16 v[88:91], v[156:159], v[202:205], v[88:91]
	v_mfma_f32_16x16x32_bf16 v[76:79], v[148:151], v[210:213], v[76:79]
	v_mfma_f32_16x16x32_bf16 v[72:75], v[156:159], v[210:213], v[72:75]
	v_mfma_f32_16x16x32_bf16 v[116:119], v[160:163], v[182:185], v[116:119]
	v_mfma_f32_16x16x32_bf16 v[112:115], v[168:171], v[182:185], v[112:115]
	v_mfma_f32_16x16x32_bf16 v[100:103], v[160:163], v[190:193], v[100:103]
	v_mfma_f32_16x16x32_bf16 v[96:99], v[168:171], v[190:193], v[96:99]
	v_mfma_f32_16x16x32_bf16 v[84:87], v[160:163], v[198:201], v[84:87]
	v_mfma_f32_16x16x32_bf16 v[80:83], v[168:171], v[198:201], v[80:83]
	v_mfma_f32_16x16x32_bf16 v[68:71], v[160:163], v[206:209], v[68:71]
	v_mfma_f32_16x16x32_bf16 v[64:67], v[168:171], v[206:209], v[64:67]
	v_mfma_f32_16x16x32_bf16 v[116:119], v[164:167], v[186:189], v[116:119]
	v_mfma_f32_16x16x32_bf16 v[112:115], v[172:175], v[186:189], v[112:115]
	v_mfma_f32_16x16x32_bf16 v[100:103], v[164:167], v[194:197], v[100:103]
	v_mfma_f32_16x16x32_bf16 v[96:99], v[172:175], v[194:197], v[96:99]
	v_mfma_f32_16x16x32_bf16 v[84:87], v[164:167], v[202:205], v[84:87]
	v_mfma_f32_16x16x32_bf16 v[80:83], v[172:175], v[202:205], v[80:83]
	v_mfma_f32_16x16x32_bf16 v[68:71], v[164:167], v[210:213], v[68:71]
	v_mfma_f32_16x16x32_bf16 v[64:67], v[172:175], v[210:213], v[64:67]
	s_setprio 0
	s_barrier
; #define PG8_STAGE(bufoff, gbase, voff) do { _Pragma("unroll") for (int _i = 0; _i < 2; ++_i) \
;         __builtin_amdgcn_global_load_lds((const unsigned*)((const char*)(gbase) + (voff)[_i]), (PG8_LAS unsigned*)(lds + (bufoff) + ldsw + _i * 8192), 16, 0, 0); } while (0)
; #define PG8_LDA(dst, b, h) do { _Pragma("unroll") for (int m = 0; m < 4; ++m) _Pragma("unroll") for (int k = 0; k < 2; ++k) dst[m][k] = *(const PG8_LAS bf16x8*)(lds + PG8_SA(b, h) + aoff + m * 2048 + k * 1024); } while (0)
; #define PG8_MMA(ai, bj, At, Bt) do { __builtin_amdgcn_s_setprio(1); _Pragma("unroll") for (int m = 0; m < 4; ++m) _Pragma("unroll") for (int n = 0; n < 2; ++n) _Pragma("unroll") for (int k = 0; k < 2; ++k) \
;         acc[ai][bj][m][n] = __builtin_amdgcn_mfma_f32_16x16x32_bf16(Bt[n][k], At[m][k], acc[ai][bj][m][n], 0, 0, 0); __builtin_amdgcn_s_setprio(0); } while (0)
; #define PG8_WAIT_V(n) asm volatile("s_waitcnt vmcnt(" #n ")" ::: "memory")
; #define PG8_WAIT_L(n) asm volatile("s_waitcnt lgkmcnt(" #n ")" ::: "memory")
; #define PG8_BAR __builtin_amdgcn_s_barrier()
; #define PG8_SCHED __builtin_amdgcn_sched_barrier(0)
; template <class Epi, class Sched, bool ALIGN_EPI = false, bool SP2 = false>
; __device__ __forceinline__ void gemm_phase(PG8_LAS unsigned char* lds, const Gemm g, const Sched& S, const Epi& E) {
;     ...
;         for (int t = 0; t < nt; t += 2) {
;             const bool last = (t == nt - 2);
;             const char* a1 = cA + (size_t)(t + 1) * kstep;
;             const char* a2 = last ? nA : cA + (size_t)(t + 2) * kstep; const char* b2 = last ? nB : cB + (size_t)(t + 2) * kstep;
;             const char* a3 = a2 + kstep; const char* b3 = b2 + kstep;
;     ...
;             PG8_LDA(At, 1, 1); PG8_STAGE(PG8_SB(1, 0), b3, voffB); PG8_STAGE(PG8_SB(1, 1), b3 + hstep, voffB); PG8_STAGE(PG8_SA(1, 0), a3, voffA);
;             PG8_WAIT_V(8); PG8_WAIT_L(0); PG8_BAR; PG8_MMA(1, 0, At, B0); PG8_MMA(1, 1, At, B1); PG8_BAR; PG8_SCHED;
	s_add_i32 s28, s28, s23
	v_lshl_add_u64 v[138:139], v[138:139], 0, s[44:45]
	s_mov_b32 m0, s28
	ds_read_b128 v[182:185], v143 offset:49152
	ds_read_b128 v[186:189], v143 offset:50176
	ds_read_b128 v[190:193], v143 offset:51200
	ds_read_b128 v[194:197], v143 offset:52224
	ds_read_b128 v[198:201], v143 offset:53248
	ds_read_b128 v[202:205], v143 offset:54272
	ds_read_b128 v[206:209], v143 offset:55296
	ds_read_b128 v[210:213], v143 offset:56320
	global_load_lds_dwordx4 v[138:139], off
	s_add_i32 m0, s28, 0x2000
	s_add_u32 s38, s64, 0x40080
	v_lshl_add_u64 v[138:139], v[214:215], 0, s[44:45]
	s_addc_u32 s39, s65, 0
	s_add_i32 s28, s48, s23
	global_load_lds_dwordx4 v[138:139], off
	v_lshl_add_u64 v[138:139], s[38:39], 0, v[176:177]
	s_mov_b32 m0, s28
	s_nop 0
	global_load_lds_dwordx4 v[138:139], off
	v_lshl_add_u64 v[138:139], s[38:39], 0, v[128:129]
	s_add_i32 m0, s28, 0x2000
	s_nop 0
	global_load_lds_dwordx4 v[138:139], off
	v_lshl_add_u64 v[138:139], v[216:217], 0, s[44:45]
	s_mov_b32 m0, s73
	s_nop 0
	global_load_lds_dwordx4 v[138:139], off
	v_lshl_add_u64 v[138:139], v[218:219], 0, s[44:45]
	s_mov_b32 m0, s74
	s_nop 0
	global_load_lds_dwordx4 v[138:139], off
	s_waitcnt vmcnt(8)
	s_waitcnt lgkmcnt(0)
	s_barrier
	s_setprio 1
	s_waitcnt lgkmcnt(0)
	v_mfma_f32_16x16x32_bf16 v[60:63], v[144:147], v[182:185], v[60:63]
	v_mfma_f32_16x16x32_bf16 v[56:59], v[152:155], v[182:185], v[56:59]
	v_mfma_f32_16x16x32_bf16 v[44:47], v[144:147], v[190:193], v[44:47]
	v_mfma_f32_16x16x32_bf16 v[40:43], v[152:155], v[190:193], v[40:43]
	v_mfma_f32_16x16x32_bf16 v[28:31], v[144:147], v[198:201], v[28:31]
	v_mfma_f32_16x16x32_bf16 v[24:27], v[152:155], v[198:201], v[24:27]
	v_mfma_f32_16x16x32_bf16 v[12:15], v[144:147], v[206:209], v[12:15]
	v_mfma_f32_16x16x32_bf16 v[8:11], v[152:155], v[206:209], v[8:11]
	v_mfma_f32_16x16x32_bf16 v[60:63], v[148:151], v[186:189], v[60:63]
	v_mfma_f32_16x16x32_bf16 v[56:59], v[156:159], v[186:189], v[56:59]
	v_mfma_f32_16x16x32_bf16 v[44:47], v[148:151], v[194:197], v[44:47]
	v_mfma_f32_16x16x32_bf16 v[40:43], v[156:159], v[194:197], v[40:43]
	v_mfma_f32_16x16x32_bf16 v[28:31], v[148:151], v[202:205], v[28:31]
	v_mfma_f32_16x16x32_bf16 v[24:27], v[156:159], v[202:205], v[24:27]
	v_mfma_f32_16x16x32_bf16 v[12:15], v[148:151], v[210:213], v[12:15]
	v_mfma_f32_16x16x32_bf16 v[8:11], v[156:159], v[210:213], v[8:11]
	v_mfma_f32_16x16x32_bf16 v[52:55], v[160:163], v[182:185], v[52:55]
	v_mfma_f32_16x16x32_bf16 v[48:51], v[168:171], v[182:185], v[48:51]
	v_mfma_f32_16x16x32_bf16 v[36:39], v[160:163], v[190:193], v[36:39]
	v_mfma_f32_16x16x32_bf16 v[32:35], v[168:171], v[190:193], v[32:35]
	v_mfma_f32_16x16x32_bf16 v[20:23], v[160:163], v[198:201], v[20:23]
	v_mfma_f32_16x16x32_bf16 v[16:19], v[168:171], v[198:201], v[16:19]
	v_mfma_f32_16x16x32_bf16 v[4:7], v[160:163], v[206:209], v[4:7]
	v_mfma_f32_16x16x32_bf16 v[0:3], v[168:171], v[206:209], v[0:3]
	v_mfma_f32_16x16x32_bf16 v[52:55], v[164:167], v[186:189], v[52:55]
	v_mfma_f32_16x16x32_bf16 v[48:51], v[172:175], v[186:189], v[48:51]
	s_add_i32 s80, s80, 2
	v_mfma_f32_16x16x32_bf16 v[36:39], v[164:167], v[194:197], v[36:39]
	s_add_u32 vcc_lo, vcc_lo, 0x100
	v_mfma_f32_16x16x32_bf16 v[32:35], v[172:175], v[194:197], v[32:35]
	s_addc_u32 vcc_hi, vcc_hi, 0
	v_mfma_f32_16x16x32_bf16 v[20:23], v[164:167], v[202:205], v[20:23]
	s_add_u32 s78, s78, 0x100
	v_mfma_f32_16x16x32_bf16 v[16:19], v[172:175], v[202:205], v[16:19]
	s_addc_u32 s79, s79, 0
	v_mfma_f32_16x16x32_bf16 v[4:7], v[164:167], v[210:213], v[4:7]
	s_cmp_gt_u32 s80, 13
	v_mfma_f32_16x16x32_bf16 v[0:3], v[172:175], v[210:213], v[0:3]
	s_setprio 0
	s_barrier
	s_cbranch_scc0 .LBB0_718
	s_branch .Lg3_post

; #define PG8_STAGE(bufoff, gbase, voff) do { _Pragma("unroll") for (int _i = 0; _i < 2; ++_i) \
;         __builtin_amdgcn_global_load_lds((const unsigned*)((const char*)(gbase) + (voff)[_i]), (PG8_LAS unsigned*)(lds + (bufoff) + ldsw + _i * 8192), 16, 0, 0); } while (0)
; #define PG8_LDA(dst, b, h) do { _Pragma("unroll") for (int m = 0; m < 4; ++m) _Pragma("unroll") for (int k = 0; k < 2; ++k) dst[m][k] = *(const PG8_LAS bf16x8*)(lds + PG8_SA(b, h) + aoff + m * 2048 + k * 1024); } while (0)
; #define PG8_LDB(dst, b, h) do { _Pragma("unroll") for (int n = 0; n < 2; ++n) _Pragma("unroll") for (int k = 0; k < 2; ++k) dst[n][k] = *(const PG8_LAS bf16x8*)(lds + PG8_SB(b, h) + boff + n * 2048 + k * 1024); } while (0)
; #define PG8_MMA(ai, bj, At, Bt) do { __builtin_amdgcn_s_setprio(1); _Pragma("unroll") for (int m = 0; m < 4; ++m) _Pragma("unroll") for (int n = 0; n < 2; ++n) _Pragma("unroll") for (int k = 0; k < 2; ++k) \
;         acc[ai][bj][m][n] = __builtin_amdgcn_mfma_f32_16x16x32_bf16(Bt[n][k], At[m][k], acc[ai][bj][m][n], 0, 0, 0); __builtin_amdgcn_s_setprio(0); } while (0)
; #define PG8_WAIT_V(n) asm volatile("s_waitcnt vmcnt(" #n ")" ::: "memory")
; #define PG8_WAIT_L(n) asm volatile("s_waitcnt lgkmcnt(" #n ")" ::: "memory")
; #define PG8_BAR __builtin_amdgcn_s_barrier()
; #define PG8_SCHED __builtin_amdgcn_sched_barrier(0)
; template <class Epi, class Sched, bool ALIGN_EPI = false, bool SP2 = false>
; __device__ __forceinline__ void gemm_phase(PG8_LAS unsigned char* lds, const Gemm g, const Sched& S, const Epi& E) {
;     ...
;             const bool last = (t == nt - 2);
;             const char* a1 = cA + (size_t)(t + 1) * kstep;
;             const char* a2 = last ? nA : cA + (size_t)(t + 2) * kstep; const char* b2 = last ? nB : cB + (size_t)(t + 2) * kstep;
;             const char* a3 = a2 + kstep; const char* b3 = b2 + kstep;
;             if (last && has_next) S.a_ready(nxt);
;             if constexpr (SP2) {
;             PG8_LDB(B0, 0, 0); PG8_LDB(B1, 0, 1); PG8_SCHED; PG8_LDA(At, 0, 0); PG8_STAGE(PG8_SA(1, 1), a1 + hstep, voffA);
;             PG8_WAIT_V(8); PG8_WAIT_L(0); PG8_BAR; PG8_MMA(0, 0, At, B0); PG8_MMA(0, 1, At, B1); PG8_BAR; PG8_SCHED;
;             PG8_LDA(At, 0, 1); PG8_STAGE(PG8_SB(0, 0), b2, voffB); PG8_STAGE(PG8_SB(0, 1), b2 + hstep, voffB); PG8_STAGE(PG8_SA(0, 0), a2, voffA);
.LBB0_790:
	s_add_u32 s4, s64, 0xfff00080
	s_addc_u32 s5, s65, -1
	s_add_i32 s28, 0, 0x10000
	s_cmp_eq_u32 s74, 60
	s_cselect_b32 s7, s35, s5
	s_cselect_b32 s6, s72, s4
	v_add_u32_e32 v138, s28, v142
	s_cselect_b32 s5, s27, s67
	s_cselect_b32 s4, s73, s66
	s_add_i32 s48, 0, 0x14000
	ds_read_b128 v[144:147], v138
	ds_read_b128 v[148:151], v138 offset:1024
	ds_read_b128 v[152:155], v138 offset:2048
	ds_read_b128 v[156:159], v138 offset:3072
	v_add_u32_e32 v138, s48, v142
	ds_read_b128 v[160:163], v138
	ds_read_b128 v[164:167], v138 offset:1024
	ds_read_b128 v[168:171], v138 offset:2048
	ds_read_b128 v[172:175], v138 offset:3072
	v_lshl_add_u64 v[138:139], s[64:65], 0, v[134:135]
	s_add_i32 m0, s23, 0xc000
	ds_read_b128 v[182:185], v143
	ds_read_b128 v[186:189], v143 offset:1024
	ds_read_b128 v[190:193], v143 offset:2048
	ds_read_b128 v[194:197], v143 offset:3072
	ds_read_b128 v[198:201], v143 offset:4096
	ds_read_b128 v[202:205], v143 offset:5120
	ds_read_b128 v[206:209], v143 offset:6144
	ds_read_b128 v[210:213], v143 offset:7168
	global_load_lds_dwordx4 v[138:139], off
	v_lshl_add_u64 v[138:139], s[64:65], 0, v[136:137]
	s_add_i32 m0, s23, 0xe000
	s_nop 0
	global_load_lds_dwordx4 v[138:139], off
	s_waitcnt vmcnt(8)
	s_waitcnt lgkmcnt(0)
	s_barrier
	s_setprio 1
	s_waitcnt lgkmcnt(0)
	v_mfma_f32_16x16x32_bf16 v[124:127], v[144:147], v[182:185], v[124:127]
	v_mfma_f32_16x16x32_bf16 v[120:123], v[152:155], v[182:185], v[120:123]
	v_mfma_f32_16x16x32_bf16 v[116:119], v[144:147], v[190:193], v[116:119]
	v_mfma_f32_16x16x32_bf16 v[108:111], v[152:155], v[190:193], v[108:111]
	v_mfma_f32_16x16x32_bf16 v[100:103], v[144:147], v[198:201], v[100:103]
	v_mfma_f32_16x16x32_bf16 v[92:95], v[152:155], v[198:201], v[92:95]
	v_mfma_f32_16x16x32_bf16 v[84:87], v[144:147], v[206:209], v[84:87]
	v_mfma_f32_16x16x32_bf16 v[76:79], v[152:155], v[206:209], v[76:79]
	v_mfma_f32_16x16x32_bf16 v[124:127], v[148:151], v[186:189], v[124:127]
	v_mfma_f32_16x16x32_bf16 v[120:123], v[156:159], v[186:189], v[120:123]
	v_mfma_f32_16x16x32_bf16 v[116:119], v[148:151], v[194:197], v[116:119]
	v_mfma_f32_16x16x32_bf16 v[108:111], v[156:159], v[194:197], v[108:111]
	v_mfma_f32_16x16x32_bf16 v[100:103], v[148:151], v[202:205], v[100:103]
	v_mfma_f32_16x16x32_bf16 v[92:95], v[156:159], v[202:205], v[92:95]
	v_mfma_f32_16x16x32_bf16 v[84:87], v[148:151], v[210:213], v[84:87]
	v_mfma_f32_16x16x32_bf16 v[76:79], v[156:159], v[210:213], v[76:79]
	v_mfma_f32_16x16x32_bf16 v[112:115], v[160:163], v[182:185], v[112:115]
	v_mfma_f32_16x16x32_bf16 v[104:107], v[168:171], v[182:185], v[104:107]
	v_mfma_f32_16x16x32_bf16 v[96:99], v[160:163], v[190:193], v[96:99]
	v_mfma_f32_16x16x32_bf16 v[88:91], v[168:171], v[190:193], v[88:91]
	v_mfma_f32_16x16x32_bf16 v[80:83], v[160:163], v[198:201], v[80:83]
	v_mfma_f32_16x16x32_bf16 v[72:75], v[168:171], v[198:201], v[72:75]
	v_mfma_f32_16x16x32_bf16 v[68:71], v[160:163], v[206:209], v[68:71]
	v_mfma_f32_16x16x32_bf16 v[64:67], v[168:171], v[206:209], v[64:67]
	v_mfma_f32_16x16x32_bf16 v[112:115], v[164:167], v[186:189], v[112:115]
	v_mfma_f32_16x16x32_bf16 v[104:107], v[172:175], v[186:189], v[104:107]
	v_mfma_f32_16x16x32_bf16 v[96:99], v[164:167], v[194:197], v[96:99]
	v_mfma_f32_16x16x32_bf16 v[88:91], v[172:175], v[194:197], v[88:91]
	v_mfma_f32_16x16x32_bf16 v[80:83], v[164:167], v[202:205], v[80:83]
	v_mfma_f32_16x16x32_bf16 v[72:75], v[172:175], v[202:205], v[72:75]
	v_mfma_f32_16x16x32_bf16 v[68:71], v[164:167], v[210:213], v[68:71]
	v_mfma_f32_16x16x32_bf16 v[64:67], v[172:175], v[210:213], v[64:67]
	s_setprio 0
	s_barrier
	s_add_i32 s28, s28, s22
	v_lshl_add_u64 v[138:139], s[4:5], 0, v[176:177]
	s_mov_b32 m0, s28
	ds_read_b128 v[182:185], v143 offset:16384
	ds_read_b128 v[186:189], v143 offset:17408
	ds_read_b128 v[190:193], v143 offset:18432
	ds_read_b128 v[194:197], v143 offset:19456
	ds_read_b128 v[198:201], v143 offset:20480
	ds_read_b128 v[202:205], v143 offset:21504
	ds_read_b128 v[206:209], v143 offset:22528
	ds_read_b128 v[210:213], v143 offset:23552
	global_load_lds_dwordx4 v[138:139], off
	s_add_i32 m0, s28, 0x2000
	s_add_u32 s38, s4, 0x100000
	v_lshl_add_u64 v[214:215], s[4:5], 0, v[128:129]
	s_addc_u32 s39, s5, 0
	s_add_i32 s28, s48, s22
	global_load_lds_dwordx4 v[214:215], off
	v_lshl_add_u64 v[216:217], s[38:39], 0, v[176:177]
	s_mov_b32 m0, s28
	v_lshl_add_u64 v[218:219], s[6:7], 0, v[130:131]
	global_load_lds_dwordx4 v[216:217], off
	v_lshl_add_u64 v[216:217], s[38:39], 0, v[128:129]
	s_add_i32 m0, s28, 0x2000
	s_nop 0
	global_load_lds_dwordx4 v[216:217], off
	v_lshl_add_u64 v[216:217], s[6:7], 0, v[132:133]
	s_mov_b32 m0, s23
	s_nop 0
	global_load_lds_dwordx4 v[216:217], off
	s_mov_b32 m0, s24
	s_nop 0
	global_load_lds_dwordx4 v[218:219], off
	s_waitcnt vmcnt(8)
	s_waitcnt lgkmcnt(0)
	s_barrier
; #define PG8_STAGE(bufoff, gbase, voff) do { _Pragma("unroll") for (int _i = 0; _i < 2; ++_i) \
;         __builtin_amdgcn_global_load_lds((const unsigned*)((const char*)(gbase) + (voff)[_i]), (PG8_LAS unsigned*)(lds + (bufoff) + ldsw + _i * 8192), 16, 0, 0); } while (0)
; #define PG8_LDA(dst, b, h) do { _Pragma("unroll") for (int m = 0; m < 4; ++m) _Pragma("unroll") for (int k = 0; k < 2; ++k) dst[m][k] = *(const PG8_LAS bf16x8*)(lds + PG8_SA(b, h) + aoff + m * 2048 + k * 1024); } while (0)
; #define PG8_LDB(dst, b, h) do { _Pragma("unroll") for (int n = 0; n < 2; ++n) _Pragma("unroll") for (int k = 0; k < 2; ++k) dst[n][k] = *(const PG8_LAS bf16x8*)(lds + PG8_SB(b, h) + boff + n * 2048 + k * 1024); } while (0)
; #define PG8_MMA(ai, bj, At, Bt) do { __builtin_amdgcn_s_setprio(1); _Pragma("unroll") for (int m = 0; m < 4; ++m) _Pragma("unroll") for (int n = 0; n < 2; ++n) _Pragma("unroll") for (int k = 0; k < 2; ++k) \
;         acc[ai][bj][m][n] = __builtin_amdgcn_mfma_f32_16x16x32_bf16(Bt[n][k], At[m][k], acc[ai][bj][m][n], 0, 0, 0); __builtin_amdgcn_s_setprio(0); } while (0)
; #define PG8_WAIT_V(n) asm volatile("s_waitcnt vmcnt(" #n ")" ::: "memory")
; #define PG8_WAIT_L(n) asm volatile("s_waitcnt lgkmcnt(" #n ")" ::: "memory")
; #define PG8_BAR __builtin_amdgcn_s_barrier()
; #define PG8_SCHED __builtin_amdgcn_sched_barrier(0)
; template <class Epi, class Sched, bool ALIGN_EPI = false, bool SP2 = false>
; __device__ __forceinline__ void gemm_phase(PG8_LAS unsigned char* lds, const Gemm g, const Sched& S, const Epi& E) {
;     ...
;             PG8_WAIT_V(8); PG8_WAIT_L(0); PG8_BAR; PG8_MMA(1, 0, At, B0); PG8_MMA(1, 1, At, B1); PG8_BAR; PG8_SCHED;
;             PG8_LDB(B0, 1, 0); PG8_LDB(B1, 1, 1); PG8_SCHED; PG8_LDA(At, 1, 0); PG8_STAGE(PG8_SA(0, 1), a2 + hstep, voffA);
;             PG8_WAIT_V(8); PG8_WAIT_L(0); PG8_BAR; PG8_MMA(0, 0, At, B0); PG8_MMA(0, 1, At, B1); PG8_BAR; PG8_SCHED;
	s_setprio 1
	s_waitcnt lgkmcnt(0)
	v_mfma_f32_16x16x32_bf16 v[60:63], v[144:147], v[182:185], v[60:63]
	v_mfma_f32_16x16x32_bf16 v[56:59], v[152:155], v[182:185], v[56:59]
	v_mfma_f32_16x16x32_bf16 v[52:55], v[144:147], v[190:193], v[52:55]
	v_mfma_f32_16x16x32_bf16 v[44:47], v[152:155], v[190:193], v[44:47]
	v_mfma_f32_16x16x32_bf16 v[36:39], v[144:147], v[198:201], v[36:39]
	v_mfma_f32_16x16x32_bf16 v[28:31], v[152:155], v[198:201], v[28:31]
	v_mfma_f32_16x16x32_bf16 v[20:23], v[144:147], v[206:209], v[20:23]
	v_mfma_f32_16x16x32_bf16 v[12:15], v[152:155], v[206:209], v[12:15]
	v_mfma_f32_16x16x32_bf16 v[60:63], v[148:151], v[186:189], v[60:63]
	v_mfma_f32_16x16x32_bf16 v[56:59], v[156:159], v[186:189], v[56:59]
	v_mfma_f32_16x16x32_bf16 v[52:55], v[148:151], v[194:197], v[52:55]
	v_mfma_f32_16x16x32_bf16 v[44:47], v[156:159], v[194:197], v[44:47]
	v_mfma_f32_16x16x32_bf16 v[36:39], v[148:151], v[202:205], v[36:39]
	v_mfma_f32_16x16x32_bf16 v[28:31], v[156:159], v[202:205], v[28:31]
	v_mfma_f32_16x16x32_bf16 v[20:23], v[148:151], v[210:213], v[20:23]
	v_mfma_f32_16x16x32_bf16 v[12:15], v[156:159], v[210:213], v[12:15]
	v_mfma_f32_16x16x32_bf16 v[48:51], v[160:163], v[182:185], v[48:51]
	v_mfma_f32_16x16x32_bf16 v[40:43], v[168:171], v[182:185], v[40:43]
	v_mfma_f32_16x16x32_bf16 v[32:35], v[160:163], v[190:193], v[32:35]
	v_mfma_f32_16x16x32_bf16 v[24:27], v[168:171], v[190:193], v[24:27]
	v_mfma_f32_16x16x32_bf16 v[16:19], v[160:163], v[198:201], v[16:19]
	v_mfma_f32_16x16x32_bf16 v[8:11], v[168:171], v[198:201], v[8:11]
	v_mfma_f32_16x16x32_bf16 v[4:7], v[160:163], v[206:209], v[4:7]
	v_mfma_f32_16x16x32_bf16 v[0:3], v[168:171], v[206:209], v[0:3]
	v_mfma_f32_16x16x32_bf16 v[48:51], v[164:167], v[186:189], v[48:51]
	v_mfma_f32_16x16x32_bf16 v[40:43], v[172:175], v[186:189], v[40:43]
	v_mfma_f32_16x16x32_bf16 v[32:35], v[164:167], v[194:197], v[32:35]
	v_mfma_f32_16x16x32_bf16 v[24:27], v[172:175], v[194:197], v[24:27]
	v_mfma_f32_16x16x32_bf16 v[16:19], v[164:167], v[202:205], v[16:19]
	v_mfma_f32_16x16x32_bf16 v[8:11], v[172:175], v[202:205], v[8:11]
	v_mfma_f32_16x16x32_bf16 v[4:7], v[164:167], v[210:213], v[4:7]
	v_mfma_f32_16x16x32_bf16 v[0:3], v[172:175], v[210:213], v[0:3]
	s_setprio 0
	s_barrier
	s_add_i32 s28, 0, 0x18000
	s_add_i32 s38, 0, 0x1c000
	v_add_u32_e32 v156, s28, v142
	v_add_u32_e32 v172, s38, v142
	ds_read_b128 v[144:147], v156
	ds_read_b128 v[148:151], v156 offset:1024
	ds_read_b128 v[152:155], v156 offset:2048
	ds_read_b128 v[156:159], v156 offset:3072
	ds_read_b128 v[160:163], v172
	ds_read_b128 v[164:167], v172 offset:1024
	ds_read_b128 v[168:171], v172 offset:2048
	ds_read_b128 v[172:175], v172 offset:3072
	s_add_u32 s6, s6, 0x100000
	s_addc_u32 s7, s7, 0
	s_mov_b32 m0, s25
	v_lshl_add_u64 v[220:221], s[6:7], 0, v[132:133]
	ds_read_b128 v[182:185], v143 offset:32768
	ds_read_b128 v[186:189], v143 offset:33792
	ds_read_b128 v[190:193], v143 offset:34816
	ds_read_b128 v[194:197], v143 offset:35840
	ds_read_b128 v[198:201], v143 offset:36864
	ds_read_b128 v[202:205], v143 offset:37888
	ds_read_b128 v[206:209], v143 offset:38912
	ds_read_b128 v[210:213], v143 offset:39936
	global_load_lds_dwordx4 v[220:221], off
	v_lshl_add_u64 v[220:221], s[6:7], 0, v[130:131]
	s_mov_b32 m0, s30
	s_nop 0
	global_load_lds_dwordx4 v[220:221], off
	s_waitcnt vmcnt(8)
	s_waitcnt lgkmcnt(0)
	s_barrier
	s_setprio 1
	s_waitcnt lgkmcnt(0)
	v_mfma_f32_16x16x32_bf16 v[124:127], v[144:147], v[182:185], v[124:127]
	v_mfma_f32_16x16x32_bf16 v[120:123], v[152:155], v[182:185], v[120:123]
	v_mfma_f32_16x16x32_bf16 v[116:119], v[144:147], v[190:193], v[116:119]
	v_mfma_f32_16x16x32_bf16 v[108:111], v[152:155], v[190:193], v[108:111]
	v_mfma_f32_16x16x32_bf16 v[100:103], v[144:147], v[198:201], v[100:103]
	v_mfma_f32_16x16x32_bf16 v[92:95], v[152:155], v[198:201], v[92:95]
	v_mfma_f32_16x16x32_bf16 v[84:87], v[144:147], v[206:209], v[84:87]
	v_mfma_f32_16x16x32_bf16 v[76:79], v[152:155], v[206:209], v[76:79]
	v_mfma_f32_16x16x32_bf16 v[124:127], v[148:151], v[186:189], v[124:127]
	v_mfma_f32_16x16x32_bf16 v[120:123], v[156:159], v[186:189], v[120:123]
	v_mfma_f32_16x16x32_bf16 v[116:119], v[148:151], v[194:197], v[116:119]
	v_mfma_f32_16x16x32_bf16 v[108:111], v[156:159], v[194:197], v[108:111]
	v_mfma_f32_16x16x32_bf16 v[100:103], v[148:151], v[202:205], v[100:103]
	v_mfma_f32_16x16x32_bf16 v[92:95], v[156:159], v[202:205], v[92:95]
	v_mfma_f32_16x16x32_bf16 v[84:87], v[148:151], v[210:213], v[84:87]
	v_mfma_f32_16x16x32_bf16 v[76:79], v[156:159], v[210:213], v[76:79]
	v_mfma_f32_16x16x32_bf16 v[112:115], v[160:163], v[182:185], v[112:115]
	v_mfma_f32_16x16x32_bf16 v[104:107], v[168:171], v[182:185], v[104:107]
	v_mfma_f32_16x16x32_bf16 v[96:99], v[160:163], v[190:193], v[96:99]
	v_mfma_f32_16x16x32_bf16 v[88:91], v[168:171], v[190:193], v[88:91]
	v_mfma_f32_16x16x32_bf16 v[80:83], v[160:163], v[198:201], v[80:83]
	v_mfma_f32_16x16x32_bf16 v[72:75], v[168:171], v[198:201], v[72:75]
	v_mfma_f32_16x16x32_bf16 v[68:71], v[160:163], v[206:209], v[68:71]
	v_mfma_f32_16x16x32_bf16 v[64:67], v[168:171], v[206:209], v[64:67]
	v_mfma_f32_16x16x32_bf16 v[112:115], v[164:167], v[186:189], v[112:115]
	v_mfma_f32_16x16x32_bf16 v[104:107], v[172:175], v[186:189], v[104:107]
	v_mfma_f32_16x16x32_bf16 v[96:99], v[164:167], v[194:197], v[96:99]
	v_mfma_f32_16x16x32_bf16 v[88:91], v[172:175], v[194:197], v[88:91]
	v_mfma_f32_16x16x32_bf16 v[80:83], v[164:167], v[202:205], v[80:83]
	v_mfma_f32_16x16x32_bf16 v[72:75], v[172:175], v[202:205], v[72:75]
	v_mfma_f32_16x16x32_bf16 v[68:71], v[164:167], v[210:213], v[68:71]
	v_mfma_f32_16x16x32_bf16 v[64:67], v[172:175], v[210:213], v[64:67]
	s_setprio 0
	s_barrier
; #define PG8_STAGE(bufoff, gbase, voff) do { _Pragma("unroll") for (int _i = 0; _i < 2; ++_i) \
;         __builtin_amdgcn_global_load_lds((const unsigned*)((const char*)(gbase) + (voff)[_i]), (PG8_LAS unsigned*)(lds + (bufoff) + ldsw + _i * 8192), 16, 0, 0); } while (0)
; #define PG8_LDA(dst, b, h) do { _Pragma("unroll") for (int m = 0; m < 4; ++m) _Pragma("unroll") for (int k = 0; k < 2; ++k) dst[m][k] = *(const PG8_LAS bf16x8*)(lds + PG8_SA(b, h) + aoff + m * 2048 + k * 1024); } while (0)
; #define PG8_MMA(ai, bj, At, Bt) do { __builtin_amdgcn_s_setprio(1); _Pragma("unroll") for (int m = 0; m < 4; ++m) _Pragma("unroll") for (int n = 0; n < 2; ++n) _Pragma("unroll") for (int k = 0; k < 2; ++k) \
;         acc[ai][bj][m][n] = __builtin_amdgcn_mfma_f32_16x16x32_bf16(Bt[n][k], At[m][k], acc[ai][bj][m][n], 0, 0, 0); __builtin_amdgcn_s_setprio(0); } while (0)
; #define PG8_WAIT_V(n) asm volatile("s_waitcnt vmcnt(" #n ")" ::: "memory")
; #define PG8_WAIT_L(n) asm volatile("s_waitcnt lgkmcnt(" #n ")" ::: "memory")
; #define PG8_BAR __builtin_amdgcn_s_barrier()
; #define PG8_SCHED __builtin_amdgcn_sched_barrier(0)
; template <class Epi, class Sched, bool ALIGN_EPI = false, bool SP2 = false>
; __device__ __forceinline__ void gemm_phase(PG8_LAS unsigned char* lds, const Gemm g, const Sched& S, const Epi& E) {
;     ...
;             PG8_LDA(At, 1, 1); PG8_STAGE(PG8_SB(1, 0), b3, voffB); PG8_STAGE(PG8_SB(1, 1), b3 + hstep, voffB); PG8_STAGE(PG8_SA(1, 0), a3, voffA);
;             PG8_WAIT_V(8); PG8_WAIT_L(0); PG8_BAR; PG8_MMA(1, 0, At, B0); PG8_MMA(1, 1, At, B1); PG8_BAR; PG8_SCHED;
	s_add_i32 s6, s28, s22
	v_lshl_add_u64 v[138:139], v[138:139], 0, s[44:45]
	s_mov_b32 m0, s6
	ds_read_b128 v[182:185], v143 offset:49152
	ds_read_b128 v[186:189], v143 offset:50176
	ds_read_b128 v[190:193], v143 offset:51200
	ds_read_b128 v[194:197], v143 offset:52224
	ds_read_b128 v[198:201], v143 offset:53248
	ds_read_b128 v[202:205], v143 offset:54272
	ds_read_b128 v[206:209], v143 offset:55296
	ds_read_b128 v[210:213], v143 offset:56320
	global_load_lds_dwordx4 v[138:139], off
	s_add_i32 m0, s6, 0x2000
	s_add_u32 s4, s4, 0x100080
	v_lshl_add_u64 v[138:139], v[214:215], 0, s[44:45]
	s_addc_u32 s5, s5, 0
	s_add_i32 s6, s38, s22
	global_load_lds_dwordx4 v[138:139], off
	v_lshl_add_u64 v[138:139], s[4:5], 0, v[176:177]
	s_mov_b32 m0, s6
	s_nop 0
	global_load_lds_dwordx4 v[138:139], off
	v_lshl_add_u64 v[138:139], s[4:5], 0, v[128:129]
	s_add_i32 m0, s6, 0x2000
	s_nop 0
	global_load_lds_dwordx4 v[138:139], off
	v_lshl_add_u64 v[138:139], v[216:217], 0, s[44:45]
	s_mov_b32 m0, s63
	s_nop 0
	global_load_lds_dwordx4 v[138:139], off
	v_lshl_add_u64 v[138:139], v[218:219], 0, s[44:45]
	s_mov_b32 m0, s68
	s_nop 0
	global_load_lds_dwordx4 v[138:139], off
	s_waitcnt vmcnt(8)
	s_waitcnt lgkmcnt(0)
	s_barrier
	s_setprio 1
	s_waitcnt lgkmcnt(0)
	v_mfma_f32_16x16x32_bf16 v[60:63], v[144:147], v[182:185], v[60:63]
	v_mfma_f32_16x16x32_bf16 v[56:59], v[152:155], v[182:185], v[56:59]
	v_mfma_f32_16x16x32_bf16 v[52:55], v[144:147], v[190:193], v[52:55]
	v_mfma_f32_16x16x32_bf16 v[44:47], v[152:155], v[190:193], v[44:47]
	v_mfma_f32_16x16x32_bf16 v[36:39], v[144:147], v[198:201], v[36:39]
	v_mfma_f32_16x16x32_bf16 v[28:31], v[152:155], v[198:201], v[28:31]
	v_mfma_f32_16x16x32_bf16 v[20:23], v[144:147], v[206:209], v[20:23]
	v_mfma_f32_16x16x32_bf16 v[12:15], v[152:155], v[206:209], v[12:15]
	v_mfma_f32_16x16x32_bf16 v[60:63], v[148:151], v[186:189], v[60:63]
	v_mfma_f32_16x16x32_bf16 v[56:59], v[156:159], v[186:189], v[56:59]
	v_mfma_f32_16x16x32_bf16 v[52:55], v[148:151], v[194:197], v[52:55]
	v_mfma_f32_16x16x32_bf16 v[44:47], v[156:159], v[194:197], v[44:47]
	v_mfma_f32_16x16x32_bf16 v[36:39], v[148:151], v[202:205], v[36:39]
	v_mfma_f32_16x16x32_bf16 v[28:31], v[156:159], v[202:205], v[28:31]
	v_mfma_f32_16x16x32_bf16 v[20:23], v[148:151], v[210:213], v[20:23]
	v_mfma_f32_16x16x32_bf16 v[12:15], v[156:159], v[210:213], v[12:15]
	v_mfma_f32_16x16x32_bf16 v[48:51], v[160:163], v[182:185], v[48:51]
	v_mfma_f32_16x16x32_bf16 v[40:43], v[168:171], v[182:185], v[40:43]
	v_mfma_f32_16x16x32_bf16 v[32:35], v[160:163], v[190:193], v[32:35]
	v_mfma_f32_16x16x32_bf16 v[24:27], v[168:171], v[190:193], v[24:27]
	v_mfma_f32_16x16x32_bf16 v[16:19], v[160:163], v[198:201], v[16:19]
	v_mfma_f32_16x16x32_bf16 v[8:11], v[168:171], v[198:201], v[8:11]
	v_mfma_f32_16x16x32_bf16 v[4:7], v[160:163], v[206:209], v[4:7]
	v_mfma_f32_16x16x32_bf16 v[0:3], v[168:171], v[206:209], v[0:3]
	v_mfma_f32_16x16x32_bf16 v[48:51], v[164:167], v[186:189], v[48:51]
	v_mfma_f32_16x16x32_bf16 v[40:43], v[172:175], v[186:189], v[40:43]
	s_add_i32 s74, s74, 2
	v_mfma_f32_16x16x32_bf16 v[32:35], v[164:167], v[194:197], v[32:35]
	s_add_u32 s64, s64, 0x100
	v_mfma_f32_16x16x32_bf16 v[24:27], v[172:175], v[194:197], v[24:27]
	s_addc_u32 s65, s65, 0
	v_mfma_f32_16x16x32_bf16 v[16:19], v[164:167], v[202:205], v[16:19]
	s_add_u32 s66, s66, 0x100
	v_mfma_f32_16x16x32_bf16 v[8:11], v[172:175], v[202:205], v[8:11]
	s_addc_u32 s67, s67, 0
	v_mfma_f32_16x16x32_bf16 v[4:7], v[164:167], v[210:213], v[4:7]
	s_cmp_gt_u32 s74, 61
	v_mfma_f32_16x16x32_bf16 v[0:3], v[172:175], v[210:213], v[0:3]
	s_setprio 0
	s_barrier
	s_cbranch_scc0 .LBB0_790

; #define PG8_STAGE(bufoff, gbase, voff) do { _Pragma("unroll") for (int _i = 0; _i < 2; ++_i) \
;         __builtin_amdgcn_global_load_lds((const unsigned*)((const char*)(gbase) + (voff)[_i]), (PG8_LAS unsigned*)(lds + (bufoff) + ldsw + _i * 8192), 16, 0, 0); } while (0)
; #define PG8_LDA(dst, b, h) do { _Pragma("unroll") for (int m = 0; m < 4; ++m) _Pragma("unroll") for (int k = 0; k < 2; ++k) dst[m][k] = *(const PG8_LAS bf16x8*)(lds + PG8_SA(b, h) + aoff + m * 2048 + k * 1024); } while (0)
; #define PG8_LDB(dst, b, h) do { _Pragma("unroll") for (int n = 0; n < 2; ++n) _Pragma("unroll") for (int k = 0; k < 2; ++k) dst[n][k] = *(const PG8_LAS bf16x8*)(lds + PG8_SB(b, h) + boff + n * 2048 + k * 1024); } while (0)
; #define PG8_WAIT_V(n) asm volatile("s_waitcnt vmcnt(" #n ")" ::: "memory")
; #define PG8_WAIT_L(n) asm volatile("s_waitcnt lgkmcnt(" #n ")" ::: "memory")
; #define PG8_BAR __builtin_amdgcn_s_barrier()
; template <class Epi, class Sched, bool ALIGN_EPI = false, bool SP2 = false>
; __device__ __forceinline__ void gemm_phase(PG8_LAS unsigned char* lds, const Gemm g, const Sched& S, const Epi& E) {
;     ...
;             const bool last = (t == nt - 2);
;             const char* a1 = cA + (size_t)(t + 1) * kstep;
;             const char* a2 = last ? nA : cA + (size_t)(t + 2) * kstep; const char* b2 = last ? nB : cB + (size_t)(t + 2) * kstep;
;             const char* a3 = a2 + kstep; const char* b3 = b2 + kstep;
;             if (last && has_next) S.a_ready(nxt);
;             if constexpr (SP2) {
;             PG8_LDB(B0, 0, 0); PG8_LDB(B1, 0, 1); PG8_SCHED; PG8_LDA(At, 0, 0); PG8_STAGE(PG8_SA(1, 1), a1 + hstep, voffA);
;             PG8_WAIT_V(8); PG8_WAIT_L(0); PG8_BAR; PG8_MMA(0, 0, At, B0); PG8_MMA(0, 1, At, B1); PG8_BAR; PG8_SCHED;
;             PG8_LDA(At, 0, 1); PG8_STAGE(PG8_SB(0, 0), b2, voffB); PG8_STAGE(PG8_SB(0, 1), b2 + hstep, voffB); PG8_STAGE(PG8_SA(0, 0), a2, voffA);
;             PG8_WAIT_V(8); PG8_WAIT_L(0); PG8_BAR; PG8_MMA(1, 0, At, B0); PG8_MMA(1, 1, At, B1); PG8_BAR; PG8_SCHED;
;     ...
; #pragma unroll
;         for (int a = 0; a < 2; ++a)
; #pragma unroll
;             for (int b = 0; b < 2; ++b)
; #pragma unroll
;                 for (int m = 0; m < 4; ++m)
; #pragma unroll
;                     for (int n = 0; n < 2; ++n) acc[a][b][m][n] = (f32x4){0.f, 0.f, 0.f, 0.f};
;         cur = nxt; cA = nA; cB = nB; ++ui;
.Lg4_peel:
	s_add_u32 s4, s64, 0xfff00080
	s_addc_u32 s5, s65, -1
	s_add_i32 s28, 0, 0x10000
	s_cmp_eq_u32 s74, 60
	s_cselect_b32 s7, s35, s5
	s_cselect_b32 s6, s72, s4
	v_add_u32_e32 v138, s28, v142
	s_cselect_b32 s5, s27, s67
	s_cselect_b32 s4, s73, s66
	s_add_i32 s48, 0, 0x14000
	ds_read_b128 v[144:147], v138
	ds_read_b128 v[148:151], v138 offset:1024
	ds_read_b128 v[152:155], v138 offset:2048
	ds_read_b128 v[156:159], v138 offset:3072
	v_add_u32_e32 v138, s48, v142
	ds_read_b128 v[160:163], v138
	ds_read_b128 v[164:167], v138 offset:1024
	ds_read_b128 v[168:171], v138 offset:2048
	ds_read_b128 v[172:175], v138 offset:3072
	v_lshl_add_u64 v[138:139], s[64:65], 0, v[134:135]
	s_add_i32 m0, s23, 0xc000
	ds_read_b128 v[182:185], v143
	ds_read_b128 v[186:189], v143 offset:1024
	ds_read_b128 v[190:193], v143 offset:2048
	ds_read_b128 v[194:197], v143 offset:3072
	ds_read_b128 v[198:201], v143 offset:4096
	ds_read_b128 v[202:205], v143 offset:5120
	ds_read_b128 v[206:209], v143 offset:6144
	ds_read_b128 v[210:213], v143 offset:7168
	global_load_lds_dwordx4 v[138:139], off
	v_lshl_add_u64 v[138:139], s[64:65], 0, v[136:137]
	s_add_i32 m0, s23, 0xe000
	s_nop 0
	global_load_lds_dwordx4 v[138:139], off
	s_waitcnt vmcnt(24)
	s_waitcnt lgkmcnt(0)
	s_barrier
	s_setprio 1
	s_waitcnt lgkmcnt(0)
	v_mfma_f32_16x16x32_bf16 v[124:127], v[144:147], v[182:185], 0
	v_mfma_f32_16x16x32_bf16 v[120:123], v[152:155], v[182:185], 0
	v_mfma_f32_16x16x32_bf16 v[116:119], v[144:147], v[190:193], 0
	v_mfma_f32_16x16x32_bf16 v[108:111], v[152:155], v[190:193], 0
	v_mfma_f32_16x16x32_bf16 v[100:103], v[144:147], v[198:201], 0
	v_mfma_f32_16x16x32_bf16 v[92:95], v[152:155], v[198:201], 0
	v_mfma_f32_16x16x32_bf16 v[84:87], v[144:147], v[206:209], 0
	v_mfma_f32_16x16x32_bf16 v[76:79], v[152:155], v[206:209], 0
	v_mfma_f32_16x16x32_bf16 v[124:127], v[148:151], v[186:189], v[124:127]
	v_mfma_f32_16x16x32_bf16 v[120:123], v[156:159], v[186:189], v[120:123]
	v_mfma_f32_16x16x32_bf16 v[116:119], v[148:151], v[194:197], v[116:119]
	v_mfma_f32_16x16x32_bf16 v[108:111], v[156:159], v[194:197], v[108:111]
	v_mfma_f32_16x16x32_bf16 v[100:103], v[148:151], v[202:205], v[100:103]
	v_mfma_f32_16x16x32_bf16 v[92:95], v[156:159], v[202:205], v[92:95]
	v_mfma_f32_16x16x32_bf16 v[84:87], v[148:151], v[210:213], v[84:87]
	v_mfma_f32_16x16x32_bf16 v[76:79], v[156:159], v[210:213], v[76:79]
	v_mfma_f32_16x16x32_bf16 v[112:115], v[160:163], v[182:185], 0
	v_mfma_f32_16x16x32_bf16 v[104:107], v[168:171], v[182:185], 0
	v_mfma_f32_16x16x32_bf16 v[96:99], v[160:163], v[190:193], 0
	v_mfma_f32_16x16x32_bf16 v[88:91], v[168:171], v[190:193], 0
	v_mfma_f32_16x16x32_bf16 v[80:83], v[160:163], v[198:201], 0
	v_mfma_f32_16x16x32_bf16 v[72:75], v[168:171], v[198:201], 0
	v_mfma_f32_16x16x32_bf16 v[68:71], v[160:163], v[206:209], 0
	v_mfma_f32_16x16x32_bf16 v[64:67], v[168:171], v[206:209], 0
	v_mfma_f32_16x16x32_bf16 v[112:115], v[164:167], v[186:189], v[112:115]
	v_mfma_f32_16x16x32_bf16 v[104:107], v[172:175], v[186:189], v[104:107]
	v_mfma_f32_16x16x32_bf16 v[96:99], v[164:167], v[194:197], v[96:99]
	v_mfma_f32_16x16x32_bf16 v[88:91], v[172:175], v[194:197], v[88:91]
	v_mfma_f32_16x16x32_bf16 v[80:83], v[164:167], v[202:205], v[80:83]
	v_mfma_f32_16x16x32_bf16 v[72:75], v[172:175], v[202:205], v[72:75]
	v_mfma_f32_16x16x32_bf16 v[68:71], v[164:167], v[210:213], v[68:71]
	v_mfma_f32_16x16x32_bf16 v[64:67], v[172:175], v[210:213], v[64:67]
	s_setprio 0
	s_barrier
	s_add_i32 s28, s28, s22
	v_lshl_add_u64 v[138:139], s[4:5], 0, v[176:177]
	s_mov_b32 m0, s28
	ds_read_b128 v[182:185], v143 offset:16384
	ds_read_b128 v[186:189], v143 offset:17408
	ds_read_b128 v[190:193], v143 offset:18432
	ds_read_b128 v[194:197], v143 offset:19456
	ds_read_b128 v[198:201], v143 offset:20480
	ds_read_b128 v[202:205], v143 offset:21504
	ds_read_b128 v[206:209], v143 offset:22528
	ds_read_b128 v[210:213], v143 offset:23552
	global_load_lds_dwordx4 v[138:139], off
	s_add_i32 m0, s28, 0x2000
	s_add_u32 s38, s4, 0x100000
	v_lshl_add_u64 v[214:215], s[4:5], 0, v[128:129]
	s_addc_u32 s39, s5, 0
	s_add_i32 s28, s48, s22
	global_load_lds_dwordx4 v[214:215], off
	v_lshl_add_u64 v[216:217], s[38:39], 0, v[176:177]
	s_mov_b32 m0, s28
	v_lshl_add_u64 v[218:219], s[6:7], 0, v[130:131]
	global_load_lds_dwordx4 v[216:217], off
	v_lshl_add_u64 v[216:217], s[38:39], 0, v[128:129]
	s_add_i32 m0, s28, 0x2000
	s_nop 0
	global_load_lds_dwordx4 v[216:217], off
	v_lshl_add_u64 v[216:217], s[6:7], 0, v[132:133]
	s_mov_b32 m0, s23
	s_nop 0
	global_load_lds_dwordx4 v[216:217], off
	s_mov_b32 m0, s24
	s_nop 0
	global_load_lds_dwordx4 v[218:219], off
	s_waitcnt vmcnt(24)
	s_waitcnt lgkmcnt(0)
	s_barrier
; #define PG8_STAGE(bufoff, gbase, voff) do { _Pragma("unroll") for (int _i = 0; _i < 2; ++_i) \
;         __builtin_amdgcn_global_load_lds((const unsigned*)((const char*)(gbase) + (voff)[_i]), (PG8_LAS unsigned*)(lds + (bufoff) + ldsw + _i * 8192), 16, 0, 0); } while (0)
; #define PG8_LDA(dst, b, h) do { _Pragma("unroll") for (int m = 0; m < 4; ++m) _Pragma("unroll") for (int k = 0; k < 2; ++k) dst[m][k] = *(const PG8_LAS bf16x8*)(lds + PG8_SA(b, h) + aoff + m * 2048 + k * 1024); } while (0)
; #define PG8_LDB(dst, b, h) do { _Pragma("unroll") for (int n = 0; n < 2; ++n) _Pragma("unroll") for (int k = 0; k < 2; ++k) dst[n][k] = *(const PG8_LAS bf16x8*)(lds + PG8_SB(b, h) + boff + n * 2048 + k * 1024); } while (0)
; #define PG8_MMA(ai, bj, At, Bt) do { __builtin_amdgcn_s_setprio(1); _Pragma("unroll") for (int m = 0; m < 4; ++m) _Pragma("unroll") for (int n = 0; n < 2; ++n) _Pragma("unroll") for (int k = 0; k < 2; ++k) \
;         acc[ai][bj][m][n] = __builtin_amdgcn_mfma_f32_16x16x32_bf16(Bt[n][k], At[m][k], acc[ai][bj][m][n], 0, 0, 0); __builtin_amdgcn_s_setprio(0); } while (0)
; #define PG8_WAIT_V(n) asm volatile("s_waitcnt vmcnt(" #n ")" ::: "memory")
; #define PG8_WAIT_L(n) asm volatile("s_waitcnt lgkmcnt(" #n ")" ::: "memory")
; #define PG8_BAR __builtin_amdgcn_s_barrier()
; #define PG8_SCHED __builtin_amdgcn_sched_barrier(0)
; template <class Epi, class Sched, bool ALIGN_EPI = false, bool SP2 = false>
; __device__ __forceinline__ void gemm_phase(PG8_LAS unsigned char* lds, const Gemm g, const Sched& S, const Epi& E) {
;     ...
;             PG8_WAIT_V(8); PG8_WAIT_L(0); PG8_BAR; PG8_MMA(1, 0, At, B0); PG8_MMA(1, 1, At, B1); PG8_BAR; PG8_SCHED;
;             PG8_LDB(B0, 1, 0); PG8_LDB(B1, 1, 1); PG8_SCHED; PG8_LDA(At, 1, 0); PG8_STAGE(PG8_SA(0, 1), a2 + hstep, voffA);
;             PG8_WAIT_V(8); PG8_WAIT_L(0); PG8_BAR; PG8_MMA(0, 0, At, B0); PG8_MMA(0, 1, At, B1); PG8_BAR; PG8_SCHED;
	s_setprio 1
	s_waitcnt lgkmcnt(0)
	v_mfma_f32_16x16x32_bf16 v[60:63], v[144:147], v[182:185], 0
	v_mfma_f32_16x16x32_bf16 v[56:59], v[152:155], v[182:185], 0
	v_mfma_f32_16x16x32_bf16 v[52:55], v[144:147], v[190:193], 0
	v_mfma_f32_16x16x32_bf16 v[44:47], v[152:155], v[190:193], 0
	v_mfma_f32_16x16x32_bf16 v[36:39], v[144:147], v[198:201], 0
	v_mfma_f32_16x16x32_bf16 v[28:31], v[152:155], v[198:201], 0
	v_mfma_f32_16x16x32_bf16 v[20:23], v[144:147], v[206:209], 0
	v_mfma_f32_16x16x32_bf16 v[12:15], v[152:155], v[206:209], 0
	v_mfma_f32_16x16x32_bf16 v[60:63], v[148:151], v[186:189], v[60:63]
	v_mfma_f32_16x16x32_bf16 v[56:59], v[156:159], v[186:189], v[56:59]
	v_mfma_f32_16x16x32_bf16 v[52:55], v[148:151], v[194:197], v[52:55]
	v_mfma_f32_16x16x32_bf16 v[44:47], v[156:159], v[194:197], v[44:47]
	v_mfma_f32_16x16x32_bf16 v[36:39], v[148:151], v[202:205], v[36:39]
	v_mfma_f32_16x16x32_bf16 v[28:31], v[156:159], v[202:205], v[28:31]
	v_mfma_f32_16x16x32_bf16 v[20:23], v[148:151], v[210:213], v[20:23]
	v_mfma_f32_16x16x32_bf16 v[12:15], v[156:159], v[210:213], v[12:15]
	v_mfma_f32_16x16x32_bf16 v[48:51], v[160:163], v[182:185], 0
	v_mfma_f32_16x16x32_bf16 v[40:43], v[168:171], v[182:185], 0
	v_mfma_f32_16x16x32_bf16 v[32:35], v[160:163], v[190:193], 0
	v_mfma_f32_16x16x32_bf16 v[24:27], v[168:171], v[190:193], 0
	v_mfma_f32_16x16x32_bf16 v[16:19], v[160:163], v[198:201], 0
	v_mfma_f32_16x16x32_bf16 v[8:11], v[168:171], v[198:201], 0
	v_mfma_f32_16x16x32_bf16 v[4:7], v[160:163], v[206:209], 0
	v_mfma_f32_16x16x32_bf16 v[0:3], v[168:171], v[206:209], 0
	v_mfma_f32_16x16x32_bf16 v[48:51], v[164:167], v[186:189], v[48:51]
	v_mfma_f32_16x16x32_bf16 v[40:43], v[172:175], v[186:189], v[40:43]
	v_mfma_f32_16x16x32_bf16 v[32:35], v[164:167], v[194:197], v[32:35]
	v_mfma_f32_16x16x32_bf16 v[24:27], v[172:175], v[194:197], v[24:27]
	v_mfma_f32_16x16x32_bf16 v[16:19], v[164:167], v[202:205], v[16:19]
	v_mfma_f32_16x16x32_bf16 v[8:11], v[172:175], v[202:205], v[8:11]
	v_mfma_f32_16x16x32_bf16 v[4:7], v[164:167], v[210:213], v[4:7]
	v_mfma_f32_16x16x32_bf16 v[0:3], v[172:175], v[210:213], v[0:3]
	s_setprio 0
	s_barrier
	s_add_i32 s28, 0, 0x18000
	s_add_i32 s38, 0, 0x1c000
	v_add_u32_e32 v156, s28, v142
	v_add_u32_e32 v172, s38, v142
	ds_read_b128 v[144:147], v156
	ds_read_b128 v[148:151], v156 offset:1024
	ds_read_b128 v[152:155], v156 offset:2048
	ds_read_b128 v[156:159], v156 offset:3072
	ds_read_b128 v[160:163], v172
	ds_read_b128 v[164:167], v172 offset:1024
	ds_read_b128 v[168:171], v172 offset:2048
	ds_read_b128 v[172:175], v172 offset:3072
	s_add_u32 s6, s6, 0x100000
	s_addc_u32 s7, s7, 0
	s_mov_b32 m0, s25
	v_lshl_add_u64 v[220:221], s[6:7], 0, v[132:133]
	ds_read_b128 v[182:185], v143 offset:32768
	ds_read_b128 v[186:189], v143 offset:33792
	ds_read_b128 v[190:193], v143 offset:34816
	ds_read_b128 v[194:197], v143 offset:35840
	ds_read_b128 v[198:201], v143 offset:36864
	ds_read_b128 v[202:205], v143 offset:37888
	ds_read_b128 v[206:209], v143 offset:38912
	ds_read_b128 v[210:213], v143 offset:39936
	global_load_lds_dwordx4 v[220:221], off
	v_lshl_add_u64 v[220:221], s[6:7], 0, v[130:131]
	s_mov_b32 m0, s30
	s_nop 0
	global_load_lds_dwordx4 v[220:221], off
	s_waitcnt vmcnt(8)
	s_waitcnt lgkmcnt(0)
	s_barrier
	s_setprio 1
	s_waitcnt lgkmcnt(0)
	v_mfma_f32_16x16x32_bf16 v[124:127], v[144:147], v[182:185], v[124:127]
	v_mfma_f32_16x16x32_bf16 v[120:123], v[152:155], v[182:185], v[120:123]
	v_mfma_f32_16x16x32_bf16 v[116:119], v[144:147], v[190:193], v[116:119]
	v_mfma_f32_16x16x32_bf16 v[108:111], v[152:155], v[190:193], v[108:111]
	v_mfma_f32_16x16x32_bf16 v[100:103], v[144:147], v[198:201], v[100:103]
	v_mfma_f32_16x16x32_bf16 v[92:95], v[152:155], v[198:201], v[92:95]
	v_mfma_f32_16x16x32_bf16 v[84:87], v[144:147], v[206:209], v[84:87]
	v_mfma_f32_16x16x32_bf16 v[76:79], v[152:155], v[206:209], v[76:79]
	v_mfma_f32_16x16x32_bf16 v[124:127], v[148:151], v[186:189], v[124:127]
	v_mfma_f32_16x16x32_bf16 v[120:123], v[156:159], v[186:189], v[120:123]
	v_mfma_f32_16x16x32_bf16 v[116:119], v[148:151], v[194:197], v[116:119]
	v_mfma_f32_16x16x32_bf16 v[108:111], v[156:159], v[194:197], v[108:111]
	v_mfma_f32_16x16x32_bf16 v[100:103], v[148:151], v[202:205], v[100:103]
	v_mfma_f32_16x16x32_bf16 v[92:95], v[156:159], v[202:205], v[92:95]
	v_mfma_f32_16x16x32_bf16 v[84:87], v[148:151], v[210:213], v[84:87]
	v_mfma_f32_16x16x32_bf16 v[76:79], v[156:159], v[210:213], v[76:79]
	v_mfma_f32_16x16x32_bf16 v[112:115], v[160:163], v[182:185], v[112:115]
	v_mfma_f32_16x16x32_bf16 v[104:107], v[168:171], v[182:185], v[104:107]
	v_mfma_f32_16x16x32_bf16 v[96:99], v[160:163], v[190:193], v[96:99]
	v_mfma_f32_16x16x32_bf16 v[88:91], v[168:171], v[190:193], v[88:91]
	v_mfma_f32_16x16x32_bf16 v[80:83], v[160:163], v[198:201], v[80:83]
	v_mfma_f32_16x16x32_bf16 v[72:75], v[168:171], v[198:201], v[72:75]
	v_mfma_f32_16x16x32_bf16 v[68:71], v[160:163], v[206:209], v[68:71]
	v_mfma_f32_16x16x32_bf16 v[64:67], v[168:171], v[206:209], v[64:67]
	v_mfma_f32_16x16x32_bf16 v[112:115], v[164:167], v[186:189], v[112:115]
	v_mfma_f32_16x16x32_bf16 v[104:107], v[172:175], v[186:189], v[104:107]
	v_mfma_f32_16x16x32_bf16 v[96:99], v[164:167], v[194:197], v[96:99]
	v_mfma_f32_16x16x32_bf16 v[88:91], v[172:175], v[194:197], v[88:91]
	v_mfma_f32_16x16x32_bf16 v[80:83], v[164:167], v[202:205], v[80:83]
	v_mfma_f32_16x16x32_bf16 v[72:75], v[172:175], v[202:205], v[72:75]
	v_mfma_f32_16x16x32_bf16 v[68:71], v[164:167], v[210:213], v[68:71]
	v_mfma_f32_16x16x32_bf16 v[64:67], v[172:175], v[210:213], v[64:67]
	s_setprio 0
	s_barrier
; #define PG8_STAGE(bufoff, gbase, voff) do { _Pragma("unroll") for (int _i = 0; _i < 2; ++_i) \
;         __builtin_amdgcn_global_load_lds((const unsigned*)((const char*)(gbase) + (voff)[_i]), (PG8_LAS unsigned*)(lds + (bufoff) + ldsw + _i * 8192), 16, 0, 0); } while (0)
; #define PG8_LDA(dst, b, h) do { _Pragma("unroll") for (int m = 0; m < 4; ++m) _Pragma("unroll") for (int k = 0; k < 2; ++k) dst[m][k] = *(const PG8_LAS bf16x8*)(lds + PG8_SA(b, h) + aoff + m * 2048 + k * 1024); } while (0)
; #define PG8_MMA(ai, bj, At, Bt) do { __builtin_amdgcn_s_setprio(1); _Pragma("unroll") for (int m = 0; m < 4; ++m) _Pragma("unroll") for (int n = 0; n < 2; ++n) _Pragma("unroll") for (int k = 0; k < 2; ++k) \
;         acc[ai][bj][m][n] = __builtin_amdgcn_mfma_f32_16x16x32_bf16(Bt[n][k], At[m][k], acc[ai][bj][m][n], 0, 0, 0); __builtin_amdgcn_s_setprio(0); } while (0)
; #define PG8_WAIT_V(n) asm volatile("s_waitcnt vmcnt(" #n ")" ::: "memory")
; #define PG8_WAIT_L(n) asm volatile("s_waitcnt lgkmcnt(" #n ")" ::: "memory")
; #define PG8_BAR __builtin_amdgcn_s_barrier()
; #define PG8_SCHED __builtin_amdgcn_sched_barrier(0)
; template <class Epi, class Sched, bool ALIGN_EPI = false, bool SP2 = false>
; __device__ __forceinline__ void gemm_phase(PG8_LAS unsigned char* lds, const Gemm g, const Sched& S, const Epi& E) {
;     ...
;         for (int t = 0; t < nt; t += 2) {
;             const bool last = (t == nt - 2);
;             const char* a1 = cA + (size_t)(t + 1) * kstep;
;             const char* a2 = last ? nA : cA + (size_t)(t + 2) * kstep; const char* b2 = last ? nB : cB + (size_t)(t + 2) * kstep;
;             const char* a3 = a2 + kstep; const char* b3 = b2 + kstep;
;     ...
;             PG8_LDA(At, 1, 1); PG8_STAGE(PG8_SB(1, 0), b3, voffB); PG8_STAGE(PG8_SB(1, 1), b3 + hstep, voffB); PG8_STAGE(PG8_SA(1, 0), a3, voffA);
;             PG8_WAIT_V(8); PG8_WAIT_L(0); PG8_BAR; PG8_MMA(1, 0, At, B0); PG8_MMA(1, 1, At, B1); PG8_BAR; PG8_SCHED;
	s_add_i32 s6, s28, s22
	v_lshl_add_u64 v[138:139], v[138:139], 0, s[44:45]
	s_mov_b32 m0, s6
	ds_read_b128 v[182:185], v143 offset:49152
	ds_read_b128 v[186:189], v143 offset:50176
	ds_read_b128 v[190:193], v143 offset:51200
	ds_read_b128 v[194:197], v143 offset:52224
	ds_read_b128 v[198:201], v143 offset:53248
	ds_read_b128 v[202:205], v143 offset:54272
	ds_read_b128 v[206:209], v143 offset:55296
	ds_read_b128 v[210:213], v143 offset:56320
	global_load_lds_dwordx4 v[138:139], off
	s_add_i32 m0, s6, 0x2000
	s_add_u32 s4, s4, 0x100080
	v_lshl_add_u64 v[138:139], v[214:215], 0, s[44:45]
	s_addc_u32 s5, s5, 0
	s_add_i32 s6, s38, s22
	global_load_lds_dwordx4 v[138:139], off
	v_lshl_add_u64 v[138:139], s[4:5], 0, v[176:177]
	s_mov_b32 m0, s6
	s_nop 0
	global_load_lds_dwordx4 v[138:139], off
	v_lshl_add_u64 v[138:139], s[4:5], 0, v[128:129]
	s_add_i32 m0, s6, 0x2000
	s_nop 0
	global_load_lds_dwordx4 v[138:139], off
	v_lshl_add_u64 v[138:139], v[216:217], 0, s[44:45]
	s_mov_b32 m0, s63
	s_nop 0
	global_load_lds_dwordx4 v[138:139], off
	v_lshl_add_u64 v[138:139], v[218:219], 0, s[44:45]
	s_mov_b32 m0, s68
	s_nop 0
	global_load_lds_dwordx4 v[138:139], off
	s_waitcnt vmcnt(8)
	s_waitcnt lgkmcnt(0)
	s_barrier
	s_setprio 1
	s_waitcnt lgkmcnt(0)
	v_mfma_f32_16x16x32_bf16 v[60:63], v[144:147], v[182:185], v[60:63]
	v_mfma_f32_16x16x32_bf16 v[56:59], v[152:155], v[182:185], v[56:59]
	v_mfma_f32_16x16x32_bf16 v[52:55], v[144:147], v[190:193], v[52:55]
	v_mfma_f32_16x16x32_bf16 v[44:47], v[152:155], v[190:193], v[44:47]
	v_mfma_f32_16x16x32_bf16 v[36:39], v[144:147], v[198:201], v[36:39]
	v_mfma_f32_16x16x32_bf16 v[28:31], v[152:155], v[198:201], v[28:31]
	v_mfma_f32_16x16x32_bf16 v[20:23], v[144:147], v[206:209], v[20:23]
	v_mfma_f32_16x16x32_bf16 v[12:15], v[152:155], v[206:209], v[12:15]
	v_mfma_f32_16x16x32_bf16 v[60:63], v[148:151], v[186:189], v[60:63]
	v_mfma_f32_16x16x32_bf16 v[56:59], v[156:159], v[186:189], v[56:59]
	v_mfma_f32_16x16x32_bf16 v[52:55], v[148:151], v[194:197], v[52:55]
	v_mfma_f32_16x16x32_bf16 v[44:47], v[156:159], v[194:197], v[44:47]
	v_mfma_f32_16x16x32_bf16 v[36:39], v[148:151], v[202:205], v[36:39]
	v_mfma_f32_16x16x32_bf16 v[28:31], v[156:159], v[202:205], v[28:31]
	v_mfma_f32_16x16x32_bf16 v[20:23], v[148:151], v[210:213], v[20:23]
	v_mfma_f32_16x16x32_bf16 v[12:15], v[156:159], v[210:213], v[12:15]
	v_mfma_f32_16x16x32_bf16 v[48:51], v[160:163], v[182:185], v[48:51]
	v_mfma_f32_16x16x32_bf16 v[40:43], v[168:171], v[182:185], v[40:43]
	v_mfma_f32_16x16x32_bf16 v[32:35], v[160:163], v[190:193], v[32:35]
	v_mfma_f32_16x16x32_bf16 v[24:27], v[168:171], v[190:193], v[24:27]
	v_mfma_f32_16x16x32_bf16 v[16:19], v[160:163], v[198:201], v[16:19]
	v_mfma_f32_16x16x32_bf16 v[8:11], v[168:171], v[198:201], v[8:11]
	v_mfma_f32_16x16x32_bf16 v[4:7], v[160:163], v[206:209], v[4:7]
	v_mfma_f32_16x16x32_bf16 v[0:3], v[168:171], v[206:209], v[0:3]
	v_mfma_f32_16x16x32_bf16 v[48:51], v[164:167], v[186:189], v[48:51]
	v_mfma_f32_16x16x32_bf16 v[40:43], v[172:175], v[186:189], v[40:43]
	s_add_i32 s74, s74, 2
	v_mfma_f32_16x16x32_bf16 v[32:35], v[164:167], v[194:197], v[32:35]
	s_add_u32 s64, s64, 0x100
	v_mfma_f32_16x16x32_bf16 v[24:27], v[172:175], v[194:197], v[24:27]
	s_addc_u32 s65, s65, 0
	v_mfma_f32_16x16x32_bf16 v[16:19], v[164:167], v[202:205], v[16:19]
	s_add_u32 s66, s66, 0x100
	v_mfma_f32_16x16x32_bf16 v[8:11], v[172:175], v[202:205], v[8:11]
	s_addc_u32 s67, s67, 0
	v_mfma_f32_16x16x32_bf16 v[4:7], v[164:167], v[210:213], v[4:7]
	s_cmp_gt_u32 s74, 61
	v_mfma_f32_16x16x32_bf16 v[0:3], v[172:175], v[210:213], v[0:3]
	s_setprio 0
	s_barrier
	s_cbranch_scc0 .LBB0_790
	s_branch .Lg4_post

; #define PG8_STAGE(bufoff, gbase, voff) do { _Pragma("unroll") for (int _i = 0; _i < 2; ++_i) \
;         __builtin_amdgcn_global_load_lds((const unsigned*)((const char*)(gbase) + (voff)[_i]), (PG8_LAS unsigned*)(lds + (bufoff) + ldsw + _i * 8192), 16, 0, 0); } while (0)
; #define PG8_LDA(dst, b, h) do { _Pragma("unroll") for (int m = 0; m < 4; ++m) _Pragma("unroll") for (int k = 0; k < 2; ++k) dst[m][k] = *(const PG8_LAS bf16x8*)(lds + PG8_SA(b, h) + aoff + m * 2048 + k * 1024); } while (0)
; #define PG8_LDB(dst, b, h) do { _Pragma("unroll") for (int n = 0; n < 2; ++n) _Pragma("unroll") for (int k = 0; k < 2; ++k) dst[n][k] = *(const PG8_LAS bf16x8*)(lds + PG8_SB(b, h) + boff + n * 2048 + k * 1024); } while (0)
; #define PG8_MMA(ai, bj, At, Bt) do { __builtin_amdgcn_s_setprio(1); _Pragma("unroll") for (int m = 0; m < 4; ++m) _Pragma("unroll") for (int n = 0; n < 2; ++n) _Pragma("unroll") for (int k = 0; k < 2; ++k) \
;         acc[ai][bj][m][n] = __builtin_amdgcn_mfma_f32_16x16x32_bf16(Bt[n][k], At[m][k], acc[ai][bj][m][n], 0, 0, 0); __builtin_amdgcn_s_setprio(0); } while (0)
; #define PG8_WAIT_V(n) asm volatile("s_waitcnt vmcnt(" #n ")" ::: "memory")
; #define PG8_WAIT_L(n) asm volatile("s_waitcnt lgkmcnt(" #n ")" ::: "memory")
; #define PG8_BAR __builtin_amdgcn_s_barrier()
; #define PG8_SCHED __builtin_amdgcn_sched_barrier(0)
; template <class Epi, class Sched, bool ALIGN_EPI = false, bool SP2 = false>
; __device__ __forceinline__ void gemm_phase(PG8_LAS unsigned char* lds, const Gemm g, const Sched& S, const Epi& E) {
;     ...
;             const bool last = (t == nt - 2);
;             const char* a1 = cA + (size_t)(t + 1) * kstep;
;             const char* a2 = last ? nA : cA + (size_t)(t + 2) * kstep; const char* b2 = last ? nB : cB + (size_t)(t + 2) * kstep;
;             const char* a3 = a2 + kstep; const char* b3 = b2 + kstep;
;             if (last && has_next) S.a_ready(nxt);
;             if constexpr (SP2) {
;             PG8_LDB(B0, 0, 0); PG8_LDB(B1, 0, 1); PG8_SCHED; PG8_LDA(At, 0, 0); PG8_STAGE(PG8_SA(1, 1), a1 + hstep, voffA);
;             PG8_WAIT_V(8); PG8_WAIT_L(0); PG8_BAR; PG8_MMA(0, 0, At, B0); PG8_MMA(0, 1, At, B1); PG8_BAR; PG8_SCHED;
;             PG8_LDA(At, 0, 1); PG8_STAGE(PG8_SB(0, 0), b2, voffB); PG8_STAGE(PG8_SB(0, 1), b2 + hstep, voffB); PG8_STAGE(PG8_SA(0, 0), a2, voffA);
.LBB0_812:
	s_add_i32 s83, s4, 2
	s_add_u32 s28, s64, 0x80
	s_addc_u32 s5, s65, 0
	s_add_i32 s48, 0, 0x10000
	s_cmp_eq_u32 s72, s4
	s_cselect_b32 s5, s37, s5
	s_cselect_b32 s4, s36, s28
	s_cselect_b32 s39, s41, s67
	s_cselect_b32 s38, s40, s66
	s_add_i32 s28, 0, 0x14000
	v_add_u32_e32 v154, s48, v140
	v_add_u32_e32 v170, s28, v140
	ds_read_b128 v[142:145], v154
	ds_read_b128 v[146:149], v154 offset:1024
	ds_read_b128 v[150:153], v154 offset:2048
	ds_read_b128 v[154:157], v154 offset:3072
	ds_read_b128 v[158:161], v170
	ds_read_b128 v[162:165], v170 offset:1024
	ds_read_b128 v[166:169], v170 offset:2048
	ds_read_b128 v[170:173], v170 offset:3072
	v_lshl_add_u64 v[174:175], s[64:65], 0, v[134:135]
	s_add_i32 m0, s25, 0xc000
	ds_read_b128 v[182:185], v141
	ds_read_b128 v[186:189], v141 offset:1024
	ds_read_b128 v[190:193], v141 offset:2048
	ds_read_b128 v[194:197], v141 offset:3072
	ds_read_b128 v[198:201], v141 offset:4096
	ds_read_b128 v[202:205], v141 offset:5120
	ds_read_b128 v[206:209], v141 offset:6144
	ds_read_b128 v[210:213], v141 offset:7168
	global_load_lds_dwordx4 v[174:175], off
	v_lshl_add_u64 v[174:175], s[64:65], 0, v[136:137]
	s_add_i32 m0, s25, 0xe000
	s_nop 0
	global_load_lds_dwordx4 v[174:175], off
	s_waitcnt vmcnt(8)
	s_waitcnt lgkmcnt(0)
	s_barrier
	s_setprio 1
	s_waitcnt lgkmcnt(0)
	v_mfma_f32_16x16x32_bf16 v[124:127], v[142:145], v[182:185], v[124:127]
	v_mfma_f32_16x16x32_bf16 v[120:123], v[150:153], v[182:185], v[120:123]
	v_mfma_f32_16x16x32_bf16 v[108:111], v[142:145], v[190:193], v[108:111]
	v_mfma_f32_16x16x32_bf16 v[104:107], v[150:153], v[190:193], v[104:107]
	v_mfma_f32_16x16x32_bf16 v[92:95], v[142:145], v[198:201], v[92:95]
	v_mfma_f32_16x16x32_bf16 v[88:91], v[150:153], v[198:201], v[88:91]
	v_mfma_f32_16x16x32_bf16 v[76:79], v[142:145], v[206:209], v[76:79]
	v_mfma_f32_16x16x32_bf16 v[72:75], v[150:153], v[206:209], v[72:75]
	v_mfma_f32_16x16x32_bf16 v[124:127], v[146:149], v[186:189], v[124:127]
	v_mfma_f32_16x16x32_bf16 v[120:123], v[154:157], v[186:189], v[120:123]
	v_mfma_f32_16x16x32_bf16 v[108:111], v[146:149], v[194:197], v[108:111]
	v_mfma_f32_16x16x32_bf16 v[104:107], v[154:157], v[194:197], v[104:107]
	v_mfma_f32_16x16x32_bf16 v[92:95], v[146:149], v[202:205], v[92:95]
	v_mfma_f32_16x16x32_bf16 v[88:91], v[154:157], v[202:205], v[88:91]
	v_mfma_f32_16x16x32_bf16 v[76:79], v[146:149], v[210:213], v[76:79]
	v_mfma_f32_16x16x32_bf16 v[72:75], v[154:157], v[210:213], v[72:75]
	v_mfma_f32_16x16x32_bf16 v[116:119], v[158:161], v[182:185], v[116:119]
	v_mfma_f32_16x16x32_bf16 v[112:115], v[166:169], v[182:185], v[112:115]
	v_mfma_f32_16x16x32_bf16 v[100:103], v[158:161], v[190:193], v[100:103]
	v_mfma_f32_16x16x32_bf16 v[96:99], v[166:169], v[190:193], v[96:99]
	v_mfma_f32_16x16x32_bf16 v[84:87], v[158:161], v[198:201], v[84:87]
	v_mfma_f32_16x16x32_bf16 v[80:83], v[166:169], v[198:201], v[80:83]
	v_mfma_f32_16x16x32_bf16 v[68:71], v[158:161], v[206:209], v[68:71]
	v_mfma_f32_16x16x32_bf16 v[64:67], v[166:169], v[206:209], v[64:67]
	v_mfma_f32_16x16x32_bf16 v[116:119], v[162:165], v[186:189], v[116:119]
	v_mfma_f32_16x16x32_bf16 v[112:115], v[170:173], v[186:189], v[112:115]
	v_mfma_f32_16x16x32_bf16 v[100:103], v[162:165], v[194:197], v[100:103]
	v_mfma_f32_16x16x32_bf16 v[96:99], v[170:173], v[194:197], v[96:99]
	v_mfma_f32_16x16x32_bf16 v[84:87], v[162:165], v[202:205], v[84:87]
	v_mfma_f32_16x16x32_bf16 v[80:83], v[170:173], v[202:205], v[80:83]
	v_mfma_f32_16x16x32_bf16 v[68:71], v[162:165], v[210:213], v[68:71]
	v_mfma_f32_16x16x32_bf16 v[64:67], v[170:173], v[210:213], v[64:67]
	s_setprio 0
	s_barrier
	s_add_i32 s48, s48, s24
	v_lshl_add_u64 v[174:175], s[38:39], 0, v[176:177]
	s_mov_b32 m0, s48
	ds_read_b128 v[182:185], v141 offset:16384
	ds_read_b128 v[186:189], v141 offset:17408
	ds_read_b128 v[190:193], v141 offset:18432
	ds_read_b128 v[194:197], v141 offset:19456
	ds_read_b128 v[198:201], v141 offset:20480
	ds_read_b128 v[202:205], v141 offset:21504
	ds_read_b128 v[206:209], v141 offset:22528
	ds_read_b128 v[210:213], v141 offset:23552
	global_load_lds_dwordx4 v[174:175], off
	s_add_i32 m0, s48, 0x2000
	v_lshl_add_u64 v[214:215], s[38:39], 0, v[128:129]
	s_add_u32 s38, s38, s0
	s_addc_u32 s39, s39, s1
	s_add_i32 s28, s28, s24
	global_load_lds_dwordx4 v[214:215], off
	v_lshl_add_u64 v[216:217], s[38:39], 0, v[176:177]
	s_mov_b32 m0, s28
	v_lshl_add_u64 v[218:219], s[38:39], 0, v[128:129]
	global_load_lds_dwordx4 v[216:217], off
	s_add_i32 m0, s28, 0x2000
	v_lshl_add_u64 v[220:221], s[4:5], 0, v[132:133]
	global_load_lds_dwordx4 v[218:219], off
	s_mov_b32 m0, s25
	v_lshl_add_u64 v[222:223], s[4:5], 0, v[130:131]
	global_load_lds_dwordx4 v[220:221], off
	s_mov_b32 m0, s30
	s_nop 0
	global_load_lds_dwordx4 v[222:223], off
	s_waitcnt vmcnt(8)
	s_waitcnt lgkmcnt(0)
	s_barrier
; #define PG8_STAGE(bufoff, gbase, voff) do { _Pragma("unroll") for (int _i = 0; _i < 2; ++_i) \
;         __builtin_amdgcn_global_load_lds((const unsigned*)((const char*)(gbase) + (voff)[_i]), (PG8_LAS unsigned*)(lds + (bufoff) + ldsw + _i * 8192), 16, 0, 0); } while (0)
; #define PG8_LDA(dst, b, h) do { _Pragma("unroll") for (int m = 0; m < 4; ++m) _Pragma("unroll") for (int k = 0; k < 2; ++k) dst[m][k] = *(const PG8_LAS bf16x8*)(lds + PG8_SA(b, h) + aoff + m * 2048 + k * 1024); } while (0)
; #define PG8_LDB(dst, b, h) do { _Pragma("unroll") for (int n = 0; n < 2; ++n) _Pragma("unroll") for (int k = 0; k < 2; ++k) dst[n][k] = *(const PG8_LAS bf16x8*)(lds + PG8_SB(b, h) + boff + n * 2048 + k * 1024); } while (0)
; #define PG8_MMA(ai, bj, At, Bt) do { __builtin_amdgcn_s_setprio(1); _Pragma("unroll") for (int m = 0; m < 4; ++m) _Pragma("unroll") for (int n = 0; n < 2; ++n) _Pragma("unroll") for (int k = 0; k < 2; ++k) \
;         acc[ai][bj][m][n] = __builtin_amdgcn_mfma_f32_16x16x32_bf16(Bt[n][k], At[m][k], acc[ai][bj][m][n], 0, 0, 0); __builtin_amdgcn_s_setprio(0); } while (0)
; #define PG8_WAIT_V(n) asm volatile("s_waitcnt vmcnt(" #n ")" ::: "memory")
; #define PG8_WAIT_L(n) asm volatile("s_waitcnt lgkmcnt(" #n ")" ::: "memory")
; #define PG8_BAR __builtin_amdgcn_s_barrier()
; #define PG8_SCHED __builtin_amdgcn_sched_barrier(0)
; template <class Epi, class Sched, bool ALIGN_EPI = false, bool SP2 = false>
; __device__ __forceinline__ void gemm_phase(PG8_LAS unsigned char* lds, const Gemm g, const Sched& S, const Epi& E) {
;     ...
;             PG8_WAIT_V(8); PG8_WAIT_L(0); PG8_BAR; PG8_MMA(1, 0, At, B0); PG8_MMA(1, 1, At, B1); PG8_BAR; PG8_SCHED;
;             PG8_LDB(B0, 1, 0); PG8_LDB(B1, 1, 1); PG8_SCHED; PG8_LDA(At, 1, 0); PG8_STAGE(PG8_SA(0, 1), a2 + hstep, voffA);
;             PG8_WAIT_V(8); PG8_WAIT_L(0); PG8_BAR; PG8_MMA(0, 0, At, B0); PG8_MMA(0, 1, At, B1); PG8_BAR; PG8_SCHED;
	s_setprio 1
	s_waitcnt lgkmcnt(0)
	v_mfma_f32_16x16x32_bf16 v[60:63], v[142:145], v[182:185], v[60:63]
	v_mfma_f32_16x16x32_bf16 v[56:59], v[150:153], v[182:185], v[56:59]
	v_mfma_f32_16x16x32_bf16 v[44:47], v[142:145], v[190:193], v[44:47]
	v_mfma_f32_16x16x32_bf16 v[40:43], v[150:153], v[190:193], v[40:43]
	v_mfma_f32_16x16x32_bf16 v[28:31], v[142:145], v[198:201], v[28:31]
	v_mfma_f32_16x16x32_bf16 v[24:27], v[150:153], v[198:201], v[24:27]
	v_mfma_f32_16x16x32_bf16 v[12:15], v[142:145], v[206:209], v[12:15]
	v_mfma_f32_16x16x32_bf16 v[8:11], v[150:153], v[206:209], v[8:11]
	v_mfma_f32_16x16x32_bf16 v[60:63], v[146:149], v[186:189], v[60:63]
	v_mfma_f32_16x16x32_bf16 v[56:59], v[154:157], v[186:189], v[56:59]
	v_mfma_f32_16x16x32_bf16 v[44:47], v[146:149], v[194:197], v[44:47]
	v_mfma_f32_16x16x32_bf16 v[40:43], v[154:157], v[194:197], v[40:43]
	v_mfma_f32_16x16x32_bf16 v[28:31], v[146:149], v[202:205], v[28:31]
	v_mfma_f32_16x16x32_bf16 v[24:27], v[154:157], v[202:205], v[24:27]
	v_mfma_f32_16x16x32_bf16 v[12:15], v[146:149], v[210:213], v[12:15]
	v_mfma_f32_16x16x32_bf16 v[8:11], v[154:157], v[210:213], v[8:11]
	v_mfma_f32_16x16x32_bf16 v[52:55], v[158:161], v[182:185], v[52:55]
	v_mfma_f32_16x16x32_bf16 v[48:51], v[166:169], v[182:185], v[48:51]
	v_mfma_f32_16x16x32_bf16 v[36:39], v[158:161], v[190:193], v[36:39]
	v_mfma_f32_16x16x32_bf16 v[32:35], v[166:169], v[190:193], v[32:35]
	v_mfma_f32_16x16x32_bf16 v[20:23], v[158:161], v[198:201], v[20:23]
	v_mfma_f32_16x16x32_bf16 v[16:19], v[166:169], v[198:201], v[16:19]
	v_mfma_f32_16x16x32_bf16 v[4:7], v[158:161], v[206:209], v[4:7]
	v_mfma_f32_16x16x32_bf16 v[0:3], v[166:169], v[206:209], v[0:3]
	v_mfma_f32_16x16x32_bf16 v[52:55], v[162:165], v[186:189], v[52:55]
	v_mfma_f32_16x16x32_bf16 v[48:51], v[170:173], v[186:189], v[48:51]
	v_mfma_f32_16x16x32_bf16 v[36:39], v[162:165], v[194:197], v[36:39]
	v_mfma_f32_16x16x32_bf16 v[32:35], v[170:173], v[194:197], v[32:35]
	v_mfma_f32_16x16x32_bf16 v[20:23], v[162:165], v[202:205], v[20:23]
	v_mfma_f32_16x16x32_bf16 v[16:19], v[170:173], v[202:205], v[16:19]
	v_mfma_f32_16x16x32_bf16 v[4:7], v[162:165], v[210:213], v[4:7]
	v_mfma_f32_16x16x32_bf16 v[0:3], v[170:173], v[210:213], v[0:3]
	s_setprio 0
	s_barrier
	s_add_i32 s28, 0, 0x18000
	s_add_i32 s38, 0, 0x1c000
	v_add_u32_e32 v154, s28, v140
	v_add_u32_e32 v170, s38, v140
	ds_read_b128 v[142:145], v154
	ds_read_b128 v[146:149], v154 offset:1024
	ds_read_b128 v[150:153], v154 offset:2048
	ds_read_b128 v[154:157], v154 offset:3072
	ds_read_b128 v[158:161], v170
	ds_read_b128 v[162:165], v170 offset:1024
	ds_read_b128 v[166:169], v170 offset:2048
	ds_read_b128 v[170:173], v170 offset:3072
	s_add_u32 s4, s4, s0
	s_addc_u32 s5, s5, s1
	s_mov_b32 m0, s31
	v_lshl_add_u64 v[224:225], s[4:5], 0, v[132:133]
	ds_read_b128 v[182:185], v141 offset:32768
	ds_read_b128 v[186:189], v141 offset:33792
	ds_read_b128 v[190:193], v141 offset:34816
	ds_read_b128 v[194:197], v141 offset:35840
	ds_read_b128 v[198:201], v141 offset:36864
	ds_read_b128 v[202:205], v141 offset:37888
	ds_read_b128 v[206:209], v141 offset:38912
	ds_read_b128 v[210:213], v141 offset:39936
	global_load_lds_dwordx4 v[224:225], off
	v_lshl_add_u64 v[224:225], s[4:5], 0, v[130:131]
	s_mov_b32 m0, s46
	s_nop 0
	global_load_lds_dwordx4 v[224:225], off
	s_waitcnt vmcnt(8)
	s_waitcnt lgkmcnt(0)
	s_barrier
	s_setprio 1
	s_waitcnt lgkmcnt(0)
	v_mfma_f32_16x16x32_bf16 v[124:127], v[142:145], v[182:185], v[124:127]
	v_mfma_f32_16x16x32_bf16 v[120:123], v[150:153], v[182:185], v[120:123]
	v_mfma_f32_16x16x32_bf16 v[108:111], v[142:145], v[190:193], v[108:111]
	v_mfma_f32_16x16x32_bf16 v[104:107], v[150:153], v[190:193], v[104:107]
	v_mfma_f32_16x16x32_bf16 v[92:95], v[142:145], v[198:201], v[92:95]
	v_mfma_f32_16x16x32_bf16 v[88:91], v[150:153], v[198:201], v[88:91]
	v_mfma_f32_16x16x32_bf16 v[76:79], v[142:145], v[206:209], v[76:79]
	v_mfma_f32_16x16x32_bf16 v[72:75], v[150:153], v[206:209], v[72:75]
	v_mfma_f32_16x16x32_bf16 v[124:127], v[146:149], v[186:189], v[124:127]
	v_mfma_f32_16x16x32_bf16 v[120:123], v[154:157], v[186:189], v[120:123]
	v_mfma_f32_16x16x32_bf16 v[108:111], v[146:149], v[194:197], v[108:111]
	v_mfma_f32_16x16x32_bf16 v[104:107], v[154:157], v[194:197], v[104:107]
	v_mfma_f32_16x16x32_bf16 v[92:95], v[146:149], v[202:205], v[92:95]
	v_mfma_f32_16x16x32_bf16 v[88:91], v[154:157], v[202:205], v[88:91]
	v_mfma_f32_16x16x32_bf16 v[76:79], v[146:149], v[210:213], v[76:79]
	v_mfma_f32_16x16x32_bf16 v[72:75], v[154:157], v[210:213], v[72:75]
	v_mfma_f32_16x16x32_bf16 v[116:119], v[158:161], v[182:185], v[116:119]
	v_mfma_f32_16x16x32_bf16 v[112:115], v[166:169], v[182:185], v[112:115]
	v_mfma_f32_16x16x32_bf16 v[100:103], v[158:161], v[190:193], v[100:103]
	v_mfma_f32_16x16x32_bf16 v[96:99], v[166:169], v[190:193], v[96:99]
	v_mfma_f32_16x16x32_bf16 v[84:87], v[158:161], v[198:201], v[84:87]
	v_mfma_f32_16x16x32_bf16 v[80:83], v[166:169], v[198:201], v[80:83]
	v_mfma_f32_16x16x32_bf16 v[68:71], v[158:161], v[206:209], v[68:71]
	v_mfma_f32_16x16x32_bf16 v[64:67], v[166:169], v[206:209], v[64:67]
	v_mfma_f32_16x16x32_bf16 v[116:119], v[162:165], v[186:189], v[116:119]
	v_mfma_f32_16x16x32_bf16 v[112:115], v[170:173], v[186:189], v[112:115]
	v_mfma_f32_16x16x32_bf16 v[100:103], v[162:165], v[194:197], v[100:103]
	v_mfma_f32_16x16x32_bf16 v[96:99], v[170:173], v[194:197], v[96:99]
	v_mfma_f32_16x16x32_bf16 v[84:87], v[162:165], v[202:205], v[84:87]
	v_mfma_f32_16x16x32_bf16 v[80:83], v[170:173], v[202:205], v[80:83]
	v_mfma_f32_16x16x32_bf16 v[68:71], v[162:165], v[210:213], v[68:71]
	v_mfma_f32_16x16x32_bf16 v[64:67], v[170:173], v[210:213], v[64:67]
	s_setprio 0
	s_barrier
; #define PG8_STAGE(bufoff, gbase, voff) do { _Pragma("unroll") for (int _i = 0; _i < 2; ++_i) \
;         __builtin_amdgcn_global_load_lds((const unsigned*)((const char*)(gbase) + (voff)[_i]), (PG8_LAS unsigned*)(lds + (bufoff) + ldsw + _i * 8192), 16, 0, 0); } while (0)
; #define PG8_LDA(dst, b, h) do { _Pragma("unroll") for (int m = 0; m < 4; ++m) _Pragma("unroll") for (int k = 0; k < 2; ++k) dst[m][k] = *(const PG8_LAS bf16x8*)(lds + PG8_SA(b, h) + aoff + m * 2048 + k * 1024); } while (0)
; #define PG8_MMA(ai, bj, At, Bt) do { __builtin_amdgcn_s_setprio(1); _Pragma("unroll") for (int m = 0; m < 4; ++m) _Pragma("unroll") for (int n = 0; n < 2; ++n) _Pragma("unroll") for (int k = 0; k < 2; ++k) \
;         acc[ai][bj][m][n] = __builtin_amdgcn_mfma_f32_16x16x32_bf16(Bt[n][k], At[m][k], acc[ai][bj][m][n], 0, 0, 0); __builtin_amdgcn_s_setprio(0); } while (0)
; #define PG8_WAIT_V(n) asm volatile("s_waitcnt vmcnt(" #n ")" ::: "memory")
; #define PG8_WAIT_L(n) asm volatile("s_waitcnt lgkmcnt(" #n ")" ::: "memory")
; #define PG8_BAR __builtin_amdgcn_s_barrier()
; #define PG8_SCHED __builtin_amdgcn_sched_barrier(0)
; template <class Epi, class Sched, bool ALIGN_EPI = false, bool SP2 = false>
; __device__ __forceinline__ void gemm_phase(PG8_LAS unsigned char* lds, const Gemm g, const Sched& S, const Epi& E) {
;     ...
;             PG8_LDA(At, 1, 1); PG8_STAGE(PG8_SB(1, 0), b3, voffB); PG8_STAGE(PG8_SB(1, 1), b3 + hstep, voffB); PG8_STAGE(PG8_SA(1, 0), a3, voffA);
;             PG8_WAIT_V(8); PG8_WAIT_L(0); PG8_BAR; PG8_MMA(1, 0, At, B0); PG8_MMA(1, 1, At, B1); PG8_BAR; PG8_SCHED;
	s_add_i32 s4, s28, s24
	v_lshl_add_u64 v[174:175], v[174:175], 0, s[44:45]
	s_mov_b32 m0, s4
	ds_read_b128 v[182:185], v141 offset:49152
	ds_read_b128 v[186:189], v141 offset:50176
	ds_read_b128 v[190:193], v141 offset:51200
	ds_read_b128 v[194:197], v141 offset:52224
	ds_read_b128 v[198:201], v141 offset:53248
	ds_read_b128 v[202:205], v141 offset:54272
	ds_read_b128 v[206:209], v141 offset:55296
	ds_read_b128 v[210:213], v141 offset:56320
	global_load_lds_dwordx4 v[174:175], off
	v_lshl_add_u64 v[174:175], v[214:215], 0, s[44:45]
	s_add_i32 m0, s4, 0x2000
	s_add_i32 s4, s38, s24
	global_load_lds_dwordx4 v[174:175], off
	v_lshl_add_u64 v[174:175], v[216:217], 0, s[44:45]
	s_mov_b32 m0, s4
	s_nop 0
	global_load_lds_dwordx4 v[174:175], off
	v_lshl_add_u64 v[174:175], v[218:219], 0, s[44:45]
	s_add_i32 m0, s4, 0x2000
	s_nop 0
	global_load_lds_dwordx4 v[174:175], off
	v_lshl_add_u64 v[174:175], v[220:221], 0, s[44:45]
	s_mov_b32 m0, s69
	s_nop 0
	global_load_lds_dwordx4 v[174:175], off
	v_lshl_add_u64 v[174:175], v[222:223], 0, s[44:45]
	s_mov_b32 m0, s70
	s_nop 0
	global_load_lds_dwordx4 v[174:175], off
	s_waitcnt vmcnt(8)
	s_waitcnt lgkmcnt(0)
	s_barrier
	s_setprio 1
	s_waitcnt lgkmcnt(0)
	v_mfma_f32_16x16x32_bf16 v[60:63], v[142:145], v[182:185], v[60:63]
	v_mfma_f32_16x16x32_bf16 v[56:59], v[150:153], v[182:185], v[56:59]
	v_mfma_f32_16x16x32_bf16 v[44:47], v[142:145], v[190:193], v[44:47]
	v_mfma_f32_16x16x32_bf16 v[40:43], v[150:153], v[190:193], v[40:43]
	v_mfma_f32_16x16x32_bf16 v[28:31], v[142:145], v[198:201], v[28:31]
	v_mfma_f32_16x16x32_bf16 v[24:27], v[150:153], v[198:201], v[24:27]
	v_mfma_f32_16x16x32_bf16 v[12:15], v[142:145], v[206:209], v[12:15]
	v_mfma_f32_16x16x32_bf16 v[8:11], v[150:153], v[206:209], v[8:11]
	v_mfma_f32_16x16x32_bf16 v[60:63], v[146:149], v[186:189], v[60:63]
	v_mfma_f32_16x16x32_bf16 v[56:59], v[154:157], v[186:189], v[56:59]
	v_mfma_f32_16x16x32_bf16 v[44:47], v[146:149], v[194:197], v[44:47]
	v_mfma_f32_16x16x32_bf16 v[40:43], v[154:157], v[194:197], v[40:43]
	v_mfma_f32_16x16x32_bf16 v[28:31], v[146:149], v[202:205], v[28:31]
	v_mfma_f32_16x16x32_bf16 v[24:27], v[154:157], v[202:205], v[24:27]
	v_mfma_f32_16x16x32_bf16 v[12:15], v[146:149], v[210:213], v[12:15]
	v_mfma_f32_16x16x32_bf16 v[8:11], v[154:157], v[210:213], v[8:11]
	v_mfma_f32_16x16x32_bf16 v[52:55], v[158:161], v[182:185], v[52:55]
	v_mfma_f32_16x16x32_bf16 v[48:51], v[166:169], v[182:185], v[48:51]
	v_mfma_f32_16x16x32_bf16 v[36:39], v[158:161], v[190:193], v[36:39]
	v_mfma_f32_16x16x32_bf16 v[32:35], v[166:169], v[190:193], v[32:35]
	v_mfma_f32_16x16x32_bf16 v[20:23], v[158:161], v[198:201], v[20:23]
	v_mfma_f32_16x16x32_bf16 v[16:19], v[166:169], v[198:201], v[16:19]
	v_mfma_f32_16x16x32_bf16 v[4:7], v[158:161], v[206:209], v[4:7]
	v_mfma_f32_16x16x32_bf16 v[0:3], v[166:169], v[206:209], v[0:3]
	v_mfma_f32_16x16x32_bf16 v[52:55], v[162:165], v[186:189], v[52:55]
	v_mfma_f32_16x16x32_bf16 v[48:51], v[170:173], v[186:189], v[48:51]
	s_add_u32 s64, s64, 0x100
	v_mfma_f32_16x16x32_bf16 v[36:39], v[162:165], v[194:197], v[36:39]
	s_addc_u32 s65, s65, 0
	v_mfma_f32_16x16x32_bf16 v[32:35], v[170:173], v[194:197], v[32:35]
	s_add_u32 s66, s66, 0x100
	v_mfma_f32_16x16x32_bf16 v[20:23], v[162:165], v[202:205], v[20:23]
	s_addc_u32 s67, s67, 0
	v_mfma_f32_16x16x32_bf16 v[16:19], v[170:173], v[202:205], v[16:19]
	s_cmp_ge_i32 s83, s63
	v_mfma_f32_16x16x32_bf16 v[4:7], v[162:165], v[210:213], v[4:7]
	s_mov_b32 s4, s83
	v_mfma_f32_16x16x32_bf16 v[0:3], v[170:173], v[210:213], v[0:3]
	s_setprio 0
	s_barrier
	s_cbranch_scc0 .LBB0_812
